# FFN-up GEMM epilogues (prompt+sample rows) rewritten by hand; sample rows: prefetched history rows (4-deep ring), counted waits, outputs parked in dead accumulators
# speedup vs baseline: 1.0441x; 1.0441x over previous
.LBB0_2030:
	ds_read_b128 v[130:133], v228
	ds_read_b128 v[134:137], v228 offset:1024
	ds_read_b128 v[138:141], v228 offset:2048
	ds_read_b128 v[142:145], v228 offset:3072
	s_add_u32 s18, s16, 0xfffc0080
	s_addc_u32 s19, s17, -1
	s_cmp_eq_u32 s26, 12
	s_cselect_b32 s21, s13, s19
	s_cselect_b32 s20, s15, s18
	s_cselect_b32 s19, s22, s25
	s_cselect_b32 s18, s23, s24
	v_lshl_add_u64 v[204:205], s[16:17], 0, v[196:197]
	s_add_i32 m0, s85, 0xc000
	ds_read_b128 v[146:149], v229
	ds_read_b128 v[150:153], v229 offset:1024
	ds_read_b128 v[154:157], v229 offset:2048
	ds_read_b128 v[158:161], v229 offset:3072
	ds_read_b128 v[162:165], v229 offset:4096
	ds_read_b128 v[166:169], v229 offset:5120
	ds_read_b128 v[170:173], v229 offset:6144
	ds_read_b128 v[174:177], v229 offset:7168
	global_load_lds_dwordx4 v[204:205], off
	v_lshl_add_u64 v[204:205], s[16:17], 0, v[198:199]
	s_add_i32 m0, s85, 0xe000
	s_nop 0
	global_load_lds_dwordx4 v[204:205], off
	s_waitcnt lgkmcnt(8)
	s_barrier
	s_waitcnt lgkmcnt(0)
	s_setprio 1
	s_waitcnt lgkmcnt(0)
	v_mfma_f32_16x16x32_bf16 v[126:129], v[130:133], v[146:149], v[126:129]
	v_mfma_f32_16x16x32_bf16 v[62:65], v[138:141], v[146:149], v[62:65]
	v_mfma_f32_16x16x32_bf16 v[118:121], v[130:133], v[154:157], v[118:121]
	v_mfma_f32_16x16x32_bf16 v[54:57], v[138:141], v[154:157], v[54:57]
	v_mfma_f32_16x16x32_bf16 v[110:113], v[130:133], v[162:165], v[110:113]
	v_mfma_f32_16x16x32_bf16 v[46:49], v[138:141], v[162:165], v[46:49]
	v_mfma_f32_16x16x32_bf16 v[102:105], v[130:133], v[170:173], v[102:105]
	v_mfma_f32_16x16x32_bf16 v[38:41], v[138:141], v[170:173], v[38:41]
	v_mfma_f32_16x16x32_bf16 v[126:129], v[134:137], v[150:153], v[126:129]
	v_mfma_f32_16x16x32_bf16 v[62:65], v[142:145], v[150:153], v[62:65]
	v_mfma_f32_16x16x32_bf16 v[118:121], v[134:137], v[158:161], v[118:121]
	v_mfma_f32_16x16x32_bf16 v[54:57], v[142:145], v[158:161], v[54:57]
	v_mfma_f32_16x16x32_bf16 v[110:113], v[134:137], v[166:169], v[110:113]
	v_mfma_f32_16x16x32_bf16 v[46:49], v[142:145], v[166:169], v[46:49]
	v_mfma_f32_16x16x32_bf16 v[102:105], v[134:137], v[174:177], v[102:105]
	v_mfma_f32_16x16x32_bf16 v[38:41], v[142:145], v[174:177], v[38:41]
	s_setprio 0
	s_barrier
	s_add_i32 s27, s64, s84
	v_lshl_add_u64 v[220:221], s[18:19], 0, v[184:185]
	s_mov_b32 m0, s27
	ds_read_b128 v[204:207], v230
	ds_read_b128 v[208:211], v230 offset:1024
	ds_read_b128 v[212:215], v230 offset:2048
	ds_read_b128 v[216:219], v230 offset:3072
	global_load_lds_dwordx4 v[220:221], off
	v_lshl_add_u64 v[222:223], s[18:19], 0, v[188:189]
	s_add_i32 m0, s27, 0x2000
	s_nop 0
	global_load_lds_dwordx4 v[222:223], off
	s_barrier
	s_waitcnt lgkmcnt(0)
	s_setprio 1
	s_waitcnt lgkmcnt(0)
	v_mfma_f32_16x16x32_bf16 v[122:125], v[204:207], v[146:149], v[122:125]
	v_mfma_f32_16x16x32_bf16 v[58:61], v[212:215], v[146:149], v[58:61]
	v_mfma_f32_16x16x32_bf16 v[114:117], v[204:207], v[154:157], v[114:117]
	v_mfma_f32_16x16x32_bf16 v[50:53], v[212:215], v[154:157], v[50:53]
	v_mfma_f32_16x16x32_bf16 v[106:109], v[204:207], v[162:165], v[106:109]
	v_mfma_f32_16x16x32_bf16 v[42:45], v[212:215], v[162:165], v[42:45]
	v_mfma_f32_16x16x32_bf16 v[98:101], v[204:207], v[170:173], v[98:101]
	v_mfma_f32_16x16x32_bf16 v[34:37], v[212:215], v[170:173], v[34:37]
	v_mfma_f32_16x16x32_bf16 v[122:125], v[208:211], v[150:153], v[122:125]
	v_mfma_f32_16x16x32_bf16 v[58:61], v[216:219], v[150:153], v[58:61]
	v_mfma_f32_16x16x32_bf16 v[114:117], v[208:211], v[158:161], v[114:117]
	v_mfma_f32_16x16x32_bf16 v[50:53], v[216:219], v[158:161], v[50:53]
	v_mfma_f32_16x16x32_bf16 v[106:109], v[208:211], v[166:169], v[106:109]
	v_mfma_f32_16x16x32_bf16 v[42:45], v[216:219], v[166:169], v[42:45]
	v_mfma_f32_16x16x32_bf16 v[98:101], v[208:211], v[174:177], v[98:101]
	v_mfma_f32_16x16x32_bf16 v[34:37], v[216:219], v[174:177], v[34:37]
	s_setprio 0
	s_mov_b32 m0, s85
	v_lshl_add_u64 v[224:225], s[20:21], 0, v[182:183]
	s_barrier
	ds_read_b128 v[146:149], v229 offset:16384
	ds_read_b128 v[150:153], v229 offset:17408
	ds_read_b128 v[154:157], v229 offset:18432
	ds_read_b128 v[158:161], v229 offset:19456
	ds_read_b128 v[162:165], v229 offset:20480
	ds_read_b128 v[166:169], v229 offset:21504
	ds_read_b128 v[170:173], v229 offset:22528
	ds_read_b128 v[174:177], v229 offset:23552
	global_load_lds_dwordx4 v[224:225], off
	v_lshl_add_u64 v[232:233], s[20:21], 0, v[186:187]
	s_mov_b32 m0, s86
	s_nop 0
	global_load_lds_dwordx4 v[232:233], off
	s_barrier
	s_waitcnt lgkmcnt(0)
	s_setprio 1
	s_waitcnt lgkmcnt(0)
	v_mfma_f32_16x16x32_bf16 v[94:97], v[130:133], v[146:149], v[94:97]
	v_mfma_f32_16x16x32_bf16 v[30:33], v[138:141], v[146:149], v[30:33]
	v_mfma_f32_16x16x32_bf16 v[86:89], v[130:133], v[154:157], v[86:89]
	v_mfma_f32_16x16x32_bf16 v[22:25], v[138:141], v[154:157], v[22:25]
	v_mfma_f32_16x16x32_bf16 v[78:81], v[130:133], v[162:165], v[78:81]
	v_mfma_f32_16x16x32_bf16 v[14:17], v[138:141], v[162:165], v[14:17]
	v_mfma_f32_16x16x32_bf16 v[70:73], v[130:133], v[170:173], v[70:73]
	v_mfma_f32_16x16x32_bf16 v[6:9], v[138:141], v[170:173], v[6:9]
	v_mfma_f32_16x16x32_bf16 v[94:97], v[134:137], v[150:153], v[94:97]
	v_mfma_f32_16x16x32_bf16 v[30:33], v[142:145], v[150:153], v[30:33]
	v_mfma_f32_16x16x32_bf16 v[86:89], v[134:137], v[158:161], v[86:89]
	v_mfma_f32_16x16x32_bf16 v[22:25], v[142:145], v[158:161], v[22:25]
	v_mfma_f32_16x16x32_bf16 v[78:81], v[134:137], v[166:169], v[78:81]
	v_mfma_f32_16x16x32_bf16 v[14:17], v[142:145], v[166:169], v[14:17]
	v_mfma_f32_16x16x32_bf16 v[70:73], v[134:137], v[174:177], v[70:73]
	v_mfma_f32_16x16x32_bf16 v[6:9], v[142:145], v[174:177], v[6:9]
	s_setprio 0
	s_barrier
	s_add_u32 s28, s18, 0x40000
	s_addc_u32 s29, s19, 0
	s_add_i32 s27, s65, s84
	v_lshl_add_u64 v[130:131], s[28:29], 0, v[184:185]
	s_mov_b32 m0, s27
	s_nop 0
	global_load_lds_dwordx4 v[130:131], off
	v_lshl_add_u64 v[130:131], s[28:29], 0, v[188:189]
	s_add_i32 m0, s27, 0x2000
	s_nop 0
	global_load_lds_dwordx4 v[130:131], off
	s_waitcnt vmcnt(6)
	s_barrier
	s_setprio 1
	v_mfma_f32_16x16x32_bf16 v[90:93], v[204:207], v[146:149], v[90:93]
	v_mfma_f32_16x16x32_bf16 v[26:29], v[212:215], v[146:149], v[26:29]
	v_mfma_f32_16x16x32_bf16 v[82:85], v[204:207], v[154:157], v[82:85]
	v_mfma_f32_16x16x32_bf16 v[18:21], v[212:215], v[154:157], v[18:21]
	v_mfma_f32_16x16x32_bf16 v[74:77], v[204:207], v[162:165], v[74:77]
	v_mfma_f32_16x16x32_bf16 v[10:13], v[212:215], v[162:165], v[10:13]
	v_mfma_f32_16x16x32_bf16 v[66:69], v[204:207], v[170:173], v[66:69]
	v_mfma_f32_16x16x32_bf16 v[2:5], v[212:215], v[170:173], v[2:5]
	v_mfma_f32_16x16x32_bf16 v[90:93], v[208:211], v[150:153], v[90:93]
	v_mfma_f32_16x16x32_bf16 v[26:29], v[216:219], v[150:153], v[26:29]
	v_mfma_f32_16x16x32_bf16 v[82:85], v[208:211], v[158:161], v[82:85]
	v_mfma_f32_16x16x32_bf16 v[18:21], v[216:219], v[158:161], v[18:21]
	v_mfma_f32_16x16x32_bf16 v[74:77], v[208:211], v[166:169], v[74:77]
	v_mfma_f32_16x16x32_bf16 v[10:13], v[216:219], v[166:169], v[10:13]
	v_mfma_f32_16x16x32_bf16 v[66:69], v[208:211], v[174:177], v[66:69]
	v_mfma_f32_16x16x32_bf16 v[2:5], v[216:219], v[174:177], v[2:5]
	s_setprio 0
	s_add_i32 s27, 0, 0x18000
	v_add_u32_e32 v142, s27, v1
	s_barrier
	ds_read_b128 v[130:133], v142
	ds_read_b128 v[134:137], v142 offset:1024
	ds_read_b128 v[138:141], v142 offset:2048
	ds_read_b128 v[142:145], v142 offset:3072
	s_add_u32 s20, s20, 0x40000
	s_addc_u32 s21, s21, 0
	s_mov_b32 m0, s87
	v_lshl_add_u64 v[204:205], s[20:21], 0, v[182:183]
	ds_read_b128 v[146:149], v229 offset:32768
	ds_read_b128 v[150:153], v229 offset:33792
	ds_read_b128 v[154:157], v229 offset:34816
	ds_read_b128 v[158:161], v229 offset:35840
	ds_read_b128 v[162:165], v229 offset:36864
	ds_read_b128 v[166:169], v229 offset:37888
	ds_read_b128 v[170:173], v229 offset:38912
	ds_read_b128 v[174:177], v229 offset:39936
	global_load_lds_dwordx4 v[204:205], off
	v_lshl_add_u64 v[204:205], s[20:21], 0, v[186:187]
	s_mov_b32 m0, s94
	s_nop 0
	global_load_lds_dwordx4 v[204:205], off
	s_waitcnt lgkmcnt(8)
	s_barrier
	s_waitcnt lgkmcnt(0)
	s_setprio 1
	s_waitcnt lgkmcnt(0)
	v_mfma_f32_16x16x32_bf16 v[126:129], v[130:133], v[146:149], v[126:129]
	v_mfma_f32_16x16x32_bf16 v[62:65], v[138:141], v[146:149], v[62:65]
	v_mfma_f32_16x16x32_bf16 v[118:121], v[130:133], v[154:157], v[118:121]
	v_mfma_f32_16x16x32_bf16 v[54:57], v[138:141], v[154:157], v[54:57]
	v_mfma_f32_16x16x32_bf16 v[110:113], v[130:133], v[162:165], v[110:113]
	v_mfma_f32_16x16x32_bf16 v[46:49], v[138:141], v[162:165], v[46:49]
	v_mfma_f32_16x16x32_bf16 v[102:105], v[130:133], v[170:173], v[102:105]
	v_mfma_f32_16x16x32_bf16 v[38:41], v[138:141], v[170:173], v[38:41]
	v_mfma_f32_16x16x32_bf16 v[126:129], v[134:137], v[150:153], v[126:129]
	v_mfma_f32_16x16x32_bf16 v[62:65], v[142:145], v[150:153], v[62:65]
	v_mfma_f32_16x16x32_bf16 v[118:121], v[134:137], v[158:161], v[118:121]
	v_mfma_f32_16x16x32_bf16 v[54:57], v[142:145], v[158:161], v[54:57]
	v_mfma_f32_16x16x32_bf16 v[110:113], v[134:137], v[166:169], v[110:113]
	v_mfma_f32_16x16x32_bf16 v[46:49], v[142:145], v[166:169], v[46:49]
	v_mfma_f32_16x16x32_bf16 v[102:105], v[134:137], v[174:177], v[102:105]
	v_mfma_f32_16x16x32_bf16 v[38:41], v[142:145], v[174:177], v[38:41]
	s_setprio 0
	s_barrier
	s_add_i32 s20, 0, 0x1c000
	s_add_i32 s21, s27, s84
	v_add_u32_e32 v190, s20, v1
	v_lshl_add_u64 v[220:221], v[220:221], 0, s[2:3]
	s_mov_b32 m0, s21
	ds_read_b128 v[204:207], v190
	ds_read_b128 v[208:211], v190 offset:1024
	ds_read_b128 v[212:215], v190 offset:2048
	ds_read_b128 v[216:219], v190 offset:3072
	global_load_lds_dwordx4 v[220:221], off
	v_lshl_add_u64 v[220:221], v[222:223], 0, s[2:3]
	s_add_i32 m0, s21, 0x2000
	s_nop 0
	global_load_lds_dwordx4 v[220:221], off
	s_barrier
	s_waitcnt lgkmcnt(0)
	s_setprio 1
	s_waitcnt lgkmcnt(0)
	v_mfma_f32_16x16x32_bf16 v[122:125], v[204:207], v[146:149], v[122:125]
	v_mfma_f32_16x16x32_bf16 v[58:61], v[212:215], v[146:149], v[58:61]
	v_mfma_f32_16x16x32_bf16 v[114:117], v[204:207], v[154:157], v[114:117]
	v_mfma_f32_16x16x32_bf16 v[50:53], v[212:215], v[154:157], v[50:53]
	v_mfma_f32_16x16x32_bf16 v[106:109], v[204:207], v[162:165], v[106:109]
	v_mfma_f32_16x16x32_bf16 v[42:45], v[212:215], v[162:165], v[42:45]
	v_mfma_f32_16x16x32_bf16 v[98:101], v[204:207], v[170:173], v[98:101]
	v_mfma_f32_16x16x32_bf16 v[34:37], v[212:215], v[170:173], v[34:37]
	v_mfma_f32_16x16x32_bf16 v[122:125], v[208:211], v[150:153], v[122:125]
	v_mfma_f32_16x16x32_bf16 v[58:61], v[216:219], v[150:153], v[58:61]
	v_mfma_f32_16x16x32_bf16 v[114:117], v[208:211], v[158:161], v[114:117]
	v_mfma_f32_16x16x32_bf16 v[50:53], v[216:219], v[158:161], v[50:53]
	v_mfma_f32_16x16x32_bf16 v[106:109], v[208:211], v[166:169], v[106:109]
	v_mfma_f32_16x16x32_bf16 v[42:45], v[216:219], v[166:169], v[42:45]
	v_mfma_f32_16x16x32_bf16 v[98:101], v[208:211], v[174:177], v[98:101]
	v_mfma_f32_16x16x32_bf16 v[34:37], v[216:219], v[174:177], v[34:37]
	s_setprio 0
	s_mov_b32 m0, s97
	v_lshl_add_u64 v[220:221], v[224:225], 0, s[2:3]
	s_barrier
	ds_read_b128 v[146:149], v229 offset:49152
	ds_read_b128 v[150:153], v229 offset:50176
	ds_read_b128 v[154:157], v229 offset:51200
	ds_read_b128 v[158:161], v229 offset:52224
	ds_read_b128 v[162:165], v229 offset:53248
	ds_read_b128 v[166:169], v229 offset:54272
	ds_read_b128 v[170:173], v229 offset:55296
	ds_read_b128 v[174:177], v229 offset:56320
	global_load_lds_dwordx4 v[220:221], off
	v_lshl_add_u64 v[220:221], v[232:233], 0, s[2:3]
	s_mov_b32 m0, s96
	s_nop 0
	global_load_lds_dwordx4 v[220:221], off
	s_barrier
	s_waitcnt lgkmcnt(0)
	s_setprio 1
	s_waitcnt lgkmcnt(0)
	v_mfma_f32_16x16x32_bf16 v[94:97], v[130:133], v[146:149], v[94:97]
	v_mfma_f32_16x16x32_bf16 v[30:33], v[138:141], v[146:149], v[30:33]
	v_mfma_f32_16x16x32_bf16 v[86:89], v[130:133], v[154:157], v[86:89]
	v_mfma_f32_16x16x32_bf16 v[22:25], v[138:141], v[154:157], v[22:25]
	v_mfma_f32_16x16x32_bf16 v[78:81], v[130:133], v[162:165], v[78:81]
	v_mfma_f32_16x16x32_bf16 v[14:17], v[138:141], v[162:165], v[14:17]
	v_mfma_f32_16x16x32_bf16 v[70:73], v[130:133], v[170:173], v[70:73]
	v_mfma_f32_16x16x32_bf16 v[6:9], v[138:141], v[170:173], v[6:9]
	v_mfma_f32_16x16x32_bf16 v[94:97], v[134:137], v[150:153], v[94:97]
	v_mfma_f32_16x16x32_bf16 v[30:33], v[142:145], v[150:153], v[30:33]
	v_mfma_f32_16x16x32_bf16 v[86:89], v[134:137], v[158:161], v[86:89]
	v_mfma_f32_16x16x32_bf16 v[22:25], v[142:145], v[158:161], v[22:25]
	v_mfma_f32_16x16x32_bf16 v[78:81], v[134:137], v[166:169], v[78:81]
	v_mfma_f32_16x16x32_bf16 v[14:17], v[142:145], v[166:169], v[14:17]
	v_mfma_f32_16x16x32_bf16 v[70:73], v[134:137], v[174:177], v[70:73]
	v_mfma_f32_16x16x32_bf16 v[6:9], v[142:145], v[174:177], v[6:9]
	s_setprio 0
	s_barrier
	s_add_u32 s18, s18, 0x40080
	s_addc_u32 s19, s19, 0
	s_add_i32 s20, s20, s84
	v_lshl_add_u64 v[130:131], s[18:19], 0, v[184:185]
	s_mov_b32 m0, s20
	s_nop 0
	global_load_lds_dwordx4 v[130:131], off
	v_lshl_add_u64 v[130:131], s[18:19], 0, v[188:189]
	s_add_i32 m0, s20, 0x2000
	s_nop 0
	global_load_lds_dwordx4 v[130:131], off
	s_waitcnt vmcnt(6)
	s_barrier
	s_setprio 1
	v_mfma_f32_16x16x32_bf16 v[90:93], v[204:207], v[146:149], v[90:93]
	v_mfma_f32_16x16x32_bf16 v[26:29], v[212:215], v[146:149], v[26:29]
	v_mfma_f32_16x16x32_bf16 v[82:85], v[204:207], v[154:157], v[82:85]
	v_mfma_f32_16x16x32_bf16 v[18:21], v[212:215], v[154:157], v[18:21]
	v_mfma_f32_16x16x32_bf16 v[74:77], v[204:207], v[162:165], v[74:77]
	v_mfma_f32_16x16x32_bf16 v[10:13], v[212:215], v[162:165], v[10:13]
	v_mfma_f32_16x16x32_bf16 v[66:69], v[204:207], v[170:173], v[66:69]
	v_mfma_f32_16x16x32_bf16 v[2:5], v[212:215], v[170:173], v[2:5]
	v_mfma_f32_16x16x32_bf16 v[90:93], v[208:211], v[150:153], v[90:93]
	v_mfma_f32_16x16x32_bf16 v[26:29], v[216:219], v[150:153], v[26:29]
	v_mfma_f32_16x16x32_bf16 v[82:85], v[208:211], v[158:161], v[82:85]
	v_mfma_f32_16x16x32_bf16 v[18:21], v[216:219], v[158:161], v[18:21]
	v_mfma_f32_16x16x32_bf16 v[74:77], v[208:211], v[166:169], v[74:77]
	v_mfma_f32_16x16x32_bf16 v[10:13], v[216:219], v[166:169], v[10:13]
	v_mfma_f32_16x16x32_bf16 v[66:69], v[208:211], v[174:177], v[66:69]
	v_mfma_f32_16x16x32_bf16 v[2:5], v[216:219], v[174:177], v[2:5]
	s_setprio 0
	s_add_i32 s26, s26, 2
	s_add_u32 s16, s16, 0x100
	s_addc_u32 s17, s17, 0
	s_add_u32 s24, s24, 0x100
	s_addc_u32 s25, s25, 0
	s_cmp_gt_u32 s26, 13
	s_barrier
	s_cbranch_scc0 .LBB0_2030
	s_mov_b64 s[16:17], -1
	s_cmp_lt_i32 s12, 64
	v_lshl_or_b32 v204, s14, 7, v181
	s_cbranch_scc0 .Lmy_ffnA_sample
	s_load_dwordx2 s[36:37], s[78:79], 0x268
	s_load_dwordx2 s[38:39], s[78:79], 0x2a0
	s_load_dwordx4 s[40:43], s[78:79], 0x70
	s_load_dwordx2 s[44:45], s[78:79], 0x120
	v_and_b32_e32 v204, 15, v248
	v_bfe_u32 v205, v248, 8, 1
	v_bfe_u32 v206, v248, 6, 2
	v_bfe_u32 v207, v248, 4, 2
	v_lshlrev_b32_e32 v206, 5, v206
	v_lshl_or_b32 v206, v207, 3, v206
	s_lshl_b32 s13, s14, 7
	v_add_u32_e32 v206, s13, v206
	s_lshl_b32 s13, s12, 8
	v_lshl_add_u32 v207, v205, 6, v204
	v_add_u32_e32 v207, s13, v207
	v_mul_u32_u24_e32 v231, 0x1600, v207
	v_lshl_add_u32 v231, v206, 1, v231
	v_lshlrev_b32_e32 v232, 2, v206
	s_lshl_b32 s13, s12, 4
	v_lshl_add_u32 v233, v205, 2, s13
	v_add_u32_e32 v208, -12, v204
	v_cmp_gt_u32_e32 vcc, 2, v204
	s_nop 1
	v_cndmask_b32_e32 v208, v208, v204, vcc
	v_add_u32_e32 v233, v233, v208
	v_mul_u32_u24_e32 v233, 0x2c00, v233
	v_lshl_add_u32 v233, v206, 1, v233
	s_lshr_b32 s13, s12, 3
	s_lshl_b32 s13, s13, 1
	s_add_i32 s13, s13, -14
	v_add_u32_e32 v234, s13, v204
	v_mul_u32_u24_e32 v234, 0x5800, v234
	v_lshl_add_u32 v234, v206, 2, v234
	v_readfirstlane_b32 s4, v248
	s_lshr_b32 s4, s4, 8
	s_and_b32 s5, s12, 7
	s_cmp_eq_u32 s5, 7
	s_cselect_b32 s5, 1, 0
	s_and_b32 s5, s5, s4
	s_waitcnt lgkmcnt(0)
	global_load_dwordx4 v[130:133], v232, s[40:41]
	v_add_u32_e32 v213, 0x5800, v232
	global_load_dwordx4 v[134:137], v213, s[40:41]
	v_add_u32_e32 v214, 0xb000, v232
	global_load_dwordx4 v[138:141], v214, s[40:41]
	global_load_dwordx4 v[142:145], v232, s[42:43]
	v_add_u32_e32 v215, 0x2c00, v232
	global_load_dwordx4 v[146:149], v215, s[40:41]
	v_add_u32_e32 v216, 0x8400, v232
	global_load_dwordx4 v[150:153], v216, s[40:41]
	v_add_u32_e32 v217, 0xdc00, v232
	global_load_dwordx4 v[154:157], v217, s[40:41]
	v_add_u32_e32 v218, 0x2c00, v232
	global_load_dwordx4 v[158:161], v218, s[42:43]
	s_mov_b32 exec_lo, 0x30003
	s_mov_b32 exec_hi, 0x30003
	v_cvt_pk_bf16_f32 v162, v126, v127
	v_cvt_pk_bf16_f32 v163, v128, v129
	global_store_dwordx2 v233, v[162:163], s[38:39]
	v_cvt_pk_bf16_f32 v164, v122, v123
	v_cvt_pk_bf16_f32 v165, v124, v125
	v_add_u32_e32 v220, 0x1600, v233
	global_store_dwordx2 v220, v[164:165], s[38:39]
	v_cvt_pk_bf16_f32 v166, v94, v95
	v_cvt_pk_bf16_f32 v167, v96, v97
	v_add_u32_e32 v221, 0x16000, v233
	global_store_dwordx2 v221, v[166:167], s[38:39]
	v_cvt_pk_bf16_f32 v168, v90, v91
	v_cvt_pk_bf16_f32 v169, v92, v93
	v_add_u32_e32 v222, 0x17600, v233
	global_store_dwordx2 v222, v[168:169], s[38:39]
	v_cvt_pk_bf16_f32 v170, v62, v63
	v_cvt_pk_bf16_f32 v171, v64, v65
	v_add_u32_e32 v223, 0x8, v233
	global_store_dwordx2 v223, v[170:171], s[38:39]
	v_cvt_pk_bf16_f32 v172, v58, v59
	v_cvt_pk_bf16_f32 v173, v60, v61
	v_add_u32_e32 v224, 0x1608, v233
	global_store_dwordx2 v224, v[172:173], s[38:39]
	v_cvt_pk_bf16_f32 v174, v30, v31
	v_cvt_pk_bf16_f32 v175, v32, v33
	v_add_u32_e32 v225, 0x16008, v233
	global_store_dwordx2 v225, v[174:175], s[38:39]
	v_cvt_pk_bf16_f32 v176, v26, v27
	v_cvt_pk_bf16_f32 v177, v28, v29
	v_add_u32_e32 v226, 0x17608, v233
	global_store_dwordx2 v226, v[176:177], s[38:39]
	s_mov_b32 exec_lo, 0xc000c000
	s_mov_b32 exec_hi, 0xc000c000
	v_cvt_pk_bf16_f32 v162, v102, v103
	v_cvt_pk_bf16_f32 v163, v104, v105
	global_store_dwordx2 v233, v[162:163], s[38:39]
	v_cvt_pk_bf16_f32 v164, v98, v99
	v_cvt_pk_bf16_f32 v165, v100, v101
	v_add_u32_e32 v220, 0x1600, v233
	global_store_dwordx2 v220, v[164:165], s[38:39]
	v_cvt_pk_bf16_f32 v166, v70, v71
	v_cvt_pk_bf16_f32 v167, v72, v73
	v_add_u32_e32 v221, 0x16000, v233
	global_store_dwordx2 v221, v[166:167], s[38:39]
	v_cvt_pk_bf16_f32 v168, v66, v67
	v_cvt_pk_bf16_f32 v169, v68, v69
	v_add_u32_e32 v222, 0x17600, v233
	global_store_dwordx2 v222, v[168:169], s[38:39]
	v_cvt_pk_bf16_f32 v170, v38, v39
	v_cvt_pk_bf16_f32 v171, v40, v41
	v_add_u32_e32 v223, 0x8, v233
	global_store_dwordx2 v223, v[170:171], s[38:39]
	v_cvt_pk_bf16_f32 v172, v34, v35
	v_cvt_pk_bf16_f32 v173, v36, v37
	v_add_u32_e32 v224, 0x1608, v233
	global_store_dwordx2 v224, v[172:173], s[38:39]
	v_cvt_pk_bf16_f32 v174, v6, v7
	v_cvt_pk_bf16_f32 v175, v8, v9
	v_add_u32_e32 v225, 0x16008, v233
	global_store_dwordx2 v225, v[174:175], s[38:39]
	v_cvt_pk_bf16_f32 v176, v2, v3
	v_cvt_pk_bf16_f32 v177, v4, v5
	v_add_u32_e32 v226, 0x17608, v233
	global_store_dwordx2 v226, v[176:177], s[38:39]
	s_cmp_lg_u32 s5, 0
	s_cbranch_scc0 .Lmy_ffnA_ncp
	global_store_dwordx4 v234, v[70:73], s[44:45]
	v_add_u32_e32 v220, 0x2c00, v234
	global_store_dwordx4 v220, v[66:69], s[44:45]
	v_add_u32_e32 v221, 0x10, v234
	global_store_dwordx4 v221, v[6:9], s[44:45]
	v_add_u32_e32 v222, 0x2c10, v234
	global_store_dwordx4 v222, v[2:5], s[44:45]
.Lmy_ffnA_ncp:
	s_mov_b64 exec, -1
	s_waitcnt vmcnt(16)
	v_pk_fma_f32 v[162:163], v[138:139], v[126:127], v[142:143]
	v_pk_fma_f32 v[164:165], v[140:141], v[128:129], v[144:145]
	v_pk_fma_f32 v[166:167], v[154:155], v[122:123], v[158:159]
	v_pk_fma_f32 v[168:169], v[156:157], v[124:125], v[160:161]
	v_fmac_f32_dpp v162, v126, v134 row_shr:1 row_mask:0xf bank_mask:0xf
	v_fmac_f32_dpp v166, v122, v150 row_shr:1 row_mask:0xf bank_mask:0xf
	v_fmac_f32_dpp v163, v127, v135 row_shr:1 row_mask:0xf bank_mask:0xf
	v_fmac_f32_dpp v167, v123, v151 row_shr:1 row_mask:0xf bank_mask:0xf
	v_fmac_f32_dpp v164, v128, v136 row_shr:1 row_mask:0xf bank_mask:0xf
	v_fmac_f32_dpp v168, v124, v152 row_shr:1 row_mask:0xf bank_mask:0xf
	v_fmac_f32_dpp v165, v129, v137 row_shr:1 row_mask:0xf bank_mask:0xf
	v_fmac_f32_dpp v169, v125, v153 row_shr:1 row_mask:0xf bank_mask:0xf
	v_fmac_f32_dpp v162, v126, v130 row_shr:2 row_mask:0xf bank_mask:0xf
	v_fmac_f32_dpp v166, v122, v146 row_shr:2 row_mask:0xf bank_mask:0xf
	v_fmac_f32_dpp v163, v127, v131 row_shr:2 row_mask:0xf bank_mask:0xf
	v_fmac_f32_dpp v167, v123, v147 row_shr:2 row_mask:0xf bank_mask:0xf
	v_fmac_f32_dpp v164, v128, v132 row_shr:2 row_mask:0xf bank_mask:0xf
	v_fmac_f32_dpp v168, v124, v148 row_shr:2 row_mask:0xf bank_mask:0xf
	v_fmac_f32_dpp v165, v129, v133 row_shr:2 row_mask:0xf bank_mask:0xf
	v_fmac_f32_dpp v169, v125, v149 row_shr:2 row_mask:0xf bank_mask:0xf
	v_mul_f32_e32 v170, 0xbfb8aa3b, v166
	v_mul_f32_e32 v171, 0xbfb8aa3b, v167
	v_mul_f32_e32 v172, 0xbfb8aa3b, v168
	v_mul_f32_e32 v173, 0xbfb8aa3b, v169
	v_exp_f32_e32 v170, v170
	v_exp_f32_e32 v171, v171
	v_exp_f32_e32 v172, v172
	v_exp_f32_e32 v173, v173
	v_add_f32_e32 v170, 1.0, v170
	v_add_f32_e32 v171, 1.0, v171
	v_add_f32_e32 v172, 1.0, v172
	v_add_f32_e32 v173, 1.0, v173
	v_rcp_f32_e32 v170, v170
	v_rcp_f32_e32 v171, v171
	v_rcp_f32_e32 v172, v172
	v_rcp_f32_e32 v173, v173
	v_mul_f32_e32 v170, v166, v170
	v_mul_f32_e32 v171, v167, v171
	v_mul_f32_e32 v172, v168, v172
	v_mul_f32_e32 v173, v169, v173
	v_mul_f32_e32 v170, v162, v170
	v_mul_f32_e32 v171, v163, v171
	v_mul_f32_e32 v172, v164, v172
	v_mul_f32_e32 v173, v165, v173
	v_cvt_pk_bf16_f32 v174, v170, v171
	v_cvt_pk_bf16_f32 v175, v172, v173
	v_mov_b32_e32 v176, v231
	s_mov_b32 exec_lo, 0xfffcfffc
	s_mov_b32 exec_hi, 0xfffcfffc
	global_store_dwordx2 v176, v[174:175], s[36:37]
	s_mov_b64 exec, -1
	v_pk_fma_f32 v[204:205], v[138:139], v[118:119], v[142:143]
	v_pk_fma_f32 v[206:207], v[140:141], v[120:121], v[144:145]
	v_pk_fma_f32 v[208:209], v[154:155], v[114:115], v[158:159]
	v_pk_fma_f32 v[210:211], v[156:157], v[116:117], v[160:161]
	v_fmac_f32_dpp v204, v118, v134 row_shr:1 row_mask:0xf bank_mask:0xf
	v_fmac_f32_dpp v208, v114, v150 row_shr:1 row_mask:0xf bank_mask:0xf
	v_fmac_f32_dpp v205, v119, v135 row_shr:1 row_mask:0xf bank_mask:0xf
	v_fmac_f32_dpp v209, v115, v151 row_shr:1 row_mask:0xf bank_mask:0xf
	v_fmac_f32_dpp v206, v120, v136 row_shr:1 row_mask:0xf bank_mask:0xf
	v_fmac_f32_dpp v210, v116, v152 row_shr:1 row_mask:0xf bank_mask:0xf
	v_fmac_f32_dpp v207, v121, v137 row_shr:1 row_mask:0xf bank_mask:0xf
	v_fmac_f32_dpp v211, v117, v153 row_shr:1 row_mask:0xf bank_mask:0xf
	v_fmac_f32_dpp v204, v118, v130 row_shr:2 row_mask:0xf bank_mask:0xf
	v_fmac_f32_dpp v208, v114, v146 row_shr:2 row_mask:0xf bank_mask:0xf
	v_fmac_f32_dpp v205, v119, v131 row_shr:2 row_mask:0xf bank_mask:0xf
	v_fmac_f32_dpp v209, v115, v147 row_shr:2 row_mask:0xf bank_mask:0xf
	v_fmac_f32_dpp v206, v120, v132 row_shr:2 row_mask:0xf bank_mask:0xf
	v_fmac_f32_dpp v210, v116, v148 row_shr:2 row_mask:0xf bank_mask:0xf
	v_fmac_f32_dpp v207, v121, v133 row_shr:2 row_mask:0xf bank_mask:0xf
	v_fmac_f32_dpp v211, v117, v149 row_shr:2 row_mask:0xf bank_mask:0xf
	v_fmac_f32_dpp v204, v126, v134 row_shl:15 row_mask:0xf bank_mask:0xf
	v_fmac_f32_dpp v208, v122, v150 row_shl:15 row_mask:0xf bank_mask:0xf
	v_fmac_f32_dpp v205, v127, v135 row_shl:15 row_mask:0xf bank_mask:0xf
	v_fmac_f32_dpp v209, v123, v151 row_shl:15 row_mask:0xf bank_mask:0xf
	v_fmac_f32_dpp v206, v128, v136 row_shl:15 row_mask:0xf bank_mask:0xf
	v_fmac_f32_dpp v210, v124, v152 row_shl:15 row_mask:0xf bank_mask:0xf
	v_fmac_f32_dpp v207, v129, v137 row_shl:15 row_mask:0xf bank_mask:0xf
	v_fmac_f32_dpp v211, v125, v153 row_shl:15 row_mask:0xf bank_mask:0xf
	v_fmac_f32_dpp v204, v126, v130 row_shl:14 row_mask:0xf bank_mask:0xf
	v_fmac_f32_dpp v208, v122, v146 row_shl:14 row_mask:0xf bank_mask:0xf
	v_fmac_f32_dpp v205, v127, v131 row_shl:14 row_mask:0xf bank_mask:0xf
	v_fmac_f32_dpp v209, v123, v147 row_shl:14 row_mask:0xf bank_mask:0xf
	v_fmac_f32_dpp v206, v128, v132 row_shl:14 row_mask:0xf bank_mask:0xf
	v_fmac_f32_dpp v210, v124, v148 row_shl:14 row_mask:0xf bank_mask:0xf
	v_fmac_f32_dpp v207, v129, v133 row_shl:14 row_mask:0xf bank_mask:0xf
	v_fmac_f32_dpp v211, v125, v149 row_shl:14 row_mask:0xf bank_mask:0xf
	v_mul_f32_e32 v212, 0xbfb8aa3b, v208
	v_mul_f32_e32 v213, 0xbfb8aa3b, v209
	v_mul_f32_e32 v214, 0xbfb8aa3b, v210
	v_mul_f32_e32 v215, 0xbfb8aa3b, v211
	v_exp_f32_e32 v212, v212
	v_exp_f32_e32 v213, v213
	v_exp_f32_e32 v214, v214
	v_exp_f32_e32 v215, v215
	v_add_f32_e32 v212, 1.0, v212
	v_add_f32_e32 v213, 1.0, v213
	v_add_f32_e32 v214, 1.0, v214
	v_add_f32_e32 v215, 1.0, v215
	v_rcp_f32_e32 v212, v212
	v_rcp_f32_e32 v213, v213
	v_rcp_f32_e32 v214, v214
	v_rcp_f32_e32 v215, v215
	v_mul_f32_e32 v212, v208, v212
	v_mul_f32_e32 v213, v209, v213
	v_mul_f32_e32 v214, v210, v214
	v_mul_f32_e32 v215, v211, v215
	v_mul_f32_e32 v212, v204, v212
	v_mul_f32_e32 v213, v205, v213
	v_mul_f32_e32 v214, v206, v214
	v_mul_f32_e32 v215, v207, v215
	v_cvt_pk_bf16_f32 v216, v212, v213
	v_cvt_pk_bf16_f32 v217, v214, v215
	v_add_u32_e32 v218, 0x16000, v231
	global_store_dwordx2 v218, v[216:217], s[36:37]
	v_pk_fma_f32 v[162:163], v[138:139], v[110:111], v[142:143]
	v_pk_fma_f32 v[164:165], v[140:141], v[112:113], v[144:145]
	v_pk_fma_f32 v[166:167], v[154:155], v[106:107], v[158:159]
	v_pk_fma_f32 v[168:169], v[156:157], v[108:109], v[160:161]
	v_fmac_f32_dpp v162, v110, v134 row_shr:1 row_mask:0xf bank_mask:0xf
	v_fmac_f32_dpp v166, v106, v150 row_shr:1 row_mask:0xf bank_mask:0xf
	v_fmac_f32_dpp v163, v111, v135 row_shr:1 row_mask:0xf bank_mask:0xf
	v_fmac_f32_dpp v167, v107, v151 row_shr:1 row_mask:0xf bank_mask:0xf
	v_fmac_f32_dpp v164, v112, v136 row_shr:1 row_mask:0xf bank_mask:0xf
	v_fmac_f32_dpp v168, v108, v152 row_shr:1 row_mask:0xf bank_mask:0xf
	v_fmac_f32_dpp v165, v113, v137 row_shr:1 row_mask:0xf bank_mask:0xf
	v_fmac_f32_dpp v169, v109, v153 row_shr:1 row_mask:0xf bank_mask:0xf
	v_fmac_f32_dpp v162, v110, v130 row_shr:2 row_mask:0xf bank_mask:0xf
	v_fmac_f32_dpp v166, v106, v146 row_shr:2 row_mask:0xf bank_mask:0xf
	v_fmac_f32_dpp v163, v111, v131 row_shr:2 row_mask:0xf bank_mask:0xf
	v_fmac_f32_dpp v167, v107, v147 row_shr:2 row_mask:0xf bank_mask:0xf
	v_fmac_f32_dpp v164, v112, v132 row_shr:2 row_mask:0xf bank_mask:0xf
	v_fmac_f32_dpp v168, v108, v148 row_shr:2 row_mask:0xf bank_mask:0xf
	v_fmac_f32_dpp v165, v113, v133 row_shr:2 row_mask:0xf bank_mask:0xf
	v_fmac_f32_dpp v169, v109, v149 row_shr:2 row_mask:0xf bank_mask:0xf
	v_fmac_f32_dpp v162, v118, v134 row_shl:15 row_mask:0xf bank_mask:0xf
	v_fmac_f32_dpp v166, v114, v150 row_shl:15 row_mask:0xf bank_mask:0xf
	v_fmac_f32_dpp v163, v119, v135 row_shl:15 row_mask:0xf bank_mask:0xf
	v_fmac_f32_dpp v167, v115, v151 row_shl:15 row_mask:0xf bank_mask:0xf
	v_fmac_f32_dpp v164, v120, v136 row_shl:15 row_mask:0xf bank_mask:0xf
	v_fmac_f32_dpp v168, v116, v152 row_shl:15 row_mask:0xf bank_mask:0xf
	v_fmac_f32_dpp v165, v121, v137 row_shl:15 row_mask:0xf bank_mask:0xf
	v_fmac_f32_dpp v169, v117, v153 row_shl:15 row_mask:0xf bank_mask:0xf
	v_fmac_f32_dpp v162, v118, v130 row_shl:14 row_mask:0xf bank_mask:0xf
	v_fmac_f32_dpp v166, v114, v146 row_shl:14 row_mask:0xf bank_mask:0xf
	v_fmac_f32_dpp v163, v119, v131 row_shl:14 row_mask:0xf bank_mask:0xf
	v_fmac_f32_dpp v167, v115, v147 row_shl:14 row_mask:0xf bank_mask:0xf
	v_fmac_f32_dpp v164, v120, v132 row_shl:14 row_mask:0xf bank_mask:0xf
	v_fmac_f32_dpp v168, v116, v148 row_shl:14 row_mask:0xf bank_mask:0xf
	v_fmac_f32_dpp v165, v121, v133 row_shl:14 row_mask:0xf bank_mask:0xf
	v_fmac_f32_dpp v169, v117, v149 row_shl:14 row_mask:0xf bank_mask:0xf
	v_mul_f32_e32 v170, 0xbfb8aa3b, v166
	v_mul_f32_e32 v171, 0xbfb8aa3b, v167
	v_mul_f32_e32 v172, 0xbfb8aa3b, v168
	v_mul_f32_e32 v173, 0xbfb8aa3b, v169
	v_exp_f32_e32 v170, v170
	v_exp_f32_e32 v171, v171
	v_exp_f32_e32 v172, v172
	v_exp_f32_e32 v173, v173
	v_add_f32_e32 v170, 1.0, v170
	v_add_f32_e32 v171, 1.0, v171
	v_add_f32_e32 v172, 1.0, v172
	v_add_f32_e32 v173, 1.0, v173
	v_rcp_f32_e32 v170, v170
	v_rcp_f32_e32 v171, v171
	v_rcp_f32_e32 v172, v172
	v_rcp_f32_e32 v173, v173
	v_mul_f32_e32 v170, v166, v170
	v_mul_f32_e32 v171, v167, v171
	v_mul_f32_e32 v172, v168, v172
	v_mul_f32_e32 v173, v169, v173
	v_mul_f32_e32 v170, v162, v170
	v_mul_f32_e32 v171, v163, v171
	v_mul_f32_e32 v172, v164, v172
	v_mul_f32_e32 v173, v165, v173
	v_cvt_pk_bf16_f32 v174, v170, v171
	v_cvt_pk_bf16_f32 v175, v172, v173
	v_add_u32_e32 v176, 0x2c000, v231
	global_store_dwordx2 v176, v[174:175], s[36:37]
	v_pk_fma_f32 v[204:205], v[138:139], v[102:103], v[142:143]
	v_pk_fma_f32 v[206:207], v[140:141], v[104:105], v[144:145]
	v_pk_fma_f32 v[208:209], v[154:155], v[98:99], v[158:159]
	v_pk_fma_f32 v[210:211], v[156:157], v[100:101], v[160:161]
	v_fmac_f32_dpp v204, v102, v134 row_shr:1 row_mask:0xf bank_mask:0xf
	v_fmac_f32_dpp v208, v98, v150 row_shr:1 row_mask:0xf bank_mask:0xf
	v_fmac_f32_dpp v205, v103, v135 row_shr:1 row_mask:0xf bank_mask:0xf
	v_fmac_f32_dpp v209, v99, v151 row_shr:1 row_mask:0xf bank_mask:0xf
	v_fmac_f32_dpp v206, v104, v136 row_shr:1 row_mask:0xf bank_mask:0xf
	v_fmac_f32_dpp v210, v100, v152 row_shr:1 row_mask:0xf bank_mask:0xf
	v_fmac_f32_dpp v207, v105, v137 row_shr:1 row_mask:0xf bank_mask:0xf
	v_fmac_f32_dpp v211, v101, v153 row_shr:1 row_mask:0xf bank_mask:0xf
	v_fmac_f32_dpp v204, v102, v130 row_shr:2 row_mask:0xf bank_mask:0xf
	v_fmac_f32_dpp v208, v98, v146 row_shr:2 row_mask:0xf bank_mask:0xf
	v_fmac_f32_dpp v205, v103, v131 row_shr:2 row_mask:0xf bank_mask:0xf
	v_fmac_f32_dpp v209, v99, v147 row_shr:2 row_mask:0xf bank_mask:0xf
	v_fmac_f32_dpp v206, v104, v132 row_shr:2 row_mask:0xf bank_mask:0xf
	v_fmac_f32_dpp v210, v100, v148 row_shr:2 row_mask:0xf bank_mask:0xf
	v_fmac_f32_dpp v207, v105, v133 row_shr:2 row_mask:0xf bank_mask:0xf
	v_fmac_f32_dpp v211, v101, v149 row_shr:2 row_mask:0xf bank_mask:0xf
	v_fmac_f32_dpp v204, v110, v134 row_shl:15 row_mask:0xf bank_mask:0xf
	v_fmac_f32_dpp v208, v106, v150 row_shl:15 row_mask:0xf bank_mask:0xf
	v_fmac_f32_dpp v205, v111, v135 row_shl:15 row_mask:0xf bank_mask:0xf
	v_fmac_f32_dpp v209, v107, v151 row_shl:15 row_mask:0xf bank_mask:0xf
	v_fmac_f32_dpp v206, v112, v136 row_shl:15 row_mask:0xf bank_mask:0xf
	v_fmac_f32_dpp v210, v108, v152 row_shl:15 row_mask:0xf bank_mask:0xf
	v_fmac_f32_dpp v207, v113, v137 row_shl:15 row_mask:0xf bank_mask:0xf
	v_fmac_f32_dpp v211, v109, v153 row_shl:15 row_mask:0xf bank_mask:0xf
	v_fmac_f32_dpp v204, v110, v130 row_shl:14 row_mask:0xf bank_mask:0xf
	v_fmac_f32_dpp v208, v106, v146 row_shl:14 row_mask:0xf bank_mask:0xf
	v_fmac_f32_dpp v205, v111, v131 row_shl:14 row_mask:0xf bank_mask:0xf
	v_fmac_f32_dpp v209, v107, v147 row_shl:14 row_mask:0xf bank_mask:0xf
	v_fmac_f32_dpp v206, v112, v132 row_shl:14 row_mask:0xf bank_mask:0xf
	v_fmac_f32_dpp v210, v108, v148 row_shl:14 row_mask:0xf bank_mask:0xf
	v_fmac_f32_dpp v207, v113, v133 row_shl:14 row_mask:0xf bank_mask:0xf
	v_fmac_f32_dpp v211, v109, v149 row_shl:14 row_mask:0xf bank_mask:0xf
	v_mul_f32_e32 v212, 0xbfb8aa3b, v208
	v_mul_f32_e32 v213, 0xbfb8aa3b, v209
	v_mul_f32_e32 v214, 0xbfb8aa3b, v210
	v_mul_f32_e32 v215, 0xbfb8aa3b, v211
	v_exp_f32_e32 v212, v212
	v_exp_f32_e32 v213, v213
	v_exp_f32_e32 v214, v214
	v_exp_f32_e32 v215, v215
	v_add_f32_e32 v212, 1.0, v212
	v_add_f32_e32 v213, 1.0, v213
	v_add_f32_e32 v214, 1.0, v214
	v_add_f32_e32 v215, 1.0, v215
	v_rcp_f32_e32 v212, v212
	v_rcp_f32_e32 v213, v213
	v_rcp_f32_e32 v214, v214
	v_rcp_f32_e32 v215, v215
	v_mul_f32_e32 v212, v208, v212
	v_mul_f32_e32 v213, v209, v213
	v_mul_f32_e32 v214, v210, v214
	v_mul_f32_e32 v215, v211, v215
	v_mul_f32_e32 v212, v204, v212
	v_mul_f32_e32 v213, v205, v213
	v_mul_f32_e32 v214, v206, v214
	v_mul_f32_e32 v215, v207, v215
	v_cvt_pk_bf16_f32 v216, v212, v213
	v_cvt_pk_bf16_f32 v217, v214, v215
	v_add_u32_e32 v218, 0x42000, v231
	global_store_dwordx2 v218, v[216:217], s[36:37]
	global_load_dwordx4 v[98:101], v232, s[40:41] offset:16
	v_add_u32_e32 v190, 0x5800, v232
	global_load_dwordx4 v[102:105], v190, s[40:41] offset:16
	v_add_u32_e32 v219, 0xb000, v232
	global_load_dwordx4 v[106:109], v219, s[40:41] offset:16
	global_load_dwordx4 v[110:113], v232, s[42:43] offset:16
	v_add_u32_e32 v220, 0x2c00, v232
	global_load_dwordx4 v[114:117], v220, s[40:41] offset:16
	v_add_u32_e32 v221, 0x8400, v232
	global_load_dwordx4 v[118:121], v221, s[40:41] offset:16
	v_add_u32_e32 v222, 0xdc00, v232
	global_load_dwordx4 v[122:125], v222, s[40:41] offset:16
	v_add_u32_e32 v223, 0x2c00, v232
	global_load_dwordx4 v[126:129], v223, s[42:43] offset:16
	v_pk_fma_f32 v[162:163], v[138:139], v[94:95], v[142:143]
	v_pk_fma_f32 v[164:165], v[140:141], v[96:97], v[144:145]
	v_pk_fma_f32 v[166:167], v[154:155], v[90:91], v[158:159]
	v_pk_fma_f32 v[168:169], v[156:157], v[92:93], v[160:161]
	v_fmac_f32_dpp v162, v94, v134 row_shr:1 row_mask:0xf bank_mask:0xf
	v_fmac_f32_dpp v166, v90, v150 row_shr:1 row_mask:0xf bank_mask:0xf
	v_fmac_f32_dpp v163, v95, v135 row_shr:1 row_mask:0xf bank_mask:0xf
	v_fmac_f32_dpp v167, v91, v151 row_shr:1 row_mask:0xf bank_mask:0xf
	v_fmac_f32_dpp v164, v96, v136 row_shr:1 row_mask:0xf bank_mask:0xf
	v_fmac_f32_dpp v168, v92, v152 row_shr:1 row_mask:0xf bank_mask:0xf
	v_fmac_f32_dpp v165, v97, v137 row_shr:1 row_mask:0xf bank_mask:0xf
	v_fmac_f32_dpp v169, v93, v153 row_shr:1 row_mask:0xf bank_mask:0xf
	v_fmac_f32_dpp v162, v94, v130 row_shr:2 row_mask:0xf bank_mask:0xf
	v_fmac_f32_dpp v166, v90, v146 row_shr:2 row_mask:0xf bank_mask:0xf
	v_fmac_f32_dpp v163, v95, v131 row_shr:2 row_mask:0xf bank_mask:0xf
	v_fmac_f32_dpp v167, v91, v147 row_shr:2 row_mask:0xf bank_mask:0xf
	v_fmac_f32_dpp v164, v96, v132 row_shr:2 row_mask:0xf bank_mask:0xf
	v_fmac_f32_dpp v168, v92, v148 row_shr:2 row_mask:0xf bank_mask:0xf
	v_fmac_f32_dpp v165, v97, v133 row_shr:2 row_mask:0xf bank_mask:0xf
	v_fmac_f32_dpp v169, v93, v149 row_shr:2 row_mask:0xf bank_mask:0xf
	v_mul_f32_e32 v170, 0xbfb8aa3b, v166
	v_mul_f32_e32 v171, 0xbfb8aa3b, v167
	v_mul_f32_e32 v172, 0xbfb8aa3b, v168
	v_mul_f32_e32 v173, 0xbfb8aa3b, v169
	v_exp_f32_e32 v170, v170
	v_exp_f32_e32 v171, v171
	v_exp_f32_e32 v172, v172
	v_exp_f32_e32 v173, v173
	v_add_f32_e32 v170, 1.0, v170
	v_add_f32_e32 v171, 1.0, v171
	v_add_f32_e32 v172, 1.0, v172
	v_add_f32_e32 v173, 1.0, v173
	v_rcp_f32_e32 v170, v170
	v_rcp_f32_e32 v171, v171
	v_rcp_f32_e32 v172, v172
	v_rcp_f32_e32 v173, v173
	v_mul_f32_e32 v170, v166, v170
	v_mul_f32_e32 v171, v167, v171
	v_mul_f32_e32 v172, v168, v172
	v_mul_f32_e32 v173, v169, v173
	v_mul_f32_e32 v170, v162, v170
	v_mul_f32_e32 v171, v163, v171
	v_mul_f32_e32 v172, v164, v172
	v_mul_f32_e32 v173, v165, v173
	v_cvt_pk_bf16_f32 v174, v170, v171
	v_cvt_pk_bf16_f32 v175, v172, v173
	v_add_u32_e32 v176, 0xb0000, v231
	s_mov_b32 exec_lo, 0xfffcfffc
	s_mov_b32 exec_hi, 0xfffcfffc
	global_store_dwordx2 v176, v[174:175], s[36:37]
	s_mov_b64 exec, -1
	v_pk_fma_f32 v[204:205], v[138:139], v[86:87], v[142:143]
	v_pk_fma_f32 v[206:207], v[140:141], v[88:89], v[144:145]
	v_pk_fma_f32 v[208:209], v[154:155], v[82:83], v[158:159]
	v_pk_fma_f32 v[210:211], v[156:157], v[84:85], v[160:161]
	v_fmac_f32_dpp v204, v86, v134 row_shr:1 row_mask:0xf bank_mask:0xf
	v_fmac_f32_dpp v208, v82, v150 row_shr:1 row_mask:0xf bank_mask:0xf
	v_fmac_f32_dpp v205, v87, v135 row_shr:1 row_mask:0xf bank_mask:0xf
	v_fmac_f32_dpp v209, v83, v151 row_shr:1 row_mask:0xf bank_mask:0xf
	v_fmac_f32_dpp v206, v88, v136 row_shr:1 row_mask:0xf bank_mask:0xf
	v_fmac_f32_dpp v210, v84, v152 row_shr:1 row_mask:0xf bank_mask:0xf
	v_fmac_f32_dpp v207, v89, v137 row_shr:1 row_mask:0xf bank_mask:0xf
	v_fmac_f32_dpp v211, v85, v153 row_shr:1 row_mask:0xf bank_mask:0xf
	v_fmac_f32_dpp v204, v86, v130 row_shr:2 row_mask:0xf bank_mask:0xf
	v_fmac_f32_dpp v208, v82, v146 row_shr:2 row_mask:0xf bank_mask:0xf
	v_fmac_f32_dpp v205, v87, v131 row_shr:2 row_mask:0xf bank_mask:0xf
	v_fmac_f32_dpp v209, v83, v147 row_shr:2 row_mask:0xf bank_mask:0xf
	v_fmac_f32_dpp v206, v88, v132 row_shr:2 row_mask:0xf bank_mask:0xf
	v_fmac_f32_dpp v210, v84, v148 row_shr:2 row_mask:0xf bank_mask:0xf
	v_fmac_f32_dpp v207, v89, v133 row_shr:2 row_mask:0xf bank_mask:0xf
	v_fmac_f32_dpp v211, v85, v149 row_shr:2 row_mask:0xf bank_mask:0xf
	v_fmac_f32_dpp v204, v94, v134 row_shl:15 row_mask:0xf bank_mask:0xf
	v_fmac_f32_dpp v208, v90, v150 row_shl:15 row_mask:0xf bank_mask:0xf
	v_fmac_f32_dpp v205, v95, v135 row_shl:15 row_mask:0xf bank_mask:0xf
	v_fmac_f32_dpp v209, v91, v151 row_shl:15 row_mask:0xf bank_mask:0xf
	v_fmac_f32_dpp v206, v96, v136 row_shl:15 row_mask:0xf bank_mask:0xf
	v_fmac_f32_dpp v210, v92, v152 row_shl:15 row_mask:0xf bank_mask:0xf
	v_fmac_f32_dpp v207, v97, v137 row_shl:15 row_mask:0xf bank_mask:0xf
	v_fmac_f32_dpp v211, v93, v153 row_shl:15 row_mask:0xf bank_mask:0xf
	v_fmac_f32_dpp v204, v94, v130 row_shl:14 row_mask:0xf bank_mask:0xf
	v_fmac_f32_dpp v208, v90, v146 row_shl:14 row_mask:0xf bank_mask:0xf
	v_fmac_f32_dpp v205, v95, v131 row_shl:14 row_mask:0xf bank_mask:0xf
	v_fmac_f32_dpp v209, v91, v147 row_shl:14 row_mask:0xf bank_mask:0xf
	v_fmac_f32_dpp v206, v96, v132 row_shl:14 row_mask:0xf bank_mask:0xf
	v_fmac_f32_dpp v210, v92, v148 row_shl:14 row_mask:0xf bank_mask:0xf
	v_fmac_f32_dpp v207, v97, v133 row_shl:14 row_mask:0xf bank_mask:0xf
	v_fmac_f32_dpp v211, v93, v149 row_shl:14 row_mask:0xf bank_mask:0xf
	v_mul_f32_e32 v212, 0xbfb8aa3b, v208
	v_mul_f32_e32 v213, 0xbfb8aa3b, v209
	v_mul_f32_e32 v214, 0xbfb8aa3b, v210
	v_mul_f32_e32 v215, 0xbfb8aa3b, v211
	v_exp_f32_e32 v212, v212
	v_exp_f32_e32 v213, v213
	v_exp_f32_e32 v214, v214
	v_exp_f32_e32 v215, v215
	v_add_f32_e32 v212, 1.0, v212
	v_add_f32_e32 v213, 1.0, v213
	v_add_f32_e32 v214, 1.0, v214
	v_add_f32_e32 v215, 1.0, v215
	v_rcp_f32_e32 v212, v212
	v_rcp_f32_e32 v213, v213
	v_rcp_f32_e32 v214, v214
	v_rcp_f32_e32 v215, v215
	v_mul_f32_e32 v212, v208, v212
	v_mul_f32_e32 v213, v209, v213
	v_mul_f32_e32 v214, v210, v214
	v_mul_f32_e32 v215, v211, v215
	v_mul_f32_e32 v212, v204, v212
	v_mul_f32_e32 v213, v205, v213
	v_mul_f32_e32 v214, v206, v214
	v_mul_f32_e32 v215, v207, v215
	v_cvt_pk_bf16_f32 v216, v212, v213
	v_cvt_pk_bf16_f32 v217, v214, v215
	v_add_u32_e32 v218, 0xc6000, v231
	global_store_dwordx2 v218, v[216:217], s[36:37]
	v_pk_fma_f32 v[162:163], v[138:139], v[78:79], v[142:143]
	v_pk_fma_f32 v[164:165], v[140:141], v[80:81], v[144:145]
	v_pk_fma_f32 v[166:167], v[154:155], v[74:75], v[158:159]
	v_pk_fma_f32 v[168:169], v[156:157], v[76:77], v[160:161]
	v_fmac_f32_dpp v162, v78, v134 row_shr:1 row_mask:0xf bank_mask:0xf
	v_fmac_f32_dpp v166, v74, v150 row_shr:1 row_mask:0xf bank_mask:0xf
	v_fmac_f32_dpp v163, v79, v135 row_shr:1 row_mask:0xf bank_mask:0xf
	v_fmac_f32_dpp v167, v75, v151 row_shr:1 row_mask:0xf bank_mask:0xf
	v_fmac_f32_dpp v164, v80, v136 row_shr:1 row_mask:0xf bank_mask:0xf
	v_fmac_f32_dpp v168, v76, v152 row_shr:1 row_mask:0xf bank_mask:0xf
	v_fmac_f32_dpp v165, v81, v137 row_shr:1 row_mask:0xf bank_mask:0xf
	v_fmac_f32_dpp v169, v77, v153 row_shr:1 row_mask:0xf bank_mask:0xf
	v_fmac_f32_dpp v162, v78, v130 row_shr:2 row_mask:0xf bank_mask:0xf
	v_fmac_f32_dpp v166, v74, v146 row_shr:2 row_mask:0xf bank_mask:0xf
	v_fmac_f32_dpp v163, v79, v131 row_shr:2 row_mask:0xf bank_mask:0xf
	v_fmac_f32_dpp v167, v75, v147 row_shr:2 row_mask:0xf bank_mask:0xf
	v_fmac_f32_dpp v164, v80, v132 row_shr:2 row_mask:0xf bank_mask:0xf
	v_fmac_f32_dpp v168, v76, v148 row_shr:2 row_mask:0xf bank_mask:0xf
	v_fmac_f32_dpp v165, v81, v133 row_shr:2 row_mask:0xf bank_mask:0xf
	v_fmac_f32_dpp v169, v77, v149 row_shr:2 row_mask:0xf bank_mask:0xf
	v_fmac_f32_dpp v162, v86, v134 row_shl:15 row_mask:0xf bank_mask:0xf
	v_fmac_f32_dpp v166, v82, v150 row_shl:15 row_mask:0xf bank_mask:0xf
	v_fmac_f32_dpp v163, v87, v135 row_shl:15 row_mask:0xf bank_mask:0xf
	v_fmac_f32_dpp v167, v83, v151 row_shl:15 row_mask:0xf bank_mask:0xf
	v_fmac_f32_dpp v164, v88, v136 row_shl:15 row_mask:0xf bank_mask:0xf
	v_fmac_f32_dpp v168, v84, v152 row_shl:15 row_mask:0xf bank_mask:0xf
	v_fmac_f32_dpp v165, v89, v137 row_shl:15 row_mask:0xf bank_mask:0xf
	v_fmac_f32_dpp v169, v85, v153 row_shl:15 row_mask:0xf bank_mask:0xf
	v_fmac_f32_dpp v162, v86, v130 row_shl:14 row_mask:0xf bank_mask:0xf
	v_fmac_f32_dpp v166, v82, v146 row_shl:14 row_mask:0xf bank_mask:0xf
	v_fmac_f32_dpp v163, v87, v131 row_shl:14 row_mask:0xf bank_mask:0xf
	v_fmac_f32_dpp v167, v83, v147 row_shl:14 row_mask:0xf bank_mask:0xf
	v_fmac_f32_dpp v164, v88, v132 row_shl:14 row_mask:0xf bank_mask:0xf
	v_fmac_f32_dpp v168, v84, v148 row_shl:14 row_mask:0xf bank_mask:0xf
	v_fmac_f32_dpp v165, v89, v133 row_shl:14 row_mask:0xf bank_mask:0xf
	v_fmac_f32_dpp v169, v85, v149 row_shl:14 row_mask:0xf bank_mask:0xf
	v_mul_f32_e32 v170, 0xbfb8aa3b, v166
	v_mul_f32_e32 v171, 0xbfb8aa3b, v167
	v_mul_f32_e32 v172, 0xbfb8aa3b, v168
	v_mul_f32_e32 v173, 0xbfb8aa3b, v169
	v_exp_f32_e32 v170, v170
	v_exp_f32_e32 v171, v171
	v_exp_f32_e32 v172, v172
	v_exp_f32_e32 v173, v173
	v_add_f32_e32 v170, 1.0, v170
	v_add_f32_e32 v171, 1.0, v171
	v_add_f32_e32 v172, 1.0, v172
	v_add_f32_e32 v173, 1.0, v173
	v_rcp_f32_e32 v170, v170
	v_rcp_f32_e32 v171, v171
	v_rcp_f32_e32 v172, v172
	v_rcp_f32_e32 v173, v173
	v_mul_f32_e32 v170, v166, v170
	v_mul_f32_e32 v171, v167, v171
	v_mul_f32_e32 v172, v168, v172
	v_mul_f32_e32 v173, v169, v173
	v_mul_f32_e32 v170, v162, v170
	v_mul_f32_e32 v171, v163, v171
	v_mul_f32_e32 v172, v164, v172
	v_mul_f32_e32 v173, v165, v173
	v_cvt_pk_bf16_f32 v174, v170, v171
	v_cvt_pk_bf16_f32 v175, v172, v173
	v_add_u32_e32 v176, 0xdc000, v231
	global_store_dwordx2 v176, v[174:175], s[36:37]
	v_pk_fma_f32 v[204:205], v[138:139], v[70:71], v[142:143]
	v_pk_fma_f32 v[206:207], v[140:141], v[72:73], v[144:145]
	v_pk_fma_f32 v[208:209], v[154:155], v[66:67], v[158:159]
	v_pk_fma_f32 v[210:211], v[156:157], v[68:69], v[160:161]
	v_fmac_f32_dpp v204, v70, v134 row_shr:1 row_mask:0xf bank_mask:0xf
	v_fmac_f32_dpp v208, v66, v150 row_shr:1 row_mask:0xf bank_mask:0xf
	v_fmac_f32_dpp v205, v71, v135 row_shr:1 row_mask:0xf bank_mask:0xf
	v_fmac_f32_dpp v209, v67, v151 row_shr:1 row_mask:0xf bank_mask:0xf
	v_fmac_f32_dpp v206, v72, v136 row_shr:1 row_mask:0xf bank_mask:0xf
	v_fmac_f32_dpp v210, v68, v152 row_shr:1 row_mask:0xf bank_mask:0xf
	v_fmac_f32_dpp v207, v73, v137 row_shr:1 row_mask:0xf bank_mask:0xf
	v_fmac_f32_dpp v211, v69, v153 row_shr:1 row_mask:0xf bank_mask:0xf
	v_fmac_f32_dpp v204, v70, v130 row_shr:2 row_mask:0xf bank_mask:0xf
	v_fmac_f32_dpp v208, v66, v146 row_shr:2 row_mask:0xf bank_mask:0xf
	v_fmac_f32_dpp v205, v71, v131 row_shr:2 row_mask:0xf bank_mask:0xf
	v_fmac_f32_dpp v209, v67, v147 row_shr:2 row_mask:0xf bank_mask:0xf
	v_fmac_f32_dpp v206, v72, v132 row_shr:2 row_mask:0xf bank_mask:0xf
	v_fmac_f32_dpp v210, v68, v148 row_shr:2 row_mask:0xf bank_mask:0xf
	v_fmac_f32_dpp v207, v73, v133 row_shr:2 row_mask:0xf bank_mask:0xf
	v_fmac_f32_dpp v211, v69, v149 row_shr:2 row_mask:0xf bank_mask:0xf
	v_fmac_f32_dpp v204, v78, v134 row_shl:15 row_mask:0xf bank_mask:0xf
	v_fmac_f32_dpp v208, v74, v150 row_shl:15 row_mask:0xf bank_mask:0xf
	v_fmac_f32_dpp v205, v79, v135 row_shl:15 row_mask:0xf bank_mask:0xf
	v_fmac_f32_dpp v209, v75, v151 row_shl:15 row_mask:0xf bank_mask:0xf
	v_fmac_f32_dpp v206, v80, v136 row_shl:15 row_mask:0xf bank_mask:0xf
	v_fmac_f32_dpp v210, v76, v152 row_shl:15 row_mask:0xf bank_mask:0xf
	v_fmac_f32_dpp v207, v81, v137 row_shl:15 row_mask:0xf bank_mask:0xf
	v_fmac_f32_dpp v211, v77, v153 row_shl:15 row_mask:0xf bank_mask:0xf
	v_fmac_f32_dpp v204, v78, v130 row_shl:14 row_mask:0xf bank_mask:0xf
	v_fmac_f32_dpp v208, v74, v146 row_shl:14 row_mask:0xf bank_mask:0xf
	v_fmac_f32_dpp v205, v79, v131 row_shl:14 row_mask:0xf bank_mask:0xf
	v_fmac_f32_dpp v209, v75, v147 row_shl:14 row_mask:0xf bank_mask:0xf
	v_fmac_f32_dpp v206, v80, v132 row_shl:14 row_mask:0xf bank_mask:0xf
	v_fmac_f32_dpp v210, v76, v148 row_shl:14 row_mask:0xf bank_mask:0xf
	v_fmac_f32_dpp v207, v81, v133 row_shl:14 row_mask:0xf bank_mask:0xf
	v_fmac_f32_dpp v211, v77, v149 row_shl:14 row_mask:0xf bank_mask:0xf
	v_mul_f32_e32 v212, 0xbfb8aa3b, v208
	v_mul_f32_e32 v213, 0xbfb8aa3b, v209
	v_mul_f32_e32 v214, 0xbfb8aa3b, v210
	v_mul_f32_e32 v215, 0xbfb8aa3b, v211
	v_exp_f32_e32 v212, v212
	v_exp_f32_e32 v213, v213
	v_exp_f32_e32 v214, v214
	v_exp_f32_e32 v215, v215
	v_add_f32_e32 v212, 1.0, v212
	v_add_f32_e32 v213, 1.0, v213
	v_add_f32_e32 v214, 1.0, v214
	v_add_f32_e32 v215, 1.0, v215
	v_rcp_f32_e32 v212, v212
	v_rcp_f32_e32 v213, v213
	v_rcp_f32_e32 v214, v214
	v_rcp_f32_e32 v215, v215
	v_mul_f32_e32 v212, v208, v212
	v_mul_f32_e32 v213, v209, v213
	v_mul_f32_e32 v214, v210, v214
	v_mul_f32_e32 v215, v211, v215
	v_mul_f32_e32 v212, v204, v212
	v_mul_f32_e32 v213, v205, v213
	v_mul_f32_e32 v214, v206, v214
	v_mul_f32_e32 v215, v207, v215
	v_cvt_pk_bf16_f32 v216, v212, v213
	v_cvt_pk_bf16_f32 v217, v214, v215
	v_add_u32_e32 v218, 0xf2000, v231
	global_store_dwordx2 v218, v[216:217], s[36:37]
	s_waitcnt vmcnt(4)
	v_pk_fma_f32 v[162:163], v[106:107], v[62:63], v[110:111]
	v_pk_fma_f32 v[164:165], v[108:109], v[64:65], v[112:113]
	v_pk_fma_f32 v[166:167], v[122:123], v[58:59], v[126:127]
	v_pk_fma_f32 v[168:169], v[124:125], v[60:61], v[128:129]
	v_fmac_f32_dpp v162, v62, v102 row_shr:1 row_mask:0xf bank_mask:0xf
	v_fmac_f32_dpp v166, v58, v118 row_shr:1 row_mask:0xf bank_mask:0xf
	v_fmac_f32_dpp v163, v63, v103 row_shr:1 row_mask:0xf bank_mask:0xf
	v_fmac_f32_dpp v167, v59, v119 row_shr:1 row_mask:0xf bank_mask:0xf
	v_fmac_f32_dpp v164, v64, v104 row_shr:1 row_mask:0xf bank_mask:0xf
	v_fmac_f32_dpp v168, v60, v120 row_shr:1 row_mask:0xf bank_mask:0xf
	v_fmac_f32_dpp v165, v65, v105 row_shr:1 row_mask:0xf bank_mask:0xf
	v_fmac_f32_dpp v169, v61, v121 row_shr:1 row_mask:0xf bank_mask:0xf
	v_fmac_f32_dpp v162, v62, v98 row_shr:2 row_mask:0xf bank_mask:0xf
	v_fmac_f32_dpp v166, v58, v114 row_shr:2 row_mask:0xf bank_mask:0xf
	v_fmac_f32_dpp v163, v63, v99 row_shr:2 row_mask:0xf bank_mask:0xf
	v_fmac_f32_dpp v167, v59, v115 row_shr:2 row_mask:0xf bank_mask:0xf
	v_fmac_f32_dpp v164, v64, v100 row_shr:2 row_mask:0xf bank_mask:0xf
	v_fmac_f32_dpp v168, v60, v116 row_shr:2 row_mask:0xf bank_mask:0xf
	v_fmac_f32_dpp v165, v65, v101 row_shr:2 row_mask:0xf bank_mask:0xf
	v_fmac_f32_dpp v169, v61, v117 row_shr:2 row_mask:0xf bank_mask:0xf
	v_mul_f32_e32 v170, 0xbfb8aa3b, v166
	v_mul_f32_e32 v171, 0xbfb8aa3b, v167
	v_mul_f32_e32 v172, 0xbfb8aa3b, v168
	v_mul_f32_e32 v173, 0xbfb8aa3b, v169
	v_exp_f32_e32 v170, v170
	v_exp_f32_e32 v171, v171
	v_exp_f32_e32 v172, v172
	v_exp_f32_e32 v173, v173
	v_add_f32_e32 v170, 1.0, v170
	v_add_f32_e32 v171, 1.0, v171
	v_add_f32_e32 v172, 1.0, v172
	v_add_f32_e32 v173, 1.0, v173
	v_rcp_f32_e32 v170, v170
	v_rcp_f32_e32 v171, v171
	v_rcp_f32_e32 v172, v172
	v_rcp_f32_e32 v173, v173
	v_mul_f32_e32 v170, v166, v170
	v_mul_f32_e32 v171, v167, v171
	v_mul_f32_e32 v172, v168, v172
	v_mul_f32_e32 v173, v169, v173
	v_mul_f32_e32 v170, v162, v170
	v_mul_f32_e32 v171, v163, v171
	v_mul_f32_e32 v172, v164, v172
	v_mul_f32_e32 v173, v165, v173
	v_cvt_pk_bf16_f32 v174, v170, v171
	v_cvt_pk_bf16_f32 v175, v172, v173
	v_add_u32_e32 v176, 0x8, v231
	s_mov_b32 exec_lo, 0xfffcfffc
	s_mov_b32 exec_hi, 0xfffcfffc
	global_store_dwordx2 v176, v[174:175], s[36:37]
	s_mov_b64 exec, -1
	v_pk_fma_f32 v[204:205], v[106:107], v[54:55], v[110:111]
	v_pk_fma_f32 v[206:207], v[108:109], v[56:57], v[112:113]
	v_pk_fma_f32 v[208:209], v[122:123], v[50:51], v[126:127]
	v_pk_fma_f32 v[210:211], v[124:125], v[52:53], v[128:129]
	v_fmac_f32_dpp v204, v54, v102 row_shr:1 row_mask:0xf bank_mask:0xf
	v_fmac_f32_dpp v208, v50, v118 row_shr:1 row_mask:0xf bank_mask:0xf
	v_fmac_f32_dpp v205, v55, v103 row_shr:1 row_mask:0xf bank_mask:0xf
	v_fmac_f32_dpp v209, v51, v119 row_shr:1 row_mask:0xf bank_mask:0xf
	v_fmac_f32_dpp v206, v56, v104 row_shr:1 row_mask:0xf bank_mask:0xf
	v_fmac_f32_dpp v210, v52, v120 row_shr:1 row_mask:0xf bank_mask:0xf
	v_fmac_f32_dpp v207, v57, v105 row_shr:1 row_mask:0xf bank_mask:0xf
	v_fmac_f32_dpp v211, v53, v121 row_shr:1 row_mask:0xf bank_mask:0xf
	v_fmac_f32_dpp v204, v54, v98 row_shr:2 row_mask:0xf bank_mask:0xf
	v_fmac_f32_dpp v208, v50, v114 row_shr:2 row_mask:0xf bank_mask:0xf
	v_fmac_f32_dpp v205, v55, v99 row_shr:2 row_mask:0xf bank_mask:0xf
	v_fmac_f32_dpp v209, v51, v115 row_shr:2 row_mask:0xf bank_mask:0xf
	v_fmac_f32_dpp v206, v56, v100 row_shr:2 row_mask:0xf bank_mask:0xf
	v_fmac_f32_dpp v210, v52, v116 row_shr:2 row_mask:0xf bank_mask:0xf
	v_fmac_f32_dpp v207, v57, v101 row_shr:2 row_mask:0xf bank_mask:0xf
	v_fmac_f32_dpp v211, v53, v117 row_shr:2 row_mask:0xf bank_mask:0xf
	v_fmac_f32_dpp v204, v62, v102 row_shl:15 row_mask:0xf bank_mask:0xf
	v_fmac_f32_dpp v208, v58, v118 row_shl:15 row_mask:0xf bank_mask:0xf
	v_fmac_f32_dpp v205, v63, v103 row_shl:15 row_mask:0xf bank_mask:0xf
	v_fmac_f32_dpp v209, v59, v119 row_shl:15 row_mask:0xf bank_mask:0xf
	v_fmac_f32_dpp v206, v64, v104 row_shl:15 row_mask:0xf bank_mask:0xf
	v_fmac_f32_dpp v210, v60, v120 row_shl:15 row_mask:0xf bank_mask:0xf
	v_fmac_f32_dpp v207, v65, v105 row_shl:15 row_mask:0xf bank_mask:0xf
	v_fmac_f32_dpp v211, v61, v121 row_shl:15 row_mask:0xf bank_mask:0xf
	v_fmac_f32_dpp v204, v62, v98 row_shl:14 row_mask:0xf bank_mask:0xf
	v_fmac_f32_dpp v208, v58, v114 row_shl:14 row_mask:0xf bank_mask:0xf
	v_fmac_f32_dpp v205, v63, v99 row_shl:14 row_mask:0xf bank_mask:0xf
	v_fmac_f32_dpp v209, v59, v115 row_shl:14 row_mask:0xf bank_mask:0xf
	v_fmac_f32_dpp v206, v64, v100 row_shl:14 row_mask:0xf bank_mask:0xf
	v_fmac_f32_dpp v210, v60, v116 row_shl:14 row_mask:0xf bank_mask:0xf
	v_fmac_f32_dpp v207, v65, v101 row_shl:14 row_mask:0xf bank_mask:0xf
	v_fmac_f32_dpp v211, v61, v117 row_shl:14 row_mask:0xf bank_mask:0xf
	v_mul_f32_e32 v212, 0xbfb8aa3b, v208
	v_mul_f32_e32 v213, 0xbfb8aa3b, v209
	v_mul_f32_e32 v214, 0xbfb8aa3b, v210
	v_mul_f32_e32 v215, 0xbfb8aa3b, v211
	v_exp_f32_e32 v212, v212
	v_exp_f32_e32 v213, v213
	v_exp_f32_e32 v214, v214
	v_exp_f32_e32 v215, v215
	v_add_f32_e32 v212, 1.0, v212
	v_add_f32_e32 v213, 1.0, v213
	v_add_f32_e32 v214, 1.0, v214
	v_add_f32_e32 v215, 1.0, v215
	v_rcp_f32_e32 v212, v212
	v_rcp_f32_e32 v213, v213
	v_rcp_f32_e32 v214, v214
	v_rcp_f32_e32 v215, v215
	v_mul_f32_e32 v212, v208, v212
	v_mul_f32_e32 v213, v209, v213
	v_mul_f32_e32 v214, v210, v214
	v_mul_f32_e32 v215, v211, v215
	v_mul_f32_e32 v212, v204, v212
	v_mul_f32_e32 v213, v205, v213
	v_mul_f32_e32 v214, v206, v214
	v_mul_f32_e32 v215, v207, v215
	v_cvt_pk_bf16_f32 v216, v212, v213
	v_cvt_pk_bf16_f32 v217, v214, v215
	v_add_u32_e32 v218, 0x16008, v231
	global_store_dwordx2 v218, v[216:217], s[36:37]
	v_pk_fma_f32 v[162:163], v[106:107], v[46:47], v[110:111]
	v_pk_fma_f32 v[164:165], v[108:109], v[48:49], v[112:113]
	v_pk_fma_f32 v[166:167], v[122:123], v[42:43], v[126:127]
	v_pk_fma_f32 v[168:169], v[124:125], v[44:45], v[128:129]
	v_fmac_f32_dpp v162, v46, v102 row_shr:1 row_mask:0xf bank_mask:0xf
	v_fmac_f32_dpp v166, v42, v118 row_shr:1 row_mask:0xf bank_mask:0xf
	v_fmac_f32_dpp v163, v47, v103 row_shr:1 row_mask:0xf bank_mask:0xf
	v_fmac_f32_dpp v167, v43, v119 row_shr:1 row_mask:0xf bank_mask:0xf
	v_fmac_f32_dpp v164, v48, v104 row_shr:1 row_mask:0xf bank_mask:0xf
	v_fmac_f32_dpp v168, v44, v120 row_shr:1 row_mask:0xf bank_mask:0xf
	v_fmac_f32_dpp v165, v49, v105 row_shr:1 row_mask:0xf bank_mask:0xf
	v_fmac_f32_dpp v169, v45, v121 row_shr:1 row_mask:0xf bank_mask:0xf
	v_fmac_f32_dpp v162, v46, v98 row_shr:2 row_mask:0xf bank_mask:0xf
	v_fmac_f32_dpp v166, v42, v114 row_shr:2 row_mask:0xf bank_mask:0xf
	v_fmac_f32_dpp v163, v47, v99 row_shr:2 row_mask:0xf bank_mask:0xf
	v_fmac_f32_dpp v167, v43, v115 row_shr:2 row_mask:0xf bank_mask:0xf
	v_fmac_f32_dpp v164, v48, v100 row_shr:2 row_mask:0xf bank_mask:0xf
	v_fmac_f32_dpp v168, v44, v116 row_shr:2 row_mask:0xf bank_mask:0xf
	v_fmac_f32_dpp v165, v49, v101 row_shr:2 row_mask:0xf bank_mask:0xf
	v_fmac_f32_dpp v169, v45, v117 row_shr:2 row_mask:0xf bank_mask:0xf
	v_fmac_f32_dpp v162, v54, v102 row_shl:15 row_mask:0xf bank_mask:0xf
	v_fmac_f32_dpp v166, v50, v118 row_shl:15 row_mask:0xf bank_mask:0xf
	v_fmac_f32_dpp v163, v55, v103 row_shl:15 row_mask:0xf bank_mask:0xf
	v_fmac_f32_dpp v167, v51, v119 row_shl:15 row_mask:0xf bank_mask:0xf
	v_fmac_f32_dpp v164, v56, v104 row_shl:15 row_mask:0xf bank_mask:0xf
	v_fmac_f32_dpp v168, v52, v120 row_shl:15 row_mask:0xf bank_mask:0xf
	v_fmac_f32_dpp v165, v57, v105 row_shl:15 row_mask:0xf bank_mask:0xf
	v_fmac_f32_dpp v169, v53, v121 row_shl:15 row_mask:0xf bank_mask:0xf
	v_fmac_f32_dpp v162, v54, v98 row_shl:14 row_mask:0xf bank_mask:0xf
	v_fmac_f32_dpp v166, v50, v114 row_shl:14 row_mask:0xf bank_mask:0xf
	v_fmac_f32_dpp v163, v55, v99 row_shl:14 row_mask:0xf bank_mask:0xf
	v_fmac_f32_dpp v167, v51, v115 row_shl:14 row_mask:0xf bank_mask:0xf
	v_fmac_f32_dpp v164, v56, v100 row_shl:14 row_mask:0xf bank_mask:0xf
	v_fmac_f32_dpp v168, v52, v116 row_shl:14 row_mask:0xf bank_mask:0xf
	v_fmac_f32_dpp v165, v57, v101 row_shl:14 row_mask:0xf bank_mask:0xf
	v_fmac_f32_dpp v169, v53, v117 row_shl:14 row_mask:0xf bank_mask:0xf
	v_mul_f32_e32 v170, 0xbfb8aa3b, v166
	v_mul_f32_e32 v171, 0xbfb8aa3b, v167
	v_mul_f32_e32 v172, 0xbfb8aa3b, v168
	v_mul_f32_e32 v173, 0xbfb8aa3b, v169
	v_exp_f32_e32 v170, v170
	v_exp_f32_e32 v171, v171
	v_exp_f32_e32 v172, v172
	v_exp_f32_e32 v173, v173
	v_add_f32_e32 v170, 1.0, v170
	v_add_f32_e32 v171, 1.0, v171
	v_add_f32_e32 v172, 1.0, v172
	v_add_f32_e32 v173, 1.0, v173
	v_rcp_f32_e32 v170, v170
	v_rcp_f32_e32 v171, v171
	v_rcp_f32_e32 v172, v172
	v_rcp_f32_e32 v173, v173
	v_mul_f32_e32 v170, v166, v170
	v_mul_f32_e32 v171, v167, v171
	v_mul_f32_e32 v172, v168, v172
	v_mul_f32_e32 v173, v169, v173
	v_mul_f32_e32 v170, v162, v170
	v_mul_f32_e32 v171, v163, v171
	v_mul_f32_e32 v172, v164, v172
	v_mul_f32_e32 v173, v165, v173
	v_cvt_pk_bf16_f32 v174, v170, v171
	v_cvt_pk_bf16_f32 v175, v172, v173
	v_add_u32_e32 v176, 0x2c008, v231
	global_store_dwordx2 v176, v[174:175], s[36:37]
	v_pk_fma_f32 v[204:205], v[106:107], v[38:39], v[110:111]
	v_pk_fma_f32 v[206:207], v[108:109], v[40:41], v[112:113]
	v_pk_fma_f32 v[208:209], v[122:123], v[34:35], v[126:127]
	v_pk_fma_f32 v[210:211], v[124:125], v[36:37], v[128:129]
	v_fmac_f32_dpp v204, v38, v102 row_shr:1 row_mask:0xf bank_mask:0xf
	v_fmac_f32_dpp v208, v34, v118 row_shr:1 row_mask:0xf bank_mask:0xf
	v_fmac_f32_dpp v205, v39, v103 row_shr:1 row_mask:0xf bank_mask:0xf
	v_fmac_f32_dpp v209, v35, v119 row_shr:1 row_mask:0xf bank_mask:0xf
	v_fmac_f32_dpp v206, v40, v104 row_shr:1 row_mask:0xf bank_mask:0xf
	v_fmac_f32_dpp v210, v36, v120 row_shr:1 row_mask:0xf bank_mask:0xf
	v_fmac_f32_dpp v207, v41, v105 row_shr:1 row_mask:0xf bank_mask:0xf
	v_fmac_f32_dpp v211, v37, v121 row_shr:1 row_mask:0xf bank_mask:0xf
	v_fmac_f32_dpp v204, v38, v98 row_shr:2 row_mask:0xf bank_mask:0xf
	v_fmac_f32_dpp v208, v34, v114 row_shr:2 row_mask:0xf bank_mask:0xf
	v_fmac_f32_dpp v205, v39, v99 row_shr:2 row_mask:0xf bank_mask:0xf
	v_fmac_f32_dpp v209, v35, v115 row_shr:2 row_mask:0xf bank_mask:0xf
	v_fmac_f32_dpp v206, v40, v100 row_shr:2 row_mask:0xf bank_mask:0xf
	v_fmac_f32_dpp v210, v36, v116 row_shr:2 row_mask:0xf bank_mask:0xf
	v_fmac_f32_dpp v207, v41, v101 row_shr:2 row_mask:0xf bank_mask:0xf
	v_fmac_f32_dpp v211, v37, v117 row_shr:2 row_mask:0xf bank_mask:0xf
	v_fmac_f32_dpp v204, v46, v102 row_shl:15 row_mask:0xf bank_mask:0xf
	v_fmac_f32_dpp v208, v42, v118 row_shl:15 row_mask:0xf bank_mask:0xf
	v_fmac_f32_dpp v205, v47, v103 row_shl:15 row_mask:0xf bank_mask:0xf
	v_fmac_f32_dpp v209, v43, v119 row_shl:15 row_mask:0xf bank_mask:0xf
	v_fmac_f32_dpp v206, v48, v104 row_shl:15 row_mask:0xf bank_mask:0xf
	v_fmac_f32_dpp v210, v44, v120 row_shl:15 row_mask:0xf bank_mask:0xf
	v_fmac_f32_dpp v207, v49, v105 row_shl:15 row_mask:0xf bank_mask:0xf
	v_fmac_f32_dpp v211, v45, v121 row_shl:15 row_mask:0xf bank_mask:0xf
	v_fmac_f32_dpp v204, v46, v98 row_shl:14 row_mask:0xf bank_mask:0xf
	v_fmac_f32_dpp v208, v42, v114 row_shl:14 row_mask:0xf bank_mask:0xf
	v_fmac_f32_dpp v205, v47, v99 row_shl:14 row_mask:0xf bank_mask:0xf
	v_fmac_f32_dpp v209, v43, v115 row_shl:14 row_mask:0xf bank_mask:0xf
	v_fmac_f32_dpp v206, v48, v100 row_shl:14 row_mask:0xf bank_mask:0xf
	v_fmac_f32_dpp v210, v44, v116 row_shl:14 row_mask:0xf bank_mask:0xf
	v_fmac_f32_dpp v207, v49, v101 row_shl:14 row_mask:0xf bank_mask:0xf
	v_fmac_f32_dpp v211, v45, v117 row_shl:14 row_mask:0xf bank_mask:0xf
	v_mul_f32_e32 v212, 0xbfb8aa3b, v208
	v_mul_f32_e32 v213, 0xbfb8aa3b, v209
	v_mul_f32_e32 v214, 0xbfb8aa3b, v210
	v_mul_f32_e32 v215, 0xbfb8aa3b, v211
	v_exp_f32_e32 v212, v212
	v_exp_f32_e32 v213, v213
	v_exp_f32_e32 v214, v214
	v_exp_f32_e32 v215, v215
	v_add_f32_e32 v212, 1.0, v212
	v_add_f32_e32 v213, 1.0, v213
	v_add_f32_e32 v214, 1.0, v214
	v_add_f32_e32 v215, 1.0, v215
	v_rcp_f32_e32 v212, v212
	v_rcp_f32_e32 v213, v213
	v_rcp_f32_e32 v214, v214
	v_rcp_f32_e32 v215, v215
	v_mul_f32_e32 v212, v208, v212
	v_mul_f32_e32 v213, v209, v213
	v_mul_f32_e32 v214, v210, v214
	v_mul_f32_e32 v215, v211, v215
	v_mul_f32_e32 v212, v204, v212
	v_mul_f32_e32 v213, v205, v213
	v_mul_f32_e32 v214, v206, v214
	v_mul_f32_e32 v215, v207, v215
	v_cvt_pk_bf16_f32 v216, v212, v213
	v_cvt_pk_bf16_f32 v217, v214, v215
	v_add_u32_e32 v218, 0x42008, v231
	global_store_dwordx2 v218, v[216:217], s[36:37]
	v_pk_fma_f32 v[162:163], v[106:107], v[30:31], v[110:111]
	v_pk_fma_f32 v[164:165], v[108:109], v[32:33], v[112:113]
	v_pk_fma_f32 v[166:167], v[122:123], v[26:27], v[126:127]
	v_pk_fma_f32 v[168:169], v[124:125], v[28:29], v[128:129]
	v_fmac_f32_dpp v162, v30, v102 row_shr:1 row_mask:0xf bank_mask:0xf
	v_fmac_f32_dpp v166, v26, v118 row_shr:1 row_mask:0xf bank_mask:0xf
	v_fmac_f32_dpp v163, v31, v103 row_shr:1 row_mask:0xf bank_mask:0xf
	v_fmac_f32_dpp v167, v27, v119 row_shr:1 row_mask:0xf bank_mask:0xf
	v_fmac_f32_dpp v164, v32, v104 row_shr:1 row_mask:0xf bank_mask:0xf
	v_fmac_f32_dpp v168, v28, v120 row_shr:1 row_mask:0xf bank_mask:0xf
	v_fmac_f32_dpp v165, v33, v105 row_shr:1 row_mask:0xf bank_mask:0xf
	v_fmac_f32_dpp v169, v29, v121 row_shr:1 row_mask:0xf bank_mask:0xf
	v_fmac_f32_dpp v162, v30, v98 row_shr:2 row_mask:0xf bank_mask:0xf
	v_fmac_f32_dpp v166, v26, v114 row_shr:2 row_mask:0xf bank_mask:0xf
	v_fmac_f32_dpp v163, v31, v99 row_shr:2 row_mask:0xf bank_mask:0xf
	v_fmac_f32_dpp v167, v27, v115 row_shr:2 row_mask:0xf bank_mask:0xf
	v_fmac_f32_dpp v164, v32, v100 row_shr:2 row_mask:0xf bank_mask:0xf
	v_fmac_f32_dpp v168, v28, v116 row_shr:2 row_mask:0xf bank_mask:0xf
	v_fmac_f32_dpp v165, v33, v101 row_shr:2 row_mask:0xf bank_mask:0xf
	v_fmac_f32_dpp v169, v29, v117 row_shr:2 row_mask:0xf bank_mask:0xf
	v_mul_f32_e32 v170, 0xbfb8aa3b, v166
	v_mul_f32_e32 v171, 0xbfb8aa3b, v167
	v_mul_f32_e32 v172, 0xbfb8aa3b, v168
	v_mul_f32_e32 v173, 0xbfb8aa3b, v169
	v_exp_f32_e32 v170, v170
	v_exp_f32_e32 v171, v171
	v_exp_f32_e32 v172, v172
	v_exp_f32_e32 v173, v173
	v_add_f32_e32 v170, 1.0, v170
	v_add_f32_e32 v171, 1.0, v171
	v_add_f32_e32 v172, 1.0, v172
	v_add_f32_e32 v173, 1.0, v173
	v_rcp_f32_e32 v170, v170
	v_rcp_f32_e32 v171, v171
	v_rcp_f32_e32 v172, v172
	v_rcp_f32_e32 v173, v173
	v_mul_f32_e32 v170, v166, v170
	v_mul_f32_e32 v171, v167, v171
	v_mul_f32_e32 v172, v168, v172
	v_mul_f32_e32 v173, v169, v173
	v_mul_f32_e32 v170, v162, v170
	v_mul_f32_e32 v171, v163, v171
	v_mul_f32_e32 v172, v164, v172
	v_mul_f32_e32 v173, v165, v173
	v_cvt_pk_bf16_f32 v174, v170, v171
	v_cvt_pk_bf16_f32 v175, v172, v173
	v_add_u32_e32 v176, 0xb0008, v231
	s_mov_b32 exec_lo, 0xfffcfffc
	s_mov_b32 exec_hi, 0xfffcfffc
	global_store_dwordx2 v176, v[174:175], s[36:37]
	s_mov_b64 exec, -1
	v_pk_fma_f32 v[204:205], v[106:107], v[22:23], v[110:111]
	v_pk_fma_f32 v[206:207], v[108:109], v[24:25], v[112:113]
	v_pk_fma_f32 v[208:209], v[122:123], v[18:19], v[126:127]
	v_pk_fma_f32 v[210:211], v[124:125], v[20:21], v[128:129]
	v_fmac_f32_dpp v204, v22, v102 row_shr:1 row_mask:0xf bank_mask:0xf
	v_fmac_f32_dpp v208, v18, v118 row_shr:1 row_mask:0xf bank_mask:0xf
	v_fmac_f32_dpp v205, v23, v103 row_shr:1 row_mask:0xf bank_mask:0xf
	v_fmac_f32_dpp v209, v19, v119 row_shr:1 row_mask:0xf bank_mask:0xf
	v_fmac_f32_dpp v206, v24, v104 row_shr:1 row_mask:0xf bank_mask:0xf
	v_fmac_f32_dpp v210, v20, v120 row_shr:1 row_mask:0xf bank_mask:0xf
	v_fmac_f32_dpp v207, v25, v105 row_shr:1 row_mask:0xf bank_mask:0xf
	v_fmac_f32_dpp v211, v21, v121 row_shr:1 row_mask:0xf bank_mask:0xf
	v_fmac_f32_dpp v204, v22, v98 row_shr:2 row_mask:0xf bank_mask:0xf
	v_fmac_f32_dpp v208, v18, v114 row_shr:2 row_mask:0xf bank_mask:0xf
	v_fmac_f32_dpp v205, v23, v99 row_shr:2 row_mask:0xf bank_mask:0xf
	v_fmac_f32_dpp v209, v19, v115 row_shr:2 row_mask:0xf bank_mask:0xf
	v_fmac_f32_dpp v206, v24, v100 row_shr:2 row_mask:0xf bank_mask:0xf
	v_fmac_f32_dpp v210, v20, v116 row_shr:2 row_mask:0xf bank_mask:0xf
	v_fmac_f32_dpp v207, v25, v101 row_shr:2 row_mask:0xf bank_mask:0xf
	v_fmac_f32_dpp v211, v21, v117 row_shr:2 row_mask:0xf bank_mask:0xf
	v_fmac_f32_dpp v204, v30, v102 row_shl:15 row_mask:0xf bank_mask:0xf
	v_fmac_f32_dpp v208, v26, v118 row_shl:15 row_mask:0xf bank_mask:0xf
	v_fmac_f32_dpp v205, v31, v103 row_shl:15 row_mask:0xf bank_mask:0xf
	v_fmac_f32_dpp v209, v27, v119 row_shl:15 row_mask:0xf bank_mask:0xf
	v_fmac_f32_dpp v206, v32, v104 row_shl:15 row_mask:0xf bank_mask:0xf
	v_fmac_f32_dpp v210, v28, v120 row_shl:15 row_mask:0xf bank_mask:0xf
	v_fmac_f32_dpp v207, v33, v105 row_shl:15 row_mask:0xf bank_mask:0xf
	v_fmac_f32_dpp v211, v29, v121 row_shl:15 row_mask:0xf bank_mask:0xf
	v_fmac_f32_dpp v204, v30, v98 row_shl:14 row_mask:0xf bank_mask:0xf
	v_fmac_f32_dpp v208, v26, v114 row_shl:14 row_mask:0xf bank_mask:0xf
	v_fmac_f32_dpp v205, v31, v99 row_shl:14 row_mask:0xf bank_mask:0xf
	v_fmac_f32_dpp v209, v27, v115 row_shl:14 row_mask:0xf bank_mask:0xf
	v_fmac_f32_dpp v206, v32, v100 row_shl:14 row_mask:0xf bank_mask:0xf
	v_fmac_f32_dpp v210, v28, v116 row_shl:14 row_mask:0xf bank_mask:0xf
	v_fmac_f32_dpp v207, v33, v101 row_shl:14 row_mask:0xf bank_mask:0xf
	v_fmac_f32_dpp v211, v29, v117 row_shl:14 row_mask:0xf bank_mask:0xf
	v_mul_f32_e32 v212, 0xbfb8aa3b, v208
	v_mul_f32_e32 v213, 0xbfb8aa3b, v209
	v_mul_f32_e32 v214, 0xbfb8aa3b, v210
	v_mul_f32_e32 v215, 0xbfb8aa3b, v211
	v_exp_f32_e32 v212, v212
	v_exp_f32_e32 v213, v213
	v_exp_f32_e32 v214, v214
	v_exp_f32_e32 v215, v215
	v_add_f32_e32 v212, 1.0, v212
	v_add_f32_e32 v213, 1.0, v213
	v_add_f32_e32 v214, 1.0, v214
	v_add_f32_e32 v215, 1.0, v215
	v_rcp_f32_e32 v212, v212
	v_rcp_f32_e32 v213, v213
	v_rcp_f32_e32 v214, v214
	v_rcp_f32_e32 v215, v215
	v_mul_f32_e32 v212, v208, v212
	v_mul_f32_e32 v213, v209, v213
	v_mul_f32_e32 v214, v210, v214
	v_mul_f32_e32 v215, v211, v215
	v_mul_f32_e32 v212, v204, v212
	v_mul_f32_e32 v213, v205, v213
	v_mul_f32_e32 v214, v206, v214
	v_mul_f32_e32 v215, v207, v215
	v_cvt_pk_bf16_f32 v216, v212, v213
	v_cvt_pk_bf16_f32 v217, v214, v215
	v_add_u32_e32 v218, 0xc6008, v231
	global_store_dwordx2 v218, v[216:217], s[36:37]
	v_pk_fma_f32 v[162:163], v[106:107], v[14:15], v[110:111]
	v_pk_fma_f32 v[164:165], v[108:109], v[16:17], v[112:113]
	v_pk_fma_f32 v[166:167], v[122:123], v[10:11], v[126:127]
	v_pk_fma_f32 v[168:169], v[124:125], v[12:13], v[128:129]
	v_fmac_f32_dpp v162, v14, v102 row_shr:1 row_mask:0xf bank_mask:0xf
	v_fmac_f32_dpp v166, v10, v118 row_shr:1 row_mask:0xf bank_mask:0xf
	v_fmac_f32_dpp v163, v15, v103 row_shr:1 row_mask:0xf bank_mask:0xf
	v_fmac_f32_dpp v167, v11, v119 row_shr:1 row_mask:0xf bank_mask:0xf
	v_fmac_f32_dpp v164, v16, v104 row_shr:1 row_mask:0xf bank_mask:0xf
	v_fmac_f32_dpp v168, v12, v120 row_shr:1 row_mask:0xf bank_mask:0xf
	v_fmac_f32_dpp v165, v17, v105 row_shr:1 row_mask:0xf bank_mask:0xf
	v_fmac_f32_dpp v169, v13, v121 row_shr:1 row_mask:0xf bank_mask:0xf
	v_fmac_f32_dpp v162, v14, v98 row_shr:2 row_mask:0xf bank_mask:0xf
	v_fmac_f32_dpp v166, v10, v114 row_shr:2 row_mask:0xf bank_mask:0xf
	v_fmac_f32_dpp v163, v15, v99 row_shr:2 row_mask:0xf bank_mask:0xf
	v_fmac_f32_dpp v167, v11, v115 row_shr:2 row_mask:0xf bank_mask:0xf
	v_fmac_f32_dpp v164, v16, v100 row_shr:2 row_mask:0xf bank_mask:0xf
	v_fmac_f32_dpp v168, v12, v116 row_shr:2 row_mask:0xf bank_mask:0xf
	v_fmac_f32_dpp v165, v17, v101 row_shr:2 row_mask:0xf bank_mask:0xf
	v_fmac_f32_dpp v169, v13, v117 row_shr:2 row_mask:0xf bank_mask:0xf
	v_fmac_f32_dpp v162, v22, v102 row_shl:15 row_mask:0xf bank_mask:0xf
	v_fmac_f32_dpp v166, v18, v118 row_shl:15 row_mask:0xf bank_mask:0xf
	v_fmac_f32_dpp v163, v23, v103 row_shl:15 row_mask:0xf bank_mask:0xf
	v_fmac_f32_dpp v167, v19, v119 row_shl:15 row_mask:0xf bank_mask:0xf
	v_fmac_f32_dpp v164, v24, v104 row_shl:15 row_mask:0xf bank_mask:0xf
	v_fmac_f32_dpp v168, v20, v120 row_shl:15 row_mask:0xf bank_mask:0xf
	v_fmac_f32_dpp v165, v25, v105 row_shl:15 row_mask:0xf bank_mask:0xf
	v_fmac_f32_dpp v169, v21, v121 row_shl:15 row_mask:0xf bank_mask:0xf
	v_fmac_f32_dpp v162, v22, v98 row_shl:14 row_mask:0xf bank_mask:0xf
	v_fmac_f32_dpp v166, v18, v114 row_shl:14 row_mask:0xf bank_mask:0xf
	v_fmac_f32_dpp v163, v23, v99 row_shl:14 row_mask:0xf bank_mask:0xf
	v_fmac_f32_dpp v167, v19, v115 row_shl:14 row_mask:0xf bank_mask:0xf
	v_fmac_f32_dpp v164, v24, v100 row_shl:14 row_mask:0xf bank_mask:0xf
	v_fmac_f32_dpp v168, v20, v116 row_shl:14 row_mask:0xf bank_mask:0xf
	v_fmac_f32_dpp v165, v25, v101 row_shl:14 row_mask:0xf bank_mask:0xf
	v_fmac_f32_dpp v169, v21, v117 row_shl:14 row_mask:0xf bank_mask:0xf
	v_mul_f32_e32 v170, 0xbfb8aa3b, v166
	v_mul_f32_e32 v171, 0xbfb8aa3b, v167
	v_mul_f32_e32 v172, 0xbfb8aa3b, v168
	v_mul_f32_e32 v173, 0xbfb8aa3b, v169
	v_exp_f32_e32 v170, v170
	v_exp_f32_e32 v171, v171
	v_exp_f32_e32 v172, v172
	v_exp_f32_e32 v173, v173
	v_add_f32_e32 v170, 1.0, v170
	v_add_f32_e32 v171, 1.0, v171
	v_add_f32_e32 v172, 1.0, v172
	v_add_f32_e32 v173, 1.0, v173
	v_rcp_f32_e32 v170, v170
	v_rcp_f32_e32 v171, v171
	v_rcp_f32_e32 v172, v172
	v_rcp_f32_e32 v173, v173
	v_mul_f32_e32 v170, v166, v170
	v_mul_f32_e32 v171, v167, v171
	v_mul_f32_e32 v172, v168, v172
	v_mul_f32_e32 v173, v169, v173
	v_mul_f32_e32 v170, v162, v170
	v_mul_f32_e32 v171, v163, v171
	v_mul_f32_e32 v172, v164, v172
	v_mul_f32_e32 v173, v165, v173
	v_cvt_pk_bf16_f32 v174, v170, v171
	v_cvt_pk_bf16_f32 v175, v172, v173
	v_add_u32_e32 v176, 0xdc008, v231
	global_store_dwordx2 v176, v[174:175], s[36:37]
	v_pk_fma_f32 v[204:205], v[106:107], v[6:7], v[110:111]
	v_pk_fma_f32 v[206:207], v[108:109], v[8:9], v[112:113]
	v_pk_fma_f32 v[208:209], v[122:123], v[2:3], v[126:127]
	v_pk_fma_f32 v[210:211], v[124:125], v[4:5], v[128:129]
	v_fmac_f32_dpp v204, v6, v102 row_shr:1 row_mask:0xf bank_mask:0xf
	v_fmac_f32_dpp v208, v2, v118 row_shr:1 row_mask:0xf bank_mask:0xf
	v_fmac_f32_dpp v205, v7, v103 row_shr:1 row_mask:0xf bank_mask:0xf
	v_fmac_f32_dpp v209, v3, v119 row_shr:1 row_mask:0xf bank_mask:0xf
	v_fmac_f32_dpp v206, v8, v104 row_shr:1 row_mask:0xf bank_mask:0xf
	v_fmac_f32_dpp v210, v4, v120 row_shr:1 row_mask:0xf bank_mask:0xf
	v_fmac_f32_dpp v207, v9, v105 row_shr:1 row_mask:0xf bank_mask:0xf
	v_fmac_f32_dpp v211, v5, v121 row_shr:1 row_mask:0xf bank_mask:0xf
	v_fmac_f32_dpp v204, v6, v98 row_shr:2 row_mask:0xf bank_mask:0xf
	v_fmac_f32_dpp v208, v2, v114 row_shr:2 row_mask:0xf bank_mask:0xf
	v_fmac_f32_dpp v205, v7, v99 row_shr:2 row_mask:0xf bank_mask:0xf
	v_fmac_f32_dpp v209, v3, v115 row_shr:2 row_mask:0xf bank_mask:0xf
	v_fmac_f32_dpp v206, v8, v100 row_shr:2 row_mask:0xf bank_mask:0xf
	v_fmac_f32_dpp v210, v4, v116 row_shr:2 row_mask:0xf bank_mask:0xf
	v_fmac_f32_dpp v207, v9, v101 row_shr:2 row_mask:0xf bank_mask:0xf
	v_fmac_f32_dpp v211, v5, v117 row_shr:2 row_mask:0xf bank_mask:0xf
	v_fmac_f32_dpp v204, v14, v102 row_shl:15 row_mask:0xf bank_mask:0xf
	v_fmac_f32_dpp v208, v10, v118 row_shl:15 row_mask:0xf bank_mask:0xf
	v_fmac_f32_dpp v205, v15, v103 row_shl:15 row_mask:0xf bank_mask:0xf
	v_fmac_f32_dpp v209, v11, v119 row_shl:15 row_mask:0xf bank_mask:0xf
	v_fmac_f32_dpp v206, v16, v104 row_shl:15 row_mask:0xf bank_mask:0xf
	v_fmac_f32_dpp v210, v12, v120 row_shl:15 row_mask:0xf bank_mask:0xf
	v_fmac_f32_dpp v207, v17, v105 row_shl:15 row_mask:0xf bank_mask:0xf
	v_fmac_f32_dpp v211, v13, v121 row_shl:15 row_mask:0xf bank_mask:0xf
	v_fmac_f32_dpp v204, v14, v98 row_shl:14 row_mask:0xf bank_mask:0xf
	v_fmac_f32_dpp v208, v10, v114 row_shl:14 row_mask:0xf bank_mask:0xf
	v_fmac_f32_dpp v205, v15, v99 row_shl:14 row_mask:0xf bank_mask:0xf
	v_fmac_f32_dpp v209, v11, v115 row_shl:14 row_mask:0xf bank_mask:0xf
	v_fmac_f32_dpp v206, v16, v100 row_shl:14 row_mask:0xf bank_mask:0xf
	v_fmac_f32_dpp v210, v12, v116 row_shl:14 row_mask:0xf bank_mask:0xf
	v_fmac_f32_dpp v207, v17, v101 row_shl:14 row_mask:0xf bank_mask:0xf
	v_fmac_f32_dpp v211, v13, v117 row_shl:14 row_mask:0xf bank_mask:0xf
	v_mul_f32_e32 v212, 0xbfb8aa3b, v208
	v_mul_f32_e32 v213, 0xbfb8aa3b, v209
	v_mul_f32_e32 v214, 0xbfb8aa3b, v210
	v_mul_f32_e32 v215, 0xbfb8aa3b, v211
	v_exp_f32_e32 v212, v212
	v_exp_f32_e32 v213, v213
	v_exp_f32_e32 v214, v214
	v_exp_f32_e32 v215, v215
	v_add_f32_e32 v212, 1.0, v212
	v_add_f32_e32 v213, 1.0, v213
	v_add_f32_e32 v214, 1.0, v214
	v_add_f32_e32 v215, 1.0, v215
	v_rcp_f32_e32 v212, v212
	v_rcp_f32_e32 v213, v213
	v_rcp_f32_e32 v214, v214
	v_rcp_f32_e32 v215, v215
	v_mul_f32_e32 v212, v208, v212
	v_mul_f32_e32 v213, v209, v213
	v_mul_f32_e32 v214, v210, v214
	v_mul_f32_e32 v215, v211, v215
	v_mul_f32_e32 v212, v204, v212
	v_mul_f32_e32 v213, v205, v213
	v_mul_f32_e32 v214, v206, v214
	v_mul_f32_e32 v215, v207, v215
	v_cvt_pk_bf16_f32 v216, v212, v213
	v_cvt_pk_bf16_f32 v217, v214, v215
	v_add_u32_e32 v218, 0xf2008, v231
	global_store_dwordx2 v218, v[216:217], s[36:37]
	s_branch .LBB0_2026
.Lmy_ffnA_sample:
	s_load_dwordx2 s[36:37], s[78:79], 0x268
	s_load_dwordx2 s[38:39], s[78:79], 0x2a0
	s_load_dwordx4 s[40:43], s[78:79], 0x70
	s_load_dwordx2 s[44:45], s[78:79], 0x128
	s_load_dwordx2 s[16:17], s[78:79], 0x28
	v_and_b32_e32 v204, 15, v248
	v_bfe_u32 v205, v248, 8, 1
	v_bfe_u32 v206, v248, 6, 2
	v_bfe_u32 v207, v248, 4, 2
	v_lshlrev_b32_e32 v206, 5, v206
	v_lshl_or_b32 v206, v207, 3, v206
	s_lshl_b32 s13, s14, 7
	v_add_u32_e32 v206, s13, v206
	s_lshl_b32 s13, s12, 8
	v_lshl_add_u32 v207, v205, 6, v204
	v_add_u32_e32 v207, s13, v207
	v_mul_u32_u24_e32 v231, 0x1600, v207
	v_lshl_add_u32 v231, v206, 1, v231
	v_lshlrev_b32_e32 v232, 2, v206
	s_lshl_b32 s13, s12, 4
	v_lshl_add_u32 v233, v205, 2, s13
	v_add_u32_e32 v208, -12, v204
	v_cmp_gt_u32_e32 vcc, 2, v204
	s_nop 1
	v_cndmask_b32_e32 v208, v208, v204, vcc
	v_add_u32_e32 v233, v233, v208
	v_mul_u32_u24_e32 v233, 0x2c00, v233
	v_lshl_add_u32 v233, v206, 1, v233
	s_sub_u32 s13, s12, 64
	s_lshl_b32 s13, s13, 5
	s_add_u32 s13, s13, 0
	v_lshrrev_b32_e32 v208, 3, v204
	v_lshl_add_u32 v208, v205, 3, v208
	v_add_u32_e32 v208, s13, v208
	v_mul_u32_u24_e32 v234, 0xb000, v208
	v_add_u32_e32 v234, v234, v232
	v_and_b32_e32 v209, 7, v204
	v_mul_u32_u24_e32 v190, 0x5800, v209
	v_add_u32_e32 v235, 0xfffdf000, v190
	v_add_u32_e32 v235, v235, v234
	v_add_u32_e32 v190, v190, v234
	s_mov_b32 s46, 0x01010101
	s_mov_b32 s47, 0x01010101
	s_mov_b32 s48, 0x03030303
	s_mov_b32 s49, 0x03030303
	s_mov_b32 s50, 0xc0c0c0c0
	s_mov_b32 s51, 0xc0c0c0c0
	s_waitcnt lgkmcnt(0)
	global_load_dwordx4 v[130:133], v232, s[40:41]
	v_add_u32_e32 v213, 0x5800, v232
	global_load_dwordx4 v[134:137], v213, s[40:41]
	v_add_u32_e32 v214, 0xb000, v232
	global_load_dwordx4 v[138:141], v214, s[40:41]
	global_load_dwordx4 v[142:145], v232, s[42:43]
	v_add_u32_e32 v215, 0x2c00, v232
	global_load_dwordx4 v[146:149], v215, s[40:41]
	v_add_u32_e32 v216, 0x8400, v232
	global_load_dwordx4 v[150:153], v216, s[40:41]
	v_add_u32_e32 v217, 0xdc00, v232
	global_load_dwordx4 v[154:157], v217, s[40:41]
	v_add_u32_e32 v218, 0x2c00, v232
	global_load_dwordx4 v[158:161], v218, s[42:43]
	s_mov_b64 exec, s[48:49]
	global_load_dwordx4 v[162:165], v190, s[16:17]
	s_mov_b64 exec, -1
	s_mov_b64 exec, s[48:49]
	v_add_u32_e32 v222, 0x2c00, v190
	global_load_dwordx4 v[166:169], v222, s[16:17]
	s_mov_b64 exec, -1
	s_mov_b64 exec, s[48:49]
	v_add_u32_e32 v222, 0x16000, v190
	global_load_dwordx4 v[170:173], v222, s[16:17]
	s_mov_b64 exec, -1
	s_mov_b64 exec, s[48:49]
	v_add_u32_e32 v222, 0x18c00, v190
	global_load_dwordx4 v[174:177], v222, s[16:17]
	s_mov_b64 exec, -1
	s_mov_b32 exec_lo, 0x30003
	s_mov_b32 exec_hi, 0x30003
	v_cvt_pk_bf16_f32 v204, v126, v127
	v_cvt_pk_bf16_f32 v205, v128, v129
	global_store_dwordx2 v233, v[204:205], s[38:39]
	v_cvt_pk_bf16_f32 v206, v122, v123
	v_cvt_pk_bf16_f32 v207, v124, v125
	v_add_u32_e32 v220, 0x1600, v233
	global_store_dwordx2 v220, v[206:207], s[38:39]
	v_cvt_pk_bf16_f32 v208, v94, v95
	v_cvt_pk_bf16_f32 v209, v96, v97
	v_add_u32_e32 v221, 0x16000, v233
	global_store_dwordx2 v221, v[208:209], s[38:39]
	v_cvt_pk_bf16_f32 v210, v90, v91
	v_cvt_pk_bf16_f32 v211, v92, v93
	v_add_u32_e32 v222, 0x17600, v233
	global_store_dwordx2 v222, v[210:211], s[38:39]
	v_cvt_pk_bf16_f32 v212, v62, v63
	v_cvt_pk_bf16_f32 v213, v64, v65
	v_add_u32_e32 v223, 0x8, v233
	global_store_dwordx2 v223, v[212:213], s[38:39]
	v_cvt_pk_bf16_f32 v214, v58, v59
	v_cvt_pk_bf16_f32 v215, v60, v61
	v_add_u32_e32 v224, 0x1608, v233
	global_store_dwordx2 v224, v[214:215], s[38:39]
	v_cvt_pk_bf16_f32 v216, v30, v31
	v_cvt_pk_bf16_f32 v217, v32, v33
	v_add_u32_e32 v225, 0x16008, v233
	global_store_dwordx2 v225, v[216:217], s[38:39]
	v_cvt_pk_bf16_f32 v218, v26, v27
	v_cvt_pk_bf16_f32 v219, v28, v29
	v_add_u32_e32 v226, 0x17608, v233
	global_store_dwordx2 v226, v[218:219], s[38:39]
	s_mov_b32 exec_lo, 0xc000c000
	s_mov_b32 exec_hi, 0xc000c000
	v_cvt_pk_bf16_f32 v204, v102, v103
	v_cvt_pk_bf16_f32 v205, v104, v105
	global_store_dwordx2 v233, v[204:205], s[38:39]
	v_cvt_pk_bf16_f32 v206, v98, v99
	v_cvt_pk_bf16_f32 v207, v100, v101
	v_add_u32_e32 v220, 0x1600, v233
	global_store_dwordx2 v220, v[206:207], s[38:39]
	v_cvt_pk_bf16_f32 v208, v70, v71
	v_cvt_pk_bf16_f32 v209, v72, v73
	v_add_u32_e32 v221, 0x16000, v233
	global_store_dwordx2 v221, v[208:209], s[38:39]
	v_cvt_pk_bf16_f32 v210, v66, v67
	v_cvt_pk_bf16_f32 v211, v68, v69
	v_add_u32_e32 v222, 0x17600, v233
	global_store_dwordx2 v222, v[210:211], s[38:39]
	v_cvt_pk_bf16_f32 v212, v38, v39
	v_cvt_pk_bf16_f32 v213, v40, v41
	v_add_u32_e32 v223, 0x8, v233
	global_store_dwordx2 v223, v[212:213], s[38:39]
	v_cvt_pk_bf16_f32 v214, v34, v35
	v_cvt_pk_bf16_f32 v215, v36, v37
	v_add_u32_e32 v224, 0x1608, v233
	global_store_dwordx2 v224, v[214:215], s[38:39]
	v_cvt_pk_bf16_f32 v216, v6, v7
	v_cvt_pk_bf16_f32 v217, v8, v9
	v_add_u32_e32 v225, 0x16008, v233
	global_store_dwordx2 v225, v[216:217], s[38:39]
	v_cvt_pk_bf16_f32 v218, v2, v3
	v_cvt_pk_bf16_f32 v219, v4, v5
	v_add_u32_e32 v226, 0x17608, v233
	global_store_dwordx2 v226, v[218:219], s[38:39]
	s_mov_b64 exec, -1
	s_waitcnt vmcnt(20)
	s_mov_b64 exec, s[50:51]
	global_store_dwordx4 v235, v[126:129], s[44:45]
	v_add_u32_e32 v224, 0x2c00, v235
	global_store_dwordx4 v224, v[122:125], s[44:45]
	v_add_u32_e32 v225, 0x16000, v235
	global_store_dwordx4 v225, v[118:121], s[44:45]
	v_add_u32_e32 v226, 0x18c00, v235
	global_store_dwordx4 v226, v[114:117], s[44:45]
	v_add_u32_e32 v223, 0x2c000, v235
	global_store_dwordx4 v223, v[110:113], s[44:45]
	v_add_u32_e32 v224, 0x2ec00, v235
	global_store_dwordx4 v224, v[106:109], s[44:45]
	v_add_u32_e32 v225, 0x42000, v235
	global_store_dwordx4 v225, v[102:105], s[44:45]
	v_add_u32_e32 v226, 0x44c00, v235
	global_store_dwordx4 v226, v[98:101], s[44:45]
	v_add_u32_e32 v223, 0xb0000, v235
	global_store_dwordx4 v223, v[94:97], s[44:45]
	v_add_u32_e32 v224, 0xb2c00, v235
	global_store_dwordx4 v224, v[90:93], s[44:45]
	v_add_u32_e32 v225, 0xc6000, v235
	global_store_dwordx4 v225, v[86:89], s[44:45]
	v_add_u32_e32 v226, 0xc8c00, v235
	global_store_dwordx4 v226, v[82:85], s[44:45]
	v_add_u32_e32 v223, 0xdc000, v235
	global_store_dwordx4 v223, v[78:81], s[44:45]
	v_add_u32_e32 v224, 0xdec00, v235
	global_store_dwordx4 v224, v[74:77], s[44:45]
	v_add_u32_e32 v225, 0xf2000, v235
	global_store_dwordx4 v225, v[70:73], s[44:45]
	v_add_u32_e32 v226, 0xf4c00, v235
	global_store_dwordx4 v226, v[66:69], s[44:45]
	s_mov_b64 exec, -1
	v_pk_fma_f32 v[212:213], v[138:139], v[126:127], v[142:143]
	v_pk_fma_f32 v[214:215], v[140:141], v[128:129], v[144:145]
	s_nop 2
	v_mov_b32_dpp v204, v126 row_shr:1 row_mask:0xf bank_mask:0xf
	v_mov_b32_dpp v208, v126 row_shr:2 row_mask:0xf bank_mask:0xf
	v_mov_b32_dpp v205, v127 row_shr:1 row_mask:0xf bank_mask:0xf
	v_mov_b32_dpp v209, v127 row_shr:2 row_mask:0xf bank_mask:0xf
	v_mov_b32_dpp v206, v128 row_shr:1 row_mask:0xf bank_mask:0xf
	v_mov_b32_dpp v210, v128 row_shr:2 row_mask:0xf bank_mask:0xf
	v_mov_b32_dpp v207, v129 row_shr:1 row_mask:0xf bank_mask:0xf
	v_mov_b32_dpp v211, v129 row_shr:2 row_mask:0xf bank_mask:0xf
	s_waitcnt vmcnt(35)
	v_mov_b32_dpp v223, v162 row_shl:1 row_mask:0xf bank_mask:0xf
	v_mov_b32_dpp v224, v163 row_shl:1 row_mask:0xf bank_mask:0xf
	v_mov_b32_dpp v225, v164 row_shl:1 row_mask:0xf bank_mask:0xf
	v_mov_b32_dpp v226, v165 row_shl:1 row_mask:0xf bank_mask:0xf
	v_cndmask_b32_e64 v208, v208, v162, s[48:49]
	v_cndmask_b32_e64 v209, v209, v163, s[48:49]
	v_cndmask_b32_e64 v210, v210, v164, s[48:49]
	v_cndmask_b32_e64 v211, v211, v165, s[48:49]
	v_cndmask_b32_e64 v204, v204, v223, s[46:47]
	v_cndmask_b32_e64 v205, v205, v224, s[46:47]
	v_cndmask_b32_e64 v206, v206, v225, s[46:47]
	v_cndmask_b32_e64 v207, v207, v226, s[46:47]
	s_mov_b64 exec, s[48:49]
	v_add_u32_e32 v222, 0x2c000, v190
	global_load_dwordx4 v[162:165], v222, s[16:17]
	s_mov_b64 exec, -1
	v_pk_fma_f32 v[212:213], v[134:135], v[204:205], v[212:213]
	v_pk_fma_f32 v[214:215], v[136:137], v[206:207], v[214:215]
	v_pk_fma_f32 v[212:213], v[130:131], v[208:209], v[212:213]
	v_pk_fma_f32 v[214:215], v[132:133], v[210:211], v[214:215]
	v_pk_fma_f32 v[216:217], v[154:155], v[122:123], v[158:159]
	v_pk_fma_f32 v[218:219], v[156:157], v[124:125], v[160:161]
	s_nop 2
	v_mov_b32_dpp v204, v122 row_shr:1 row_mask:0xf bank_mask:0xf
	v_mov_b32_dpp v208, v122 row_shr:2 row_mask:0xf bank_mask:0xf
	v_mov_b32_dpp v205, v123 row_shr:1 row_mask:0xf bank_mask:0xf
	v_mov_b32_dpp v209, v123 row_shr:2 row_mask:0xf bank_mask:0xf
	v_mov_b32_dpp v206, v124 row_shr:1 row_mask:0xf bank_mask:0xf
	v_mov_b32_dpp v210, v124 row_shr:2 row_mask:0xf bank_mask:0xf
	v_mov_b32_dpp v207, v125 row_shr:1 row_mask:0xf bank_mask:0xf
	v_mov_b32_dpp v211, v125 row_shr:2 row_mask:0xf bank_mask:0xf
	s_waitcnt vmcnt(35)
	v_mov_b32_dpp v223, v166 row_shl:1 row_mask:0xf bank_mask:0xf
	v_mov_b32_dpp v224, v167 row_shl:1 row_mask:0xf bank_mask:0xf
	v_mov_b32_dpp v225, v168 row_shl:1 row_mask:0xf bank_mask:0xf
	v_mov_b32_dpp v226, v169 row_shl:1 row_mask:0xf bank_mask:0xf
	v_cndmask_b32_e64 v208, v208, v166, s[48:49]
	v_cndmask_b32_e64 v209, v209, v167, s[48:49]
	v_cndmask_b32_e64 v210, v210, v168, s[48:49]
	v_cndmask_b32_e64 v211, v211, v169, s[48:49]
	v_cndmask_b32_e64 v204, v204, v223, s[46:47]
	v_cndmask_b32_e64 v205, v205, v224, s[46:47]
	v_cndmask_b32_e64 v206, v206, v225, s[46:47]
	v_cndmask_b32_e64 v207, v207, v226, s[46:47]
	s_mov_b64 exec, s[48:49]
	v_add_u32_e32 v222, 0x2ec00, v190
	global_load_dwordx4 v[166:169], v222, s[16:17]
	s_mov_b64 exec, -1
	v_pk_fma_f32 v[216:217], v[150:151], v[204:205], v[216:217]
	v_pk_fma_f32 v[218:219], v[152:153], v[206:207], v[218:219]
	v_pk_fma_f32 v[216:217], v[146:147], v[208:209], v[216:217]
	v_pk_fma_f32 v[218:219], v[148:149], v[210:211], v[218:219]
	v_mul_f32_e32 v204, 0xbfb8aa3b, v216
	v_mul_f32_e32 v205, 0xbfb8aa3b, v217
	v_mul_f32_e32 v206, 0xbfb8aa3b, v218
	v_mul_f32_e32 v207, 0xbfb8aa3b, v219
	v_exp_f32_e32 v204, v204
	v_exp_f32_e32 v205, v205
	v_exp_f32_e32 v206, v206
	v_exp_f32_e32 v207, v207
	v_add_f32_e32 v204, 1.0, v204
	v_add_f32_e32 v205, 1.0, v205
	v_add_f32_e32 v206, 1.0, v206
	v_add_f32_e32 v207, 1.0, v207
	v_rcp_f32_e32 v204, v204
	v_rcp_f32_e32 v205, v205
	v_rcp_f32_e32 v206, v206
	v_rcp_f32_e32 v207, v207
	v_mul_f32_e32 v204, v216, v204
	v_mul_f32_e32 v205, v217, v205
	v_mul_f32_e32 v206, v218, v206
	v_mul_f32_e32 v207, v219, v207
	v_mul_f32_e32 v204, v212, v204
	v_mul_f32_e32 v205, v213, v205
	v_mul_f32_e32 v206, v214, v206
	v_mul_f32_e32 v207, v215, v207
	v_cvt_pk_bf16_f32 v220, v204, v205
	v_cvt_pk_bf16_f32 v221, v206, v207
	v_mov_b32_e32 v222, v231
	s_mov_b32 exec_lo, 0xfffcfffc
	s_mov_b32 exec_hi, 0xfffcfffc
	global_store_dwordx2 v222, v[220:221], s[36:37]
	s_mov_b64 exec, -1
	v_pk_fma_f32 v[212:213], v[138:139], v[118:119], v[142:143]
	v_pk_fma_f32 v[214:215], v[140:141], v[120:121], v[144:145]
	s_nop 2
	v_mov_b32_dpp v204, v118 row_shr:1 row_mask:0xf bank_mask:0xf
	v_mov_b32_dpp v208, v118 row_shr:2 row_mask:0xf bank_mask:0xf
	v_mov_b32_dpp v205, v119 row_shr:1 row_mask:0xf bank_mask:0xf
	v_mov_b32_dpp v209, v119 row_shr:2 row_mask:0xf bank_mask:0xf
	v_mov_b32_dpp v206, v120 row_shr:1 row_mask:0xf bank_mask:0xf
	v_mov_b32_dpp v210, v120 row_shr:2 row_mask:0xf bank_mask:0xf
	v_mov_b32_dpp v207, v121 row_shr:1 row_mask:0xf bank_mask:0xf
	v_mov_b32_dpp v211, v121 row_shr:2 row_mask:0xf bank_mask:0xf
	s_waitcnt vmcnt(36)
	v_mov_b32_dpp v223, v170 row_shl:1 row_mask:0xf bank_mask:0xf
	v_mov_b32_dpp v224, v171 row_shl:1 row_mask:0xf bank_mask:0xf
	v_mov_b32_dpp v225, v172 row_shl:1 row_mask:0xf bank_mask:0xf
	v_mov_b32_dpp v226, v173 row_shl:1 row_mask:0xf bank_mask:0xf
	v_cndmask_b32_e64 v208, v208, v170, s[48:49]
	v_cndmask_b32_e64 v209, v209, v171, s[48:49]
	v_cndmask_b32_e64 v210, v210, v172, s[48:49]
	v_cndmask_b32_e64 v211, v211, v173, s[48:49]
	v_cndmask_b32_e64 v204, v204, v223, s[46:47]
	v_cndmask_b32_e64 v205, v205, v224, s[46:47]
	v_cndmask_b32_e64 v206, v206, v225, s[46:47]
	v_cndmask_b32_e64 v207, v207, v226, s[46:47]
	s_mov_b64 exec, s[48:49]
	v_add_u32_e32 v222, 0x42000, v190
	global_load_dwordx4 v[170:173], v222, s[16:17]
	s_mov_b64 exec, -1
	v_pk_fma_f32 v[212:213], v[134:135], v[204:205], v[212:213]
	v_pk_fma_f32 v[214:215], v[136:137], v[206:207], v[214:215]
	v_pk_fma_f32 v[212:213], v[130:131], v[208:209], v[212:213]
	v_pk_fma_f32 v[214:215], v[132:133], v[210:211], v[214:215]
	v_pk_fma_f32 v[216:217], v[154:155], v[114:115], v[158:159]
	v_pk_fma_f32 v[218:219], v[156:157], v[116:117], v[160:161]
	s_nop 2
	v_mov_b32_dpp v204, v114 row_shr:1 row_mask:0xf bank_mask:0xf
	v_mov_b32_dpp v208, v114 row_shr:2 row_mask:0xf bank_mask:0xf
	v_mov_b32_dpp v205, v115 row_shr:1 row_mask:0xf bank_mask:0xf
	v_mov_b32_dpp v209, v115 row_shr:2 row_mask:0xf bank_mask:0xf
	v_mov_b32_dpp v206, v116 row_shr:1 row_mask:0xf bank_mask:0xf
	v_mov_b32_dpp v210, v116 row_shr:2 row_mask:0xf bank_mask:0xf
	v_mov_b32_dpp v207, v117 row_shr:1 row_mask:0xf bank_mask:0xf
	v_mov_b32_dpp v211, v117 row_shr:2 row_mask:0xf bank_mask:0xf
	s_waitcnt vmcnt(36)
	v_mov_b32_dpp v223, v174 row_shl:1 row_mask:0xf bank_mask:0xf
	v_mov_b32_dpp v224, v175 row_shl:1 row_mask:0xf bank_mask:0xf
	v_mov_b32_dpp v225, v176 row_shl:1 row_mask:0xf bank_mask:0xf
	v_mov_b32_dpp v226, v177 row_shl:1 row_mask:0xf bank_mask:0xf
	v_cndmask_b32_e64 v208, v208, v174, s[48:49]
	v_cndmask_b32_e64 v209, v209, v175, s[48:49]
	v_cndmask_b32_e64 v210, v210, v176, s[48:49]
	v_cndmask_b32_e64 v211, v211, v177, s[48:49]
	v_cndmask_b32_e64 v204, v204, v223, s[46:47]
	v_cndmask_b32_e64 v205, v205, v224, s[46:47]
	v_cndmask_b32_e64 v206, v206, v225, s[46:47]
	v_cndmask_b32_e64 v207, v207, v226, s[46:47]
	s_mov_b64 exec, s[48:49]
	v_add_u32_e32 v222, 0x44c00, v190
	global_load_dwordx4 v[174:177], v222, s[16:17]
	s_mov_b64 exec, -1
	v_pk_fma_f32 v[216:217], v[150:151], v[204:205], v[216:217]
	v_pk_fma_f32 v[218:219], v[152:153], v[206:207], v[218:219]
	v_pk_fma_f32 v[216:217], v[146:147], v[208:209], v[216:217]
	v_pk_fma_f32 v[218:219], v[148:149], v[210:211], v[218:219]
	v_mul_f32_e32 v204, 0xbfb8aa3b, v216
	v_mul_f32_e32 v205, 0xbfb8aa3b, v217
	v_mul_f32_e32 v206, 0xbfb8aa3b, v218
	v_mul_f32_e32 v207, 0xbfb8aa3b, v219
	v_exp_f32_e32 v204, v204
	v_exp_f32_e32 v205, v205
	v_exp_f32_e32 v206, v206
	v_exp_f32_e32 v207, v207
	v_add_f32_e32 v204, 1.0, v204
	v_add_f32_e32 v205, 1.0, v205
	v_add_f32_e32 v206, 1.0, v206
	v_add_f32_e32 v207, 1.0, v207
	v_rcp_f32_e32 v204, v204
	v_rcp_f32_e32 v205, v205
	v_rcp_f32_e32 v206, v206
	v_rcp_f32_e32 v207, v207
	v_mul_f32_e32 v204, v216, v204
	v_mul_f32_e32 v205, v217, v205
	v_mul_f32_e32 v206, v218, v206
	v_mul_f32_e32 v207, v219, v207
	v_mul_f32_e32 v204, v212, v204
	v_mul_f32_e32 v205, v213, v205
	v_mul_f32_e32 v206, v214, v206
	v_mul_f32_e32 v207, v215, v207
	v_cvt_pk_bf16_f32 v220, v204, v205
	v_cvt_pk_bf16_f32 v221, v206, v207
	v_add_u32_e32 v222, 0x16000, v231
	global_store_dwordx2 v222, v[220:221], s[36:37]
	v_pk_fma_f32 v[212:213], v[138:139], v[110:111], v[142:143]
	v_pk_fma_f32 v[214:215], v[140:141], v[112:113], v[144:145]
	s_nop 2
	v_mov_b32_dpp v204, v110 row_shr:1 row_mask:0xf bank_mask:0xf
	v_mov_b32_dpp v208, v110 row_shr:2 row_mask:0xf bank_mask:0xf
	v_mov_b32_dpp v205, v111 row_shr:1 row_mask:0xf bank_mask:0xf
	v_mov_b32_dpp v209, v111 row_shr:2 row_mask:0xf bank_mask:0xf
	v_mov_b32_dpp v206, v112 row_shr:1 row_mask:0xf bank_mask:0xf
	v_mov_b32_dpp v210, v112 row_shr:2 row_mask:0xf bank_mask:0xf
	v_mov_b32_dpp v207, v113 row_shr:1 row_mask:0xf bank_mask:0xf
	v_mov_b32_dpp v211, v113 row_shr:2 row_mask:0xf bank_mask:0xf
	s_waitcnt vmcnt(5)
	v_mov_b32_dpp v223, v162 row_shl:1 row_mask:0xf bank_mask:0xf
	v_mov_b32_dpp v224, v163 row_shl:1 row_mask:0xf bank_mask:0xf
	v_mov_b32_dpp v225, v164 row_shl:1 row_mask:0xf bank_mask:0xf
	v_mov_b32_dpp v226, v165 row_shl:1 row_mask:0xf bank_mask:0xf
	v_cndmask_b32_e64 v208, v208, v162, s[48:49]
	v_cndmask_b32_e64 v209, v209, v163, s[48:49]
	v_cndmask_b32_e64 v210, v210, v164, s[48:49]
	v_cndmask_b32_e64 v211, v211, v165, s[48:49]
	v_cndmask_b32_e64 v204, v204, v223, s[46:47]
	v_cndmask_b32_e64 v205, v205, v224, s[46:47]
	v_cndmask_b32_e64 v206, v206, v225, s[46:47]
	v_cndmask_b32_e64 v207, v207, v226, s[46:47]
	s_mov_b64 exec, s[48:49]
	v_add_u32_e32 v222, 0xb0000, v190
	global_load_dwordx4 v[162:165], v222, s[16:17]
	s_mov_b64 exec, -1
	v_pk_fma_f32 v[212:213], v[134:135], v[204:205], v[212:213]
	v_pk_fma_f32 v[214:215], v[136:137], v[206:207], v[214:215]
	v_pk_fma_f32 v[212:213], v[130:131], v[208:209], v[212:213]
	v_pk_fma_f32 v[214:215], v[132:133], v[210:211], v[214:215]
	v_pk_fma_f32 v[216:217], v[154:155], v[106:107], v[158:159]
	v_pk_fma_f32 v[218:219], v[156:157], v[108:109], v[160:161]
	s_nop 2
	v_mov_b32_dpp v204, v106 row_shr:1 row_mask:0xf bank_mask:0xf
	v_mov_b32_dpp v208, v106 row_shr:2 row_mask:0xf bank_mask:0xf
	v_mov_b32_dpp v205, v107 row_shr:1 row_mask:0xf bank_mask:0xf
	v_mov_b32_dpp v209, v107 row_shr:2 row_mask:0xf bank_mask:0xf
	v_mov_b32_dpp v206, v108 row_shr:1 row_mask:0xf bank_mask:0xf
	v_mov_b32_dpp v210, v108 row_shr:2 row_mask:0xf bank_mask:0xf
	v_mov_b32_dpp v207, v109 row_shr:1 row_mask:0xf bank_mask:0xf
	v_mov_b32_dpp v211, v109 row_shr:2 row_mask:0xf bank_mask:0xf
	s_waitcnt vmcnt(5)
	v_mov_b32_dpp v223, v166 row_shl:1 row_mask:0xf bank_mask:0xf
	v_mov_b32_dpp v224, v167 row_shl:1 row_mask:0xf bank_mask:0xf
	v_mov_b32_dpp v225, v168 row_shl:1 row_mask:0xf bank_mask:0xf
	v_mov_b32_dpp v226, v169 row_shl:1 row_mask:0xf bank_mask:0xf
	v_cndmask_b32_e64 v208, v208, v166, s[48:49]
	v_cndmask_b32_e64 v209, v209, v167, s[48:49]
	v_cndmask_b32_e64 v210, v210, v168, s[48:49]
	v_cndmask_b32_e64 v211, v211, v169, s[48:49]
	v_cndmask_b32_e64 v204, v204, v223, s[46:47]
	v_cndmask_b32_e64 v205, v205, v224, s[46:47]
	v_cndmask_b32_e64 v206, v206, v225, s[46:47]
	v_cndmask_b32_e64 v207, v207, v226, s[46:47]
	s_mov_b64 exec, s[48:49]
	v_add_u32_e32 v222, 0xb2c00, v190
	global_load_dwordx4 v[166:169], v222, s[16:17]
	s_mov_b64 exec, -1
	v_pk_fma_f32 v[216:217], v[150:151], v[204:205], v[216:217]
	v_pk_fma_f32 v[218:219], v[152:153], v[206:207], v[218:219]
	v_pk_fma_f32 v[216:217], v[146:147], v[208:209], v[216:217]
	v_pk_fma_f32 v[218:219], v[148:149], v[210:211], v[218:219]
	v_mul_f32_e32 v204, 0xbfb8aa3b, v216
	v_mul_f32_e32 v205, 0xbfb8aa3b, v217
	v_mul_f32_e32 v206, 0xbfb8aa3b, v218
	v_mul_f32_e32 v207, 0xbfb8aa3b, v219
	v_exp_f32_e32 v204, v204
	v_exp_f32_e32 v205, v205
	v_exp_f32_e32 v206, v206
	v_exp_f32_e32 v207, v207
	v_add_f32_e32 v204, 1.0, v204
	v_add_f32_e32 v205, 1.0, v205
	v_add_f32_e32 v206, 1.0, v206
	v_add_f32_e32 v207, 1.0, v207
	v_rcp_f32_e32 v204, v204
	v_rcp_f32_e32 v205, v205
	v_rcp_f32_e32 v206, v206
	v_rcp_f32_e32 v207, v207
	v_mul_f32_e32 v204, v216, v204
	v_mul_f32_e32 v205, v217, v205
	v_mul_f32_e32 v206, v218, v206
	v_mul_f32_e32 v207, v219, v207
	v_mul_f32_e32 v204, v212, v204
	v_mul_f32_e32 v205, v213, v205
	v_mul_f32_e32 v206, v214, v206
	v_mul_f32_e32 v207, v215, v207
	v_cvt_pk_bf16_f32 v220, v204, v205
	v_cvt_pk_bf16_f32 v221, v206, v207
	v_add_u32_e32 v222, 0x2c000, v231
	global_store_dwordx2 v222, v[220:221], s[36:37]
	v_pk_fma_f32 v[212:213], v[138:139], v[102:103], v[142:143]
	v_pk_fma_f32 v[214:215], v[140:141], v[104:105], v[144:145]
	s_nop 2
	v_mov_b32_dpp v204, v102 row_shr:1 row_mask:0xf bank_mask:0xf
	v_mov_b32_dpp v208, v102 row_shr:2 row_mask:0xf bank_mask:0xf
	v_mov_b32_dpp v205, v103 row_shr:1 row_mask:0xf bank_mask:0xf
	v_mov_b32_dpp v209, v103 row_shr:2 row_mask:0xf bank_mask:0xf
	v_mov_b32_dpp v206, v104 row_shr:1 row_mask:0xf bank_mask:0xf
	v_mov_b32_dpp v210, v104 row_shr:2 row_mask:0xf bank_mask:0xf
	v_mov_b32_dpp v207, v105 row_shr:1 row_mask:0xf bank_mask:0xf
	v_mov_b32_dpp v211, v105 row_shr:2 row_mask:0xf bank_mask:0xf
	s_waitcnt vmcnt(5)
	v_mov_b32_dpp v223, v170 row_shl:1 row_mask:0xf bank_mask:0xf
	v_mov_b32_dpp v224, v171 row_shl:1 row_mask:0xf bank_mask:0xf
	v_mov_b32_dpp v225, v172 row_shl:1 row_mask:0xf bank_mask:0xf
	v_mov_b32_dpp v226, v173 row_shl:1 row_mask:0xf bank_mask:0xf
	v_cndmask_b32_e64 v208, v208, v170, s[48:49]
	v_cndmask_b32_e64 v209, v209, v171, s[48:49]
	v_cndmask_b32_e64 v210, v210, v172, s[48:49]
	v_cndmask_b32_e64 v211, v211, v173, s[48:49]
	v_cndmask_b32_e64 v204, v204, v223, s[46:47]
	v_cndmask_b32_e64 v205, v205, v224, s[46:47]
	v_cndmask_b32_e64 v206, v206, v225, s[46:47]
	v_cndmask_b32_e64 v207, v207, v226, s[46:47]
	s_mov_b64 exec, s[48:49]
	v_add_u32_e32 v222, 0xc6000, v190
	global_load_dwordx4 v[170:173], v222, s[16:17]
	s_mov_b64 exec, -1
	v_pk_fma_f32 v[212:213], v[134:135], v[204:205], v[212:213]
	v_pk_fma_f32 v[214:215], v[136:137], v[206:207], v[214:215]
	v_pk_fma_f32 v[212:213], v[130:131], v[208:209], v[212:213]
	v_pk_fma_f32 v[214:215], v[132:133], v[210:211], v[214:215]
	v_pk_fma_f32 v[216:217], v[154:155], v[98:99], v[158:159]
	v_pk_fma_f32 v[218:219], v[156:157], v[100:101], v[160:161]
	s_nop 2
	v_mov_b32_dpp v204, v98 row_shr:1 row_mask:0xf bank_mask:0xf
	v_mov_b32_dpp v208, v98 row_shr:2 row_mask:0xf bank_mask:0xf
	v_mov_b32_dpp v205, v99 row_shr:1 row_mask:0xf bank_mask:0xf
	v_mov_b32_dpp v209, v99 row_shr:2 row_mask:0xf bank_mask:0xf
	v_mov_b32_dpp v206, v100 row_shr:1 row_mask:0xf bank_mask:0xf
	v_mov_b32_dpp v210, v100 row_shr:2 row_mask:0xf bank_mask:0xf
	v_mov_b32_dpp v207, v101 row_shr:1 row_mask:0xf bank_mask:0xf
	v_mov_b32_dpp v211, v101 row_shr:2 row_mask:0xf bank_mask:0xf
	s_waitcnt vmcnt(5)
	v_mov_b32_dpp v223, v174 row_shl:1 row_mask:0xf bank_mask:0xf
	v_mov_b32_dpp v224, v175 row_shl:1 row_mask:0xf bank_mask:0xf
	v_mov_b32_dpp v225, v176 row_shl:1 row_mask:0xf bank_mask:0xf
	v_mov_b32_dpp v226, v177 row_shl:1 row_mask:0xf bank_mask:0xf
	v_cndmask_b32_e64 v208, v208, v174, s[48:49]
	v_cndmask_b32_e64 v209, v209, v175, s[48:49]
	v_cndmask_b32_e64 v210, v210, v176, s[48:49]
	v_cndmask_b32_e64 v211, v211, v177, s[48:49]
	v_cndmask_b32_e64 v204, v204, v223, s[46:47]
	v_cndmask_b32_e64 v205, v205, v224, s[46:47]
	v_cndmask_b32_e64 v206, v206, v225, s[46:47]
	v_cndmask_b32_e64 v207, v207, v226, s[46:47]
	s_mov_b64 exec, s[48:49]
	v_add_u32_e32 v222, 0xc8c00, v190
	global_load_dwordx4 v[174:177], v222, s[16:17]
	s_mov_b64 exec, -1
	v_pk_fma_f32 v[216:217], v[150:151], v[204:205], v[216:217]
	v_pk_fma_f32 v[218:219], v[152:153], v[206:207], v[218:219]
	v_pk_fma_f32 v[216:217], v[146:147], v[208:209], v[216:217]
	v_pk_fma_f32 v[218:219], v[148:149], v[210:211], v[218:219]
	v_mul_f32_e32 v204, 0xbfb8aa3b, v216
	v_mul_f32_e32 v205, 0xbfb8aa3b, v217
	v_mul_f32_e32 v206, 0xbfb8aa3b, v218
	v_mul_f32_e32 v207, 0xbfb8aa3b, v219
	v_exp_f32_e32 v204, v204
	v_exp_f32_e32 v205, v205
	v_exp_f32_e32 v206, v206
	v_exp_f32_e32 v207, v207
	v_add_f32_e32 v204, 1.0, v204
	v_add_f32_e32 v205, 1.0, v205
	v_add_f32_e32 v206, 1.0, v206
	v_add_f32_e32 v207, 1.0, v207
	v_rcp_f32_e32 v204, v204
	v_rcp_f32_e32 v205, v205
	v_rcp_f32_e32 v206, v206
	v_rcp_f32_e32 v207, v207
	v_mul_f32_e32 v204, v216, v204
	v_mul_f32_e32 v205, v217, v205
	v_mul_f32_e32 v206, v218, v206
	v_mul_f32_e32 v207, v219, v207
	v_mul_f32_e32 v204, v212, v204
	v_mul_f32_e32 v205, v213, v205
	v_mul_f32_e32 v206, v214, v206
	v_mul_f32_e32 v207, v215, v207
	v_cvt_pk_bf16_f32 v220, v204, v205
	v_cvt_pk_bf16_f32 v221, v206, v207
	v_add_u32_e32 v222, 0x42000, v231
	global_store_dwordx2 v222, v[220:221], s[36:37]
	global_load_dwordx4 v[98:101], v232, s[40:41] offset:16
	v_add_u32_e32 v204, 0x5800, v232
	global_load_dwordx4 v[102:105], v204, s[40:41] offset:16
	v_add_u32_e32 v205, 0xb000, v232
	global_load_dwordx4 v[106:109], v205, s[40:41] offset:16
	global_load_dwordx4 v[110:113], v232, s[42:43] offset:16
	v_add_u32_e32 v206, 0x2c00, v232
	global_load_dwordx4 v[114:117], v206, s[40:41] offset:16
	v_add_u32_e32 v207, 0x8400, v232
	global_load_dwordx4 v[118:121], v207, s[40:41] offset:16
	v_add_u32_e32 v208, 0xdc00, v232
	global_load_dwordx4 v[122:125], v208, s[40:41] offset:16
	v_add_u32_e32 v209, 0x2c00, v232
	global_load_dwordx4 v[126:129], v209, s[42:43] offset:16
	s_mov_b64 exec, s[50:51]
	v_add_u32_e32 v223, 0x10, v235
	global_store_dwordx4 v223, v[62:65], s[44:45]
	v_add_u32_e32 v224, 0x2c10, v235
	global_store_dwordx4 v224, v[58:61], s[44:45]
	v_add_u32_e32 v225, 0x16010, v235
	global_store_dwordx4 v225, v[54:57], s[44:45]
	v_add_u32_e32 v226, 0x18c10, v235
	global_store_dwordx4 v226, v[50:53], s[44:45]
	v_add_u32_e32 v223, 0x2c010, v235
	global_store_dwordx4 v223, v[46:49], s[44:45]
	v_add_u32_e32 v224, 0x2ec10, v235
	global_store_dwordx4 v224, v[42:45], s[44:45]
	v_add_u32_e32 v225, 0x42010, v235
	global_store_dwordx4 v225, v[38:41], s[44:45]
	v_add_u32_e32 v226, 0x44c10, v235
	global_store_dwordx4 v226, v[34:37], s[44:45]
	v_add_u32_e32 v223, 0xb0010, v235
	global_store_dwordx4 v223, v[30:33], s[44:45]
	v_add_u32_e32 v224, 0xb2c10, v235
	global_store_dwordx4 v224, v[26:29], s[44:45]
	v_add_u32_e32 v225, 0xc6010, v235
	global_store_dwordx4 v225, v[22:25], s[44:45]
	v_add_u32_e32 v226, 0xc8c10, v235
	global_store_dwordx4 v226, v[18:21], s[44:45]
	v_add_u32_e32 v223, 0xdc010, v235
	global_store_dwordx4 v223, v[14:17], s[44:45]
	v_add_u32_e32 v224, 0xdec10, v235
	global_store_dwordx4 v224, v[10:13], s[44:45]
	v_add_u32_e32 v225, 0xf2010, v235
	global_store_dwordx4 v225, v[6:9], s[44:45]
	v_add_u32_e32 v226, 0xf4c10, v235
	global_store_dwordx4 v226, v[2:5], s[44:45]
	s_mov_b64 exec, -1
	v_pk_fma_f32 v[212:213], v[138:139], v[94:95], v[142:143]
	v_pk_fma_f32 v[214:215], v[140:141], v[96:97], v[144:145]
	s_nop 2
	v_mov_b32_dpp v204, v94 row_shr:1 row_mask:0xf bank_mask:0xf
	v_mov_b32_dpp v208, v94 row_shr:2 row_mask:0xf bank_mask:0xf
	v_mov_b32_dpp v205, v95 row_shr:1 row_mask:0xf bank_mask:0xf
	v_mov_b32_dpp v209, v95 row_shr:2 row_mask:0xf bank_mask:0xf
	v_mov_b32_dpp v206, v96 row_shr:1 row_mask:0xf bank_mask:0xf
	v_mov_b32_dpp v210, v96 row_shr:2 row_mask:0xf bank_mask:0xf
	v_mov_b32_dpp v207, v97 row_shr:1 row_mask:0xf bank_mask:0xf
	v_mov_b32_dpp v211, v97 row_shr:2 row_mask:0xf bank_mask:0xf
	s_waitcnt vmcnt(29)
	v_mov_b32_dpp v223, v162 row_shl:1 row_mask:0xf bank_mask:0xf
	v_mov_b32_dpp v224, v163 row_shl:1 row_mask:0xf bank_mask:0xf
	v_mov_b32_dpp v225, v164 row_shl:1 row_mask:0xf bank_mask:0xf
	v_mov_b32_dpp v226, v165 row_shl:1 row_mask:0xf bank_mask:0xf
	v_cndmask_b32_e64 v208, v208, v162, s[48:49]
	v_cndmask_b32_e64 v209, v209, v163, s[48:49]
	v_cndmask_b32_e64 v210, v210, v164, s[48:49]
	v_cndmask_b32_e64 v211, v211, v165, s[48:49]
	v_cndmask_b32_e64 v204, v204, v223, s[46:47]
	v_cndmask_b32_e64 v205, v205, v224, s[46:47]
	v_cndmask_b32_e64 v206, v206, v225, s[46:47]
	v_cndmask_b32_e64 v207, v207, v226, s[46:47]
	s_mov_b64 exec, s[48:49]
	v_add_u32_e32 v222, 0xdc000, v190
	global_load_dwordx4 v[162:165], v222, s[16:17]
	s_mov_b64 exec, -1
	v_pk_fma_f32 v[212:213], v[134:135], v[204:205], v[212:213]
	v_pk_fma_f32 v[214:215], v[136:137], v[206:207], v[214:215]
	v_pk_fma_f32 v[212:213], v[130:131], v[208:209], v[212:213]
	v_pk_fma_f32 v[214:215], v[132:133], v[210:211], v[214:215]
	v_pk_fma_f32 v[216:217], v[154:155], v[90:91], v[158:159]
	v_pk_fma_f32 v[218:219], v[156:157], v[92:93], v[160:161]
	s_nop 2
	v_mov_b32_dpp v204, v90 row_shr:1 row_mask:0xf bank_mask:0xf
	v_mov_b32_dpp v208, v90 row_shr:2 row_mask:0xf bank_mask:0xf
	v_mov_b32_dpp v205, v91 row_shr:1 row_mask:0xf bank_mask:0xf
	v_mov_b32_dpp v209, v91 row_shr:2 row_mask:0xf bank_mask:0xf
	v_mov_b32_dpp v206, v92 row_shr:1 row_mask:0xf bank_mask:0xf
	v_mov_b32_dpp v210, v92 row_shr:2 row_mask:0xf bank_mask:0xf
	v_mov_b32_dpp v207, v93 row_shr:1 row_mask:0xf bank_mask:0xf
	v_mov_b32_dpp v211, v93 row_shr:2 row_mask:0xf bank_mask:0xf
	s_waitcnt vmcnt(29)
	v_mov_b32_dpp v223, v166 row_shl:1 row_mask:0xf bank_mask:0xf
	v_mov_b32_dpp v224, v167 row_shl:1 row_mask:0xf bank_mask:0xf
	v_mov_b32_dpp v225, v168 row_shl:1 row_mask:0xf bank_mask:0xf
	v_mov_b32_dpp v226, v169 row_shl:1 row_mask:0xf bank_mask:0xf
	v_cndmask_b32_e64 v208, v208, v166, s[48:49]
	v_cndmask_b32_e64 v209, v209, v167, s[48:49]
	v_cndmask_b32_e64 v210, v210, v168, s[48:49]
	v_cndmask_b32_e64 v211, v211, v169, s[48:49]
	v_cndmask_b32_e64 v204, v204, v223, s[46:47]
	v_cndmask_b32_e64 v205, v205, v224, s[46:47]
	v_cndmask_b32_e64 v206, v206, v225, s[46:47]
	v_cndmask_b32_e64 v207, v207, v226, s[46:47]
	s_mov_b64 exec, s[48:49]
	v_add_u32_e32 v222, 0xdec00, v190
	global_load_dwordx4 v[166:169], v222, s[16:17]
	s_mov_b64 exec, -1
	v_pk_fma_f32 v[216:217], v[150:151], v[204:205], v[216:217]
	v_pk_fma_f32 v[218:219], v[152:153], v[206:207], v[218:219]
	v_pk_fma_f32 v[216:217], v[146:147], v[208:209], v[216:217]
	v_pk_fma_f32 v[218:219], v[148:149], v[210:211], v[218:219]
	v_mul_f32_e32 v204, 0xbfb8aa3b, v216
	v_mul_f32_e32 v205, 0xbfb8aa3b, v217
	v_mul_f32_e32 v206, 0xbfb8aa3b, v218
	v_mul_f32_e32 v207, 0xbfb8aa3b, v219
	v_exp_f32_e32 v204, v204
	v_exp_f32_e32 v205, v205
	v_exp_f32_e32 v206, v206
	v_exp_f32_e32 v207, v207
	v_add_f32_e32 v204, 1.0, v204
	v_add_f32_e32 v205, 1.0, v205
	v_add_f32_e32 v206, 1.0, v206
	v_add_f32_e32 v207, 1.0, v207
	v_rcp_f32_e32 v204, v204
	v_rcp_f32_e32 v205, v205
	v_rcp_f32_e32 v206, v206
	v_rcp_f32_e32 v207, v207
	v_mul_f32_e32 v204, v216, v204
	v_mul_f32_e32 v205, v217, v205
	v_mul_f32_e32 v206, v218, v206
	v_mul_f32_e32 v207, v219, v207
	v_mul_f32_e32 v204, v212, v204
	v_mul_f32_e32 v205, v213, v205
	v_mul_f32_e32 v206, v214, v206
	v_mul_f32_e32 v207, v215, v207
	v_cvt_pk_bf16_f32 v94, v204, v205
	v_cvt_pk_bf16_f32 v95, v206, v207
	v_pk_fma_f32 v[212:213], v[138:139], v[86:87], v[142:143]
	v_pk_fma_f32 v[214:215], v[140:141], v[88:89], v[144:145]
	s_nop 2
	v_mov_b32_dpp v204, v86 row_shr:1 row_mask:0xf bank_mask:0xf
	v_mov_b32_dpp v208, v86 row_shr:2 row_mask:0xf bank_mask:0xf
	v_mov_b32_dpp v205, v87 row_shr:1 row_mask:0xf bank_mask:0xf
	v_mov_b32_dpp v209, v87 row_shr:2 row_mask:0xf bank_mask:0xf
	v_mov_b32_dpp v206, v88 row_shr:1 row_mask:0xf bank_mask:0xf
	v_mov_b32_dpp v210, v88 row_shr:2 row_mask:0xf bank_mask:0xf
	v_mov_b32_dpp v207, v89 row_shr:1 row_mask:0xf bank_mask:0xf
	v_mov_b32_dpp v211, v89 row_shr:2 row_mask:0xf bank_mask:0xf
	s_waitcnt vmcnt(28)
	v_mov_b32_dpp v223, v170 row_shl:1 row_mask:0xf bank_mask:0xf
	v_mov_b32_dpp v224, v171 row_shl:1 row_mask:0xf bank_mask:0xf
	v_mov_b32_dpp v225, v172 row_shl:1 row_mask:0xf bank_mask:0xf
	v_mov_b32_dpp v226, v173 row_shl:1 row_mask:0xf bank_mask:0xf
	v_cndmask_b32_e64 v208, v208, v170, s[48:49]
	v_cndmask_b32_e64 v209, v209, v171, s[48:49]
	v_cndmask_b32_e64 v210, v210, v172, s[48:49]
	v_cndmask_b32_e64 v211, v211, v173, s[48:49]
	v_cndmask_b32_e64 v204, v204, v223, s[46:47]
	v_cndmask_b32_e64 v205, v205, v224, s[46:47]
	v_cndmask_b32_e64 v206, v206, v225, s[46:47]
	v_cndmask_b32_e64 v207, v207, v226, s[46:47]
	s_mov_b64 exec, s[48:49]
	v_add_u32_e32 v222, 0xf2000, v190
	global_load_dwordx4 v[170:173], v222, s[16:17]
	s_mov_b64 exec, -1
	v_pk_fma_f32 v[212:213], v[134:135], v[204:205], v[212:213]
	v_pk_fma_f32 v[214:215], v[136:137], v[206:207], v[214:215]
	v_pk_fma_f32 v[212:213], v[130:131], v[208:209], v[212:213]
	v_pk_fma_f32 v[214:215], v[132:133], v[210:211], v[214:215]
	v_pk_fma_f32 v[216:217], v[154:155], v[82:83], v[158:159]
	v_pk_fma_f32 v[218:219], v[156:157], v[84:85], v[160:161]
	s_nop 2
	v_mov_b32_dpp v204, v82 row_shr:1 row_mask:0xf bank_mask:0xf
	v_mov_b32_dpp v208, v82 row_shr:2 row_mask:0xf bank_mask:0xf
	v_mov_b32_dpp v205, v83 row_shr:1 row_mask:0xf bank_mask:0xf
	v_mov_b32_dpp v209, v83 row_shr:2 row_mask:0xf bank_mask:0xf
	v_mov_b32_dpp v206, v84 row_shr:1 row_mask:0xf bank_mask:0xf
	v_mov_b32_dpp v210, v84 row_shr:2 row_mask:0xf bank_mask:0xf
	v_mov_b32_dpp v207, v85 row_shr:1 row_mask:0xf bank_mask:0xf
	v_mov_b32_dpp v211, v85 row_shr:2 row_mask:0xf bank_mask:0xf
	s_waitcnt vmcnt(28)
	v_mov_b32_dpp v223, v174 row_shl:1 row_mask:0xf bank_mask:0xf
	v_mov_b32_dpp v224, v175 row_shl:1 row_mask:0xf bank_mask:0xf
	v_mov_b32_dpp v225, v176 row_shl:1 row_mask:0xf bank_mask:0xf
	v_mov_b32_dpp v226, v177 row_shl:1 row_mask:0xf bank_mask:0xf
	v_cndmask_b32_e64 v208, v208, v174, s[48:49]
	v_cndmask_b32_e64 v209, v209, v175, s[48:49]
	v_cndmask_b32_e64 v210, v210, v176, s[48:49]
	v_cndmask_b32_e64 v211, v211, v177, s[48:49]
	v_cndmask_b32_e64 v204, v204, v223, s[46:47]
	v_cndmask_b32_e64 v205, v205, v224, s[46:47]
	v_cndmask_b32_e64 v206, v206, v225, s[46:47]
	v_cndmask_b32_e64 v207, v207, v226, s[46:47]
	s_mov_b64 exec, s[48:49]
	v_add_u32_e32 v222, 0xf4c00, v190
	global_load_dwordx4 v[174:177], v222, s[16:17]
	s_mov_b64 exec, -1
	v_pk_fma_f32 v[216:217], v[150:151], v[204:205], v[216:217]
	v_pk_fma_f32 v[218:219], v[152:153], v[206:207], v[218:219]
	v_pk_fma_f32 v[216:217], v[146:147], v[208:209], v[216:217]
	v_pk_fma_f32 v[218:219], v[148:149], v[210:211], v[218:219]
	v_mul_f32_e32 v204, 0xbfb8aa3b, v216
	v_mul_f32_e32 v205, 0xbfb8aa3b, v217
	v_mul_f32_e32 v206, 0xbfb8aa3b, v218
	v_mul_f32_e32 v207, 0xbfb8aa3b, v219
	v_exp_f32_e32 v204, v204
	v_exp_f32_e32 v205, v205
	v_exp_f32_e32 v206, v206
	v_exp_f32_e32 v207, v207
	v_add_f32_e32 v204, 1.0, v204
	v_add_f32_e32 v205, 1.0, v205
	v_add_f32_e32 v206, 1.0, v206
	v_add_f32_e32 v207, 1.0, v207
	v_rcp_f32_e32 v204, v204
	v_rcp_f32_e32 v205, v205
	v_rcp_f32_e32 v206, v206
	v_rcp_f32_e32 v207, v207
	v_mul_f32_e32 v204, v216, v204
	v_mul_f32_e32 v205, v217, v205
	v_mul_f32_e32 v206, v218, v206
	v_mul_f32_e32 v207, v219, v207
	v_mul_f32_e32 v204, v212, v204
	v_mul_f32_e32 v205, v213, v205
	v_mul_f32_e32 v206, v214, v206
	v_mul_f32_e32 v207, v215, v207
	v_cvt_pk_bf16_f32 v86, v204, v205
	v_cvt_pk_bf16_f32 v87, v206, v207
	v_pk_fma_f32 v[212:213], v[138:139], v[78:79], v[142:143]
	v_pk_fma_f32 v[214:215], v[140:141], v[80:81], v[144:145]
	s_nop 2
	v_mov_b32_dpp v204, v78 row_shr:1 row_mask:0xf bank_mask:0xf
	v_mov_b32_dpp v208, v78 row_shr:2 row_mask:0xf bank_mask:0xf
	v_mov_b32_dpp v205, v79 row_shr:1 row_mask:0xf bank_mask:0xf
	v_mov_b32_dpp v209, v79 row_shr:2 row_mask:0xf bank_mask:0xf
	v_mov_b32_dpp v206, v80 row_shr:1 row_mask:0xf bank_mask:0xf
	v_mov_b32_dpp v210, v80 row_shr:2 row_mask:0xf bank_mask:0xf
	v_mov_b32_dpp v207, v81 row_shr:1 row_mask:0xf bank_mask:0xf
	v_mov_b32_dpp v211, v81 row_shr:2 row_mask:0xf bank_mask:0xf
	s_waitcnt vmcnt(3)
	v_mov_b32_dpp v223, v162 row_shl:1 row_mask:0xf bank_mask:0xf
	v_mov_b32_dpp v224, v163 row_shl:1 row_mask:0xf bank_mask:0xf
	v_mov_b32_dpp v225, v164 row_shl:1 row_mask:0xf bank_mask:0xf
	v_mov_b32_dpp v226, v165 row_shl:1 row_mask:0xf bank_mask:0xf
	v_cndmask_b32_e64 v208, v208, v162, s[48:49]
	v_cndmask_b32_e64 v209, v209, v163, s[48:49]
	v_cndmask_b32_e64 v210, v210, v164, s[48:49]
	v_cndmask_b32_e64 v211, v211, v165, s[48:49]
	v_cndmask_b32_e64 v204, v204, v223, s[46:47]
	v_cndmask_b32_e64 v205, v205, v224, s[46:47]
	v_cndmask_b32_e64 v206, v206, v225, s[46:47]
	v_cndmask_b32_e64 v207, v207, v226, s[46:47]
	s_mov_b64 exec, s[48:49]
	global_load_dwordx4 v[162:165], v190, s[16:17] offset:16
	s_mov_b64 exec, -1
	v_pk_fma_f32 v[212:213], v[134:135], v[204:205], v[212:213]
	v_pk_fma_f32 v[214:215], v[136:137], v[206:207], v[214:215]
	v_pk_fma_f32 v[212:213], v[130:131], v[208:209], v[212:213]
	v_pk_fma_f32 v[214:215], v[132:133], v[210:211], v[214:215]
	v_pk_fma_f32 v[216:217], v[154:155], v[74:75], v[158:159]
	v_pk_fma_f32 v[218:219], v[156:157], v[76:77], v[160:161]
	s_nop 2
	v_mov_b32_dpp v204, v74 row_shr:1 row_mask:0xf bank_mask:0xf
	v_mov_b32_dpp v208, v74 row_shr:2 row_mask:0xf bank_mask:0xf
	v_mov_b32_dpp v205, v75 row_shr:1 row_mask:0xf bank_mask:0xf
	v_mov_b32_dpp v209, v75 row_shr:2 row_mask:0xf bank_mask:0xf
	v_mov_b32_dpp v206, v76 row_shr:1 row_mask:0xf bank_mask:0xf
	v_mov_b32_dpp v210, v76 row_shr:2 row_mask:0xf bank_mask:0xf
	v_mov_b32_dpp v207, v77 row_shr:1 row_mask:0xf bank_mask:0xf
	v_mov_b32_dpp v211, v77 row_shr:2 row_mask:0xf bank_mask:0xf
	s_waitcnt vmcnt(3)
	v_mov_b32_dpp v223, v166 row_shl:1 row_mask:0xf bank_mask:0xf
	v_mov_b32_dpp v224, v167 row_shl:1 row_mask:0xf bank_mask:0xf
	v_mov_b32_dpp v225, v168 row_shl:1 row_mask:0xf bank_mask:0xf
	v_mov_b32_dpp v226, v169 row_shl:1 row_mask:0xf bank_mask:0xf
	v_cndmask_b32_e64 v208, v208, v166, s[48:49]
	v_cndmask_b32_e64 v209, v209, v167, s[48:49]
	v_cndmask_b32_e64 v210, v210, v168, s[48:49]
	v_cndmask_b32_e64 v211, v211, v169, s[48:49]
	v_cndmask_b32_e64 v204, v204, v223, s[46:47]
	v_cndmask_b32_e64 v205, v205, v224, s[46:47]
	v_cndmask_b32_e64 v206, v206, v225, s[46:47]
	v_cndmask_b32_e64 v207, v207, v226, s[46:47]
	s_mov_b64 exec, s[48:49]
	v_add_u32_e32 v222, 0x2c00, v190
	global_load_dwordx4 v[166:169], v222, s[16:17] offset:16
	s_mov_b64 exec, -1
	v_pk_fma_f32 v[216:217], v[150:151], v[204:205], v[216:217]
	v_pk_fma_f32 v[218:219], v[152:153], v[206:207], v[218:219]
	v_pk_fma_f32 v[216:217], v[146:147], v[208:209], v[216:217]
	v_pk_fma_f32 v[218:219], v[148:149], v[210:211], v[218:219]
	v_mul_f32_e32 v204, 0xbfb8aa3b, v216
	v_mul_f32_e32 v205, 0xbfb8aa3b, v217
	v_mul_f32_e32 v206, 0xbfb8aa3b, v218
	v_mul_f32_e32 v207, 0xbfb8aa3b, v219
	v_exp_f32_e32 v204, v204
	v_exp_f32_e32 v205, v205
	v_exp_f32_e32 v206, v206
	v_exp_f32_e32 v207, v207
	v_add_f32_e32 v204, 1.0, v204
	v_add_f32_e32 v205, 1.0, v205
	v_add_f32_e32 v206, 1.0, v206
	v_add_f32_e32 v207, 1.0, v207
	v_rcp_f32_e32 v204, v204
	v_rcp_f32_e32 v205, v205
	v_rcp_f32_e32 v206, v206
	v_rcp_f32_e32 v207, v207
	v_mul_f32_e32 v204, v216, v204
	v_mul_f32_e32 v205, v217, v205
	v_mul_f32_e32 v206, v218, v206
	v_mul_f32_e32 v207, v219, v207
	v_mul_f32_e32 v204, v212, v204
	v_mul_f32_e32 v205, v213, v205
	v_mul_f32_e32 v206, v214, v206
	v_mul_f32_e32 v207, v215, v207
	v_cvt_pk_bf16_f32 v78, v204, v205
	v_cvt_pk_bf16_f32 v79, v206, v207
	v_pk_fma_f32 v[212:213], v[138:139], v[70:71], v[142:143]
	v_pk_fma_f32 v[214:215], v[140:141], v[72:73], v[144:145]
	s_nop 2
	v_mov_b32_dpp v204, v70 row_shr:1 row_mask:0xf bank_mask:0xf
	v_mov_b32_dpp v208, v70 row_shr:2 row_mask:0xf bank_mask:0xf
	v_mov_b32_dpp v205, v71 row_shr:1 row_mask:0xf bank_mask:0xf
	v_mov_b32_dpp v209, v71 row_shr:2 row_mask:0xf bank_mask:0xf
	v_mov_b32_dpp v206, v72 row_shr:1 row_mask:0xf bank_mask:0xf
	v_mov_b32_dpp v210, v72 row_shr:2 row_mask:0xf bank_mask:0xf
	v_mov_b32_dpp v207, v73 row_shr:1 row_mask:0xf bank_mask:0xf
	v_mov_b32_dpp v211, v73 row_shr:2 row_mask:0xf bank_mask:0xf
	s_waitcnt vmcnt(3)
	v_mov_b32_dpp v223, v170 row_shl:1 row_mask:0xf bank_mask:0xf
	v_mov_b32_dpp v224, v171 row_shl:1 row_mask:0xf bank_mask:0xf
	v_mov_b32_dpp v225, v172 row_shl:1 row_mask:0xf bank_mask:0xf
	v_mov_b32_dpp v226, v173 row_shl:1 row_mask:0xf bank_mask:0xf
	v_cndmask_b32_e64 v208, v208, v170, s[48:49]
	v_cndmask_b32_e64 v209, v209, v171, s[48:49]
	v_cndmask_b32_e64 v210, v210, v172, s[48:49]
	v_cndmask_b32_e64 v211, v211, v173, s[48:49]
	v_cndmask_b32_e64 v204, v204, v223, s[46:47]
	v_cndmask_b32_e64 v205, v205, v224, s[46:47]
	v_cndmask_b32_e64 v206, v206, v225, s[46:47]
	v_cndmask_b32_e64 v207, v207, v226, s[46:47]
	s_mov_b64 exec, s[48:49]
	v_add_u32_e32 v222, 0x16000, v190
	global_load_dwordx4 v[170:173], v222, s[16:17] offset:16
	s_mov_b64 exec, -1
	v_pk_fma_f32 v[212:213], v[134:135], v[204:205], v[212:213]
	v_pk_fma_f32 v[214:215], v[136:137], v[206:207], v[214:215]
	v_pk_fma_f32 v[212:213], v[130:131], v[208:209], v[212:213]
	v_pk_fma_f32 v[214:215], v[132:133], v[210:211], v[214:215]
	v_pk_fma_f32 v[216:217], v[154:155], v[66:67], v[158:159]
	v_pk_fma_f32 v[218:219], v[156:157], v[68:69], v[160:161]
	s_nop 2
	v_mov_b32_dpp v204, v66 row_shr:1 row_mask:0xf bank_mask:0xf
	v_mov_b32_dpp v208, v66 row_shr:2 row_mask:0xf bank_mask:0xf
	v_mov_b32_dpp v205, v67 row_shr:1 row_mask:0xf bank_mask:0xf
	v_mov_b32_dpp v209, v67 row_shr:2 row_mask:0xf bank_mask:0xf
	v_mov_b32_dpp v206, v68 row_shr:1 row_mask:0xf bank_mask:0xf
	v_mov_b32_dpp v210, v68 row_shr:2 row_mask:0xf bank_mask:0xf
	v_mov_b32_dpp v207, v69 row_shr:1 row_mask:0xf bank_mask:0xf
	v_mov_b32_dpp v211, v69 row_shr:2 row_mask:0xf bank_mask:0xf
	s_waitcnt vmcnt(3)
	v_mov_b32_dpp v223, v174 row_shl:1 row_mask:0xf bank_mask:0xf
	v_mov_b32_dpp v224, v175 row_shl:1 row_mask:0xf bank_mask:0xf
	v_mov_b32_dpp v225, v176 row_shl:1 row_mask:0xf bank_mask:0xf
	v_mov_b32_dpp v226, v177 row_shl:1 row_mask:0xf bank_mask:0xf
	v_cndmask_b32_e64 v208, v208, v174, s[48:49]
	v_cndmask_b32_e64 v209, v209, v175, s[48:49]
	v_cndmask_b32_e64 v210, v210, v176, s[48:49]
	v_cndmask_b32_e64 v211, v211, v177, s[48:49]
	v_cndmask_b32_e64 v204, v204, v223, s[46:47]
	v_cndmask_b32_e64 v205, v205, v224, s[46:47]
	v_cndmask_b32_e64 v206, v206, v225, s[46:47]
	v_cndmask_b32_e64 v207, v207, v226, s[46:47]
	s_mov_b64 exec, s[48:49]
	v_add_u32_e32 v222, 0x18c00, v190
	global_load_dwordx4 v[174:177], v222, s[16:17] offset:16
	s_mov_b64 exec, -1
	v_pk_fma_f32 v[216:217], v[150:151], v[204:205], v[216:217]
	v_pk_fma_f32 v[218:219], v[152:153], v[206:207], v[218:219]
	v_pk_fma_f32 v[216:217], v[146:147], v[208:209], v[216:217]
	v_pk_fma_f32 v[218:219], v[148:149], v[210:211], v[218:219]
	v_mul_f32_e32 v204, 0xbfb8aa3b, v216
	v_mul_f32_e32 v205, 0xbfb8aa3b, v217
	v_mul_f32_e32 v206, 0xbfb8aa3b, v218
	v_mul_f32_e32 v207, 0xbfb8aa3b, v219
	v_exp_f32_e32 v204, v204
	v_exp_f32_e32 v205, v205
	v_exp_f32_e32 v206, v206
	v_exp_f32_e32 v207, v207
	v_add_f32_e32 v204, 1.0, v204
	v_add_f32_e32 v205, 1.0, v205
	v_add_f32_e32 v206, 1.0, v206
	v_add_f32_e32 v207, 1.0, v207
	v_rcp_f32_e32 v204, v204
	v_rcp_f32_e32 v205, v205
	v_rcp_f32_e32 v206, v206
	v_rcp_f32_e32 v207, v207
	v_mul_f32_e32 v204, v216, v204
	v_mul_f32_e32 v205, v217, v205
	v_mul_f32_e32 v206, v218, v206
	v_mul_f32_e32 v207, v219, v207
	v_mul_f32_e32 v204, v212, v204
	v_mul_f32_e32 v205, v213, v205
	v_mul_f32_e32 v206, v214, v206
	v_mul_f32_e32 v207, v215, v207
	v_cvt_pk_bf16_f32 v70, v204, v205
	v_cvt_pk_bf16_f32 v71, v206, v207
	s_waitcnt vmcnt(24)
	v_pk_fma_f32 v[212:213], v[106:107], v[62:63], v[110:111]
	v_pk_fma_f32 v[214:215], v[108:109], v[64:65], v[112:113]
	s_nop 2
	v_mov_b32_dpp v204, v62 row_shr:1 row_mask:0xf bank_mask:0xf
	v_mov_b32_dpp v208, v62 row_shr:2 row_mask:0xf bank_mask:0xf
	v_mov_b32_dpp v205, v63 row_shr:1 row_mask:0xf bank_mask:0xf
	v_mov_b32_dpp v209, v63 row_shr:2 row_mask:0xf bank_mask:0xf
	v_mov_b32_dpp v206, v64 row_shr:1 row_mask:0xf bank_mask:0xf
	v_mov_b32_dpp v210, v64 row_shr:2 row_mask:0xf bank_mask:0xf
	v_mov_b32_dpp v207, v65 row_shr:1 row_mask:0xf bank_mask:0xf
	v_mov_b32_dpp v211, v65 row_shr:2 row_mask:0xf bank_mask:0xf
	s_waitcnt vmcnt(3)
	v_mov_b32_dpp v223, v162 row_shl:1 row_mask:0xf bank_mask:0xf
	v_mov_b32_dpp v224, v163 row_shl:1 row_mask:0xf bank_mask:0xf
	v_mov_b32_dpp v225, v164 row_shl:1 row_mask:0xf bank_mask:0xf
	v_mov_b32_dpp v226, v165 row_shl:1 row_mask:0xf bank_mask:0xf
	v_cndmask_b32_e64 v208, v208, v162, s[48:49]
	v_cndmask_b32_e64 v209, v209, v163, s[48:49]
	v_cndmask_b32_e64 v210, v210, v164, s[48:49]
	v_cndmask_b32_e64 v211, v211, v165, s[48:49]
	v_cndmask_b32_e64 v204, v204, v223, s[46:47]
	v_cndmask_b32_e64 v205, v205, v224, s[46:47]
	v_cndmask_b32_e64 v206, v206, v225, s[46:47]
	v_cndmask_b32_e64 v207, v207, v226, s[46:47]
	s_mov_b64 exec, s[48:49]
	v_add_u32_e32 v222, 0x2c000, v190
	global_load_dwordx4 v[162:165], v222, s[16:17] offset:16
	s_mov_b64 exec, -1
	v_pk_fma_f32 v[212:213], v[102:103], v[204:205], v[212:213]
	v_pk_fma_f32 v[214:215], v[104:105], v[206:207], v[214:215]
	v_pk_fma_f32 v[212:213], v[98:99], v[208:209], v[212:213]
	v_pk_fma_f32 v[214:215], v[100:101], v[210:211], v[214:215]
	v_pk_fma_f32 v[216:217], v[122:123], v[58:59], v[126:127]
	v_pk_fma_f32 v[218:219], v[124:125], v[60:61], v[128:129]
	s_nop 2
	v_mov_b32_dpp v204, v58 row_shr:1 row_mask:0xf bank_mask:0xf
	v_mov_b32_dpp v208, v58 row_shr:2 row_mask:0xf bank_mask:0xf
	v_mov_b32_dpp v205, v59 row_shr:1 row_mask:0xf bank_mask:0xf
	v_mov_b32_dpp v209, v59 row_shr:2 row_mask:0xf bank_mask:0xf
	v_mov_b32_dpp v206, v60 row_shr:1 row_mask:0xf bank_mask:0xf
	v_mov_b32_dpp v210, v60 row_shr:2 row_mask:0xf bank_mask:0xf
	v_mov_b32_dpp v207, v61 row_shr:1 row_mask:0xf bank_mask:0xf
	v_mov_b32_dpp v211, v61 row_shr:2 row_mask:0xf bank_mask:0xf
	s_waitcnt vmcnt(3)
	v_mov_b32_dpp v223, v166 row_shl:1 row_mask:0xf bank_mask:0xf
	v_mov_b32_dpp v224, v167 row_shl:1 row_mask:0xf bank_mask:0xf
	v_mov_b32_dpp v225, v168 row_shl:1 row_mask:0xf bank_mask:0xf
	v_mov_b32_dpp v226, v169 row_shl:1 row_mask:0xf bank_mask:0xf
	v_cndmask_b32_e64 v208, v208, v166, s[48:49]
	v_cndmask_b32_e64 v209, v209, v167, s[48:49]
	v_cndmask_b32_e64 v210, v210, v168, s[48:49]
	v_cndmask_b32_e64 v211, v211, v169, s[48:49]
	v_cndmask_b32_e64 v204, v204, v223, s[46:47]
	v_cndmask_b32_e64 v205, v205, v224, s[46:47]
	v_cndmask_b32_e64 v206, v206, v225, s[46:47]
	v_cndmask_b32_e64 v207, v207, v226, s[46:47]
	s_mov_b64 exec, s[48:49]
	v_add_u32_e32 v222, 0x2ec00, v190
	global_load_dwordx4 v[166:169], v222, s[16:17] offset:16
	s_mov_b64 exec, -1
	v_pk_fma_f32 v[216:217], v[118:119], v[204:205], v[216:217]
	v_pk_fma_f32 v[218:219], v[120:121], v[206:207], v[218:219]
	v_pk_fma_f32 v[216:217], v[114:115], v[208:209], v[216:217]
	v_pk_fma_f32 v[218:219], v[116:117], v[210:211], v[218:219]
	v_mul_f32_e32 v204, 0xbfb8aa3b, v216
	v_mul_f32_e32 v205, 0xbfb8aa3b, v217
	v_mul_f32_e32 v206, 0xbfb8aa3b, v218
	v_mul_f32_e32 v207, 0xbfb8aa3b, v219
	v_exp_f32_e32 v204, v204
	v_exp_f32_e32 v205, v205
	v_exp_f32_e32 v206, v206
	v_exp_f32_e32 v207, v207
	v_add_f32_e32 v204, 1.0, v204
	v_add_f32_e32 v205, 1.0, v205
	v_add_f32_e32 v206, 1.0, v206
	v_add_f32_e32 v207, 1.0, v207
	v_rcp_f32_e32 v204, v204
	v_rcp_f32_e32 v205, v205
	v_rcp_f32_e32 v206, v206
	v_rcp_f32_e32 v207, v207
	v_mul_f32_e32 v204, v216, v204
	v_mul_f32_e32 v205, v217, v205
	v_mul_f32_e32 v206, v218, v206
	v_mul_f32_e32 v207, v219, v207
	v_mul_f32_e32 v204, v212, v204
	v_mul_f32_e32 v205, v213, v205
	v_mul_f32_e32 v206, v214, v206
	v_mul_f32_e32 v207, v215, v207
	v_cvt_pk_bf16_f32 v62, v204, v205
	v_cvt_pk_bf16_f32 v63, v206, v207
	v_pk_fma_f32 v[212:213], v[106:107], v[54:55], v[110:111]
	v_pk_fma_f32 v[214:215], v[108:109], v[56:57], v[112:113]
	s_nop 2
	v_mov_b32_dpp v204, v54 row_shr:1 row_mask:0xf bank_mask:0xf
	v_mov_b32_dpp v208, v54 row_shr:2 row_mask:0xf bank_mask:0xf
	v_mov_b32_dpp v205, v55 row_shr:1 row_mask:0xf bank_mask:0xf
	v_mov_b32_dpp v209, v55 row_shr:2 row_mask:0xf bank_mask:0xf
	v_mov_b32_dpp v206, v56 row_shr:1 row_mask:0xf bank_mask:0xf
	v_mov_b32_dpp v210, v56 row_shr:2 row_mask:0xf bank_mask:0xf
	v_mov_b32_dpp v207, v57 row_shr:1 row_mask:0xf bank_mask:0xf
	v_mov_b32_dpp v211, v57 row_shr:2 row_mask:0xf bank_mask:0xf
	s_waitcnt vmcnt(3)
	v_mov_b32_dpp v223, v170 row_shl:1 row_mask:0xf bank_mask:0xf
	v_mov_b32_dpp v224, v171 row_shl:1 row_mask:0xf bank_mask:0xf
	v_mov_b32_dpp v225, v172 row_shl:1 row_mask:0xf bank_mask:0xf
	v_mov_b32_dpp v226, v173 row_shl:1 row_mask:0xf bank_mask:0xf
	v_cndmask_b32_e64 v208, v208, v170, s[48:49]
	v_cndmask_b32_e64 v209, v209, v171, s[48:49]
	v_cndmask_b32_e64 v210, v210, v172, s[48:49]
	v_cndmask_b32_e64 v211, v211, v173, s[48:49]
	v_cndmask_b32_e64 v204, v204, v223, s[46:47]
	v_cndmask_b32_e64 v205, v205, v224, s[46:47]
	v_cndmask_b32_e64 v206, v206, v225, s[46:47]
	v_cndmask_b32_e64 v207, v207, v226, s[46:47]
	s_mov_b64 exec, s[48:49]
	v_add_u32_e32 v222, 0x42000, v190
	global_load_dwordx4 v[170:173], v222, s[16:17] offset:16
	s_mov_b64 exec, -1
	v_pk_fma_f32 v[212:213], v[102:103], v[204:205], v[212:213]
	v_pk_fma_f32 v[214:215], v[104:105], v[206:207], v[214:215]
	v_pk_fma_f32 v[212:213], v[98:99], v[208:209], v[212:213]
	v_pk_fma_f32 v[214:215], v[100:101], v[210:211], v[214:215]
	v_pk_fma_f32 v[216:217], v[122:123], v[50:51], v[126:127]
	v_pk_fma_f32 v[218:219], v[124:125], v[52:53], v[128:129]
	s_nop 2
	v_mov_b32_dpp v204, v50 row_shr:1 row_mask:0xf bank_mask:0xf
	v_mov_b32_dpp v208, v50 row_shr:2 row_mask:0xf bank_mask:0xf
	v_mov_b32_dpp v205, v51 row_shr:1 row_mask:0xf bank_mask:0xf
	v_mov_b32_dpp v209, v51 row_shr:2 row_mask:0xf bank_mask:0xf
	v_mov_b32_dpp v206, v52 row_shr:1 row_mask:0xf bank_mask:0xf
	v_mov_b32_dpp v210, v52 row_shr:2 row_mask:0xf bank_mask:0xf
	v_mov_b32_dpp v207, v53 row_shr:1 row_mask:0xf bank_mask:0xf
	v_mov_b32_dpp v211, v53 row_shr:2 row_mask:0xf bank_mask:0xf
	s_waitcnt vmcnt(3)
	v_mov_b32_dpp v223, v174 row_shl:1 row_mask:0xf bank_mask:0xf
	v_mov_b32_dpp v224, v175 row_shl:1 row_mask:0xf bank_mask:0xf
	v_mov_b32_dpp v225, v176 row_shl:1 row_mask:0xf bank_mask:0xf
	v_mov_b32_dpp v226, v177 row_shl:1 row_mask:0xf bank_mask:0xf
	v_cndmask_b32_e64 v208, v208, v174, s[48:49]
	v_cndmask_b32_e64 v209, v209, v175, s[48:49]
	v_cndmask_b32_e64 v210, v210, v176, s[48:49]
	v_cndmask_b32_e64 v211, v211, v177, s[48:49]
	v_cndmask_b32_e64 v204, v204, v223, s[46:47]
	v_cndmask_b32_e64 v205, v205, v224, s[46:47]
	v_cndmask_b32_e64 v206, v206, v225, s[46:47]
	v_cndmask_b32_e64 v207, v207, v226, s[46:47]
	s_mov_b64 exec, s[48:49]
	v_add_u32_e32 v222, 0x44c00, v190
	global_load_dwordx4 v[174:177], v222, s[16:17] offset:16
	s_mov_b64 exec, -1
	v_pk_fma_f32 v[216:217], v[118:119], v[204:205], v[216:217]
	v_pk_fma_f32 v[218:219], v[120:121], v[206:207], v[218:219]
	v_pk_fma_f32 v[216:217], v[114:115], v[208:209], v[216:217]
	v_pk_fma_f32 v[218:219], v[116:117], v[210:211], v[218:219]
	v_mul_f32_e32 v204, 0xbfb8aa3b, v216
	v_mul_f32_e32 v205, 0xbfb8aa3b, v217
	v_mul_f32_e32 v206, 0xbfb8aa3b, v218
	v_mul_f32_e32 v207, 0xbfb8aa3b, v219
	v_exp_f32_e32 v204, v204
	v_exp_f32_e32 v205, v205
	v_exp_f32_e32 v206, v206
	v_exp_f32_e32 v207, v207
	v_add_f32_e32 v204, 1.0, v204
	v_add_f32_e32 v205, 1.0, v205
	v_add_f32_e32 v206, 1.0, v206
	v_add_f32_e32 v207, 1.0, v207
	v_rcp_f32_e32 v204, v204
	v_rcp_f32_e32 v205, v205
	v_rcp_f32_e32 v206, v206
	v_rcp_f32_e32 v207, v207
	v_mul_f32_e32 v204, v216, v204
	v_mul_f32_e32 v205, v217, v205
	v_mul_f32_e32 v206, v218, v206
	v_mul_f32_e32 v207, v219, v207
	v_mul_f32_e32 v204, v212, v204
	v_mul_f32_e32 v205, v213, v205
	v_mul_f32_e32 v206, v214, v206
	v_mul_f32_e32 v207, v215, v207
	v_cvt_pk_bf16_f32 v54, v204, v205
	v_cvt_pk_bf16_f32 v55, v206, v207
	v_pk_fma_f32 v[212:213], v[106:107], v[46:47], v[110:111]
	v_pk_fma_f32 v[214:215], v[108:109], v[48:49], v[112:113]
	s_nop 2
	v_mov_b32_dpp v204, v46 row_shr:1 row_mask:0xf bank_mask:0xf
	v_mov_b32_dpp v208, v46 row_shr:2 row_mask:0xf bank_mask:0xf
	v_mov_b32_dpp v205, v47 row_shr:1 row_mask:0xf bank_mask:0xf
	v_mov_b32_dpp v209, v47 row_shr:2 row_mask:0xf bank_mask:0xf
	v_mov_b32_dpp v206, v48 row_shr:1 row_mask:0xf bank_mask:0xf
	v_mov_b32_dpp v210, v48 row_shr:2 row_mask:0xf bank_mask:0xf
	v_mov_b32_dpp v207, v49 row_shr:1 row_mask:0xf bank_mask:0xf
	v_mov_b32_dpp v211, v49 row_shr:2 row_mask:0xf bank_mask:0xf
	s_waitcnt vmcnt(3)
	v_mov_b32_dpp v223, v162 row_shl:1 row_mask:0xf bank_mask:0xf
	v_mov_b32_dpp v224, v163 row_shl:1 row_mask:0xf bank_mask:0xf
	v_mov_b32_dpp v225, v164 row_shl:1 row_mask:0xf bank_mask:0xf
	v_mov_b32_dpp v226, v165 row_shl:1 row_mask:0xf bank_mask:0xf
	v_cndmask_b32_e64 v208, v208, v162, s[48:49]
	v_cndmask_b32_e64 v209, v209, v163, s[48:49]
	v_cndmask_b32_e64 v210, v210, v164, s[48:49]
	v_cndmask_b32_e64 v211, v211, v165, s[48:49]
	v_cndmask_b32_e64 v204, v204, v223, s[46:47]
	v_cndmask_b32_e64 v205, v205, v224, s[46:47]
	v_cndmask_b32_e64 v206, v206, v225, s[46:47]
	v_cndmask_b32_e64 v207, v207, v226, s[46:47]
	s_mov_b64 exec, s[48:49]
	v_add_u32_e32 v222, 0xb0000, v190
	global_load_dwordx4 v[162:165], v222, s[16:17] offset:16
	s_mov_b64 exec, -1
	v_pk_fma_f32 v[212:213], v[102:103], v[204:205], v[212:213]
	v_pk_fma_f32 v[214:215], v[104:105], v[206:207], v[214:215]
	v_pk_fma_f32 v[212:213], v[98:99], v[208:209], v[212:213]
	v_pk_fma_f32 v[214:215], v[100:101], v[210:211], v[214:215]
	v_pk_fma_f32 v[216:217], v[122:123], v[42:43], v[126:127]
	v_pk_fma_f32 v[218:219], v[124:125], v[44:45], v[128:129]
	s_nop 2
	v_mov_b32_dpp v204, v42 row_shr:1 row_mask:0xf bank_mask:0xf
	v_mov_b32_dpp v208, v42 row_shr:2 row_mask:0xf bank_mask:0xf
	v_mov_b32_dpp v205, v43 row_shr:1 row_mask:0xf bank_mask:0xf
	v_mov_b32_dpp v209, v43 row_shr:2 row_mask:0xf bank_mask:0xf
	v_mov_b32_dpp v206, v44 row_shr:1 row_mask:0xf bank_mask:0xf
	v_mov_b32_dpp v210, v44 row_shr:2 row_mask:0xf bank_mask:0xf
	v_mov_b32_dpp v207, v45 row_shr:1 row_mask:0xf bank_mask:0xf
	v_mov_b32_dpp v211, v45 row_shr:2 row_mask:0xf bank_mask:0xf
	s_waitcnt vmcnt(3)
	v_mov_b32_dpp v223, v166 row_shl:1 row_mask:0xf bank_mask:0xf
	v_mov_b32_dpp v224, v167 row_shl:1 row_mask:0xf bank_mask:0xf
	v_mov_b32_dpp v225, v168 row_shl:1 row_mask:0xf bank_mask:0xf
	v_mov_b32_dpp v226, v169 row_shl:1 row_mask:0xf bank_mask:0xf
	v_cndmask_b32_e64 v208, v208, v166, s[48:49]
	v_cndmask_b32_e64 v209, v209, v167, s[48:49]
	v_cndmask_b32_e64 v210, v210, v168, s[48:49]
	v_cndmask_b32_e64 v211, v211, v169, s[48:49]
	v_cndmask_b32_e64 v204, v204, v223, s[46:47]
	v_cndmask_b32_e64 v205, v205, v224, s[46:47]
	v_cndmask_b32_e64 v206, v206, v225, s[46:47]
	v_cndmask_b32_e64 v207, v207, v226, s[46:47]
	s_mov_b64 exec, s[48:49]
	v_add_u32_e32 v222, 0xb2c00, v190
	global_load_dwordx4 v[166:169], v222, s[16:17] offset:16
	s_mov_b64 exec, -1
	v_pk_fma_f32 v[216:217], v[118:119], v[204:205], v[216:217]
	v_pk_fma_f32 v[218:219], v[120:121], v[206:207], v[218:219]
	v_pk_fma_f32 v[216:217], v[114:115], v[208:209], v[216:217]
	v_pk_fma_f32 v[218:219], v[116:117], v[210:211], v[218:219]
	v_mul_f32_e32 v204, 0xbfb8aa3b, v216
	v_mul_f32_e32 v205, 0xbfb8aa3b, v217
	v_mul_f32_e32 v206, 0xbfb8aa3b, v218
	v_mul_f32_e32 v207, 0xbfb8aa3b, v219
	v_exp_f32_e32 v204, v204
	v_exp_f32_e32 v205, v205
	v_exp_f32_e32 v206, v206
	v_exp_f32_e32 v207, v207
	v_add_f32_e32 v204, 1.0, v204
	v_add_f32_e32 v205, 1.0, v205
	v_add_f32_e32 v206, 1.0, v206
	v_add_f32_e32 v207, 1.0, v207
	v_rcp_f32_e32 v204, v204
	v_rcp_f32_e32 v205, v205
	v_rcp_f32_e32 v206, v206
	v_rcp_f32_e32 v207, v207
	v_mul_f32_e32 v204, v216, v204
	v_mul_f32_e32 v205, v217, v205
	v_mul_f32_e32 v206, v218, v206
	v_mul_f32_e32 v207, v219, v207
	v_mul_f32_e32 v204, v212, v204
	v_mul_f32_e32 v205, v213, v205
	v_mul_f32_e32 v206, v214, v206
	v_mul_f32_e32 v207, v215, v207
	v_cvt_pk_bf16_f32 v46, v204, v205
	v_cvt_pk_bf16_f32 v47, v206, v207
	v_pk_fma_f32 v[212:213], v[106:107], v[38:39], v[110:111]
	v_pk_fma_f32 v[214:215], v[108:109], v[40:41], v[112:113]
	s_nop 2
	v_mov_b32_dpp v204, v38 row_shr:1 row_mask:0xf bank_mask:0xf
	v_mov_b32_dpp v208, v38 row_shr:2 row_mask:0xf bank_mask:0xf
	v_mov_b32_dpp v205, v39 row_shr:1 row_mask:0xf bank_mask:0xf
	v_mov_b32_dpp v209, v39 row_shr:2 row_mask:0xf bank_mask:0xf
	v_mov_b32_dpp v206, v40 row_shr:1 row_mask:0xf bank_mask:0xf
	v_mov_b32_dpp v210, v40 row_shr:2 row_mask:0xf bank_mask:0xf
	v_mov_b32_dpp v207, v41 row_shr:1 row_mask:0xf bank_mask:0xf
	v_mov_b32_dpp v211, v41 row_shr:2 row_mask:0xf bank_mask:0xf
	s_waitcnt vmcnt(3)
	v_mov_b32_dpp v223, v170 row_shl:1 row_mask:0xf bank_mask:0xf
	v_mov_b32_dpp v224, v171 row_shl:1 row_mask:0xf bank_mask:0xf
	v_mov_b32_dpp v225, v172 row_shl:1 row_mask:0xf bank_mask:0xf
	v_mov_b32_dpp v226, v173 row_shl:1 row_mask:0xf bank_mask:0xf
	v_cndmask_b32_e64 v208, v208, v170, s[48:49]
	v_cndmask_b32_e64 v209, v209, v171, s[48:49]
	v_cndmask_b32_e64 v210, v210, v172, s[48:49]
	v_cndmask_b32_e64 v211, v211, v173, s[48:49]
	v_cndmask_b32_e64 v204, v204, v223, s[46:47]
	v_cndmask_b32_e64 v205, v205, v224, s[46:47]
	v_cndmask_b32_e64 v206, v206, v225, s[46:47]
	v_cndmask_b32_e64 v207, v207, v226, s[46:47]
	s_mov_b64 exec, s[48:49]
	v_add_u32_e32 v222, 0xc6000, v190
	global_load_dwordx4 v[170:173], v222, s[16:17] offset:16
	s_mov_b64 exec, -1
	v_pk_fma_f32 v[212:213], v[102:103], v[204:205], v[212:213]
	v_pk_fma_f32 v[214:215], v[104:105], v[206:207], v[214:215]
	v_pk_fma_f32 v[212:213], v[98:99], v[208:209], v[212:213]
	v_pk_fma_f32 v[214:215], v[100:101], v[210:211], v[214:215]
	v_pk_fma_f32 v[216:217], v[122:123], v[34:35], v[126:127]
	v_pk_fma_f32 v[218:219], v[124:125], v[36:37], v[128:129]
	s_nop 2
	v_mov_b32_dpp v204, v34 row_shr:1 row_mask:0xf bank_mask:0xf
	v_mov_b32_dpp v208, v34 row_shr:2 row_mask:0xf bank_mask:0xf
	v_mov_b32_dpp v205, v35 row_shr:1 row_mask:0xf bank_mask:0xf
	v_mov_b32_dpp v209, v35 row_shr:2 row_mask:0xf bank_mask:0xf
	v_mov_b32_dpp v206, v36 row_shr:1 row_mask:0xf bank_mask:0xf
	v_mov_b32_dpp v210, v36 row_shr:2 row_mask:0xf bank_mask:0xf
	v_mov_b32_dpp v207, v37 row_shr:1 row_mask:0xf bank_mask:0xf
	v_mov_b32_dpp v211, v37 row_shr:2 row_mask:0xf bank_mask:0xf
	s_waitcnt vmcnt(3)
	v_mov_b32_dpp v223, v174 row_shl:1 row_mask:0xf bank_mask:0xf
	v_mov_b32_dpp v224, v175 row_shl:1 row_mask:0xf bank_mask:0xf
	v_mov_b32_dpp v225, v176 row_shl:1 row_mask:0xf bank_mask:0xf
	v_mov_b32_dpp v226, v177 row_shl:1 row_mask:0xf bank_mask:0xf
	v_cndmask_b32_e64 v208, v208, v174, s[48:49]
	v_cndmask_b32_e64 v209, v209, v175, s[48:49]
	v_cndmask_b32_e64 v210, v210, v176, s[48:49]
	v_cndmask_b32_e64 v211, v211, v177, s[48:49]
	v_cndmask_b32_e64 v204, v204, v223, s[46:47]
	v_cndmask_b32_e64 v205, v205, v224, s[46:47]
	v_cndmask_b32_e64 v206, v206, v225, s[46:47]
	v_cndmask_b32_e64 v207, v207, v226, s[46:47]
	s_mov_b64 exec, s[48:49]
	v_add_u32_e32 v222, 0xc8c00, v190
	global_load_dwordx4 v[174:177], v222, s[16:17] offset:16
	s_mov_b64 exec, -1
	v_pk_fma_f32 v[216:217], v[118:119], v[204:205], v[216:217]
	v_pk_fma_f32 v[218:219], v[120:121], v[206:207], v[218:219]
	v_pk_fma_f32 v[216:217], v[114:115], v[208:209], v[216:217]
	v_pk_fma_f32 v[218:219], v[116:117], v[210:211], v[218:219]
	v_mul_f32_e32 v204, 0xbfb8aa3b, v216
	v_mul_f32_e32 v205, 0xbfb8aa3b, v217
	v_mul_f32_e32 v206, 0xbfb8aa3b, v218
	v_mul_f32_e32 v207, 0xbfb8aa3b, v219
	v_exp_f32_e32 v204, v204
	v_exp_f32_e32 v205, v205
	v_exp_f32_e32 v206, v206
	v_exp_f32_e32 v207, v207
	v_add_f32_e32 v204, 1.0, v204
	v_add_f32_e32 v205, 1.0, v205
	v_add_f32_e32 v206, 1.0, v206
	v_add_f32_e32 v207, 1.0, v207
	v_rcp_f32_e32 v204, v204
	v_rcp_f32_e32 v205, v205
	v_rcp_f32_e32 v206, v206
	v_rcp_f32_e32 v207, v207
	v_mul_f32_e32 v204, v216, v204
	v_mul_f32_e32 v205, v217, v205
	v_mul_f32_e32 v206, v218, v206
	v_mul_f32_e32 v207, v219, v207
	v_mul_f32_e32 v204, v212, v204
	v_mul_f32_e32 v205, v213, v205
	v_mul_f32_e32 v206, v214, v206
	v_mul_f32_e32 v207, v215, v207
	v_cvt_pk_bf16_f32 v38, v204, v205
	v_cvt_pk_bf16_f32 v39, v206, v207
	v_pk_fma_f32 v[212:213], v[106:107], v[30:31], v[110:111]
	v_pk_fma_f32 v[214:215], v[108:109], v[32:33], v[112:113]
	s_nop 2
	v_mov_b32_dpp v204, v30 row_shr:1 row_mask:0xf bank_mask:0xf
	v_mov_b32_dpp v208, v30 row_shr:2 row_mask:0xf bank_mask:0xf
	v_mov_b32_dpp v205, v31 row_shr:1 row_mask:0xf bank_mask:0xf
	v_mov_b32_dpp v209, v31 row_shr:2 row_mask:0xf bank_mask:0xf
	v_mov_b32_dpp v206, v32 row_shr:1 row_mask:0xf bank_mask:0xf
	v_mov_b32_dpp v210, v32 row_shr:2 row_mask:0xf bank_mask:0xf
	v_mov_b32_dpp v207, v33 row_shr:1 row_mask:0xf bank_mask:0xf
	v_mov_b32_dpp v211, v33 row_shr:2 row_mask:0xf bank_mask:0xf
	s_waitcnt vmcnt(3)
	v_mov_b32_dpp v223, v162 row_shl:1 row_mask:0xf bank_mask:0xf
	v_mov_b32_dpp v224, v163 row_shl:1 row_mask:0xf bank_mask:0xf
	v_mov_b32_dpp v225, v164 row_shl:1 row_mask:0xf bank_mask:0xf
	v_mov_b32_dpp v226, v165 row_shl:1 row_mask:0xf bank_mask:0xf
	v_cndmask_b32_e64 v208, v208, v162, s[48:49]
	v_cndmask_b32_e64 v209, v209, v163, s[48:49]
	v_cndmask_b32_e64 v210, v210, v164, s[48:49]
	v_cndmask_b32_e64 v211, v211, v165, s[48:49]
	v_cndmask_b32_e64 v204, v204, v223, s[46:47]
	v_cndmask_b32_e64 v205, v205, v224, s[46:47]
	v_cndmask_b32_e64 v206, v206, v225, s[46:47]
	v_cndmask_b32_e64 v207, v207, v226, s[46:47]
	s_mov_b64 exec, s[48:49]
	v_add_u32_e32 v222, 0xdc000, v190
	global_load_dwordx4 v[162:165], v222, s[16:17] offset:16
	s_mov_b64 exec, -1
	v_pk_fma_f32 v[212:213], v[102:103], v[204:205], v[212:213]
	v_pk_fma_f32 v[214:215], v[104:105], v[206:207], v[214:215]
	v_pk_fma_f32 v[212:213], v[98:99], v[208:209], v[212:213]
	v_pk_fma_f32 v[214:215], v[100:101], v[210:211], v[214:215]
	v_pk_fma_f32 v[216:217], v[122:123], v[26:27], v[126:127]
	v_pk_fma_f32 v[218:219], v[124:125], v[28:29], v[128:129]
	s_nop 2
	v_mov_b32_dpp v204, v26 row_shr:1 row_mask:0xf bank_mask:0xf
	v_mov_b32_dpp v208, v26 row_shr:2 row_mask:0xf bank_mask:0xf
	v_mov_b32_dpp v205, v27 row_shr:1 row_mask:0xf bank_mask:0xf
	v_mov_b32_dpp v209, v27 row_shr:2 row_mask:0xf bank_mask:0xf
	v_mov_b32_dpp v206, v28 row_shr:1 row_mask:0xf bank_mask:0xf
	v_mov_b32_dpp v210, v28 row_shr:2 row_mask:0xf bank_mask:0xf
	v_mov_b32_dpp v207, v29 row_shr:1 row_mask:0xf bank_mask:0xf
	v_mov_b32_dpp v211, v29 row_shr:2 row_mask:0xf bank_mask:0xf
	s_waitcnt vmcnt(3)
	v_mov_b32_dpp v223, v166 row_shl:1 row_mask:0xf bank_mask:0xf
	v_mov_b32_dpp v224, v167 row_shl:1 row_mask:0xf bank_mask:0xf
	v_mov_b32_dpp v225, v168 row_shl:1 row_mask:0xf bank_mask:0xf
	v_mov_b32_dpp v226, v169 row_shl:1 row_mask:0xf bank_mask:0xf
	v_cndmask_b32_e64 v208, v208, v166, s[48:49]
	v_cndmask_b32_e64 v209, v209, v167, s[48:49]
	v_cndmask_b32_e64 v210, v210, v168, s[48:49]
	v_cndmask_b32_e64 v211, v211, v169, s[48:49]
	v_cndmask_b32_e64 v204, v204, v223, s[46:47]
	v_cndmask_b32_e64 v205, v205, v224, s[46:47]
	v_cndmask_b32_e64 v206, v206, v225, s[46:47]
	v_cndmask_b32_e64 v207, v207, v226, s[46:47]
	s_mov_b64 exec, s[48:49]
	v_add_u32_e32 v222, 0xdec00, v190
	global_load_dwordx4 v[166:169], v222, s[16:17] offset:16
	s_mov_b64 exec, -1
	v_pk_fma_f32 v[216:217], v[118:119], v[204:205], v[216:217]
	v_pk_fma_f32 v[218:219], v[120:121], v[206:207], v[218:219]
	v_pk_fma_f32 v[216:217], v[114:115], v[208:209], v[216:217]
	v_pk_fma_f32 v[218:219], v[116:117], v[210:211], v[218:219]
	v_mul_f32_e32 v204, 0xbfb8aa3b, v216
	v_mul_f32_e32 v205, 0xbfb8aa3b, v217
	v_mul_f32_e32 v206, 0xbfb8aa3b, v218
	v_mul_f32_e32 v207, 0xbfb8aa3b, v219
	v_exp_f32_e32 v204, v204
	v_exp_f32_e32 v205, v205
	v_exp_f32_e32 v206, v206
	v_exp_f32_e32 v207, v207
	v_add_f32_e32 v204, 1.0, v204
	v_add_f32_e32 v205, 1.0, v205
	v_add_f32_e32 v206, 1.0, v206
	v_add_f32_e32 v207, 1.0, v207
	v_rcp_f32_e32 v204, v204
	v_rcp_f32_e32 v205, v205
	v_rcp_f32_e32 v206, v206
	v_rcp_f32_e32 v207, v207
	v_mul_f32_e32 v204, v216, v204
	v_mul_f32_e32 v205, v217, v205
	v_mul_f32_e32 v206, v218, v206
	v_mul_f32_e32 v207, v219, v207
	v_mul_f32_e32 v204, v212, v204
	v_mul_f32_e32 v205, v213, v205
	v_mul_f32_e32 v206, v214, v206
	v_mul_f32_e32 v207, v215, v207
	v_cvt_pk_bf16_f32 v30, v204, v205
	v_cvt_pk_bf16_f32 v31, v206, v207
	v_pk_fma_f32 v[212:213], v[106:107], v[22:23], v[110:111]
	v_pk_fma_f32 v[214:215], v[108:109], v[24:25], v[112:113]
	s_nop 2
	v_mov_b32_dpp v204, v22 row_shr:1 row_mask:0xf bank_mask:0xf
	v_mov_b32_dpp v208, v22 row_shr:2 row_mask:0xf bank_mask:0xf
	v_mov_b32_dpp v205, v23 row_shr:1 row_mask:0xf bank_mask:0xf
	v_mov_b32_dpp v209, v23 row_shr:2 row_mask:0xf bank_mask:0xf
	v_mov_b32_dpp v206, v24 row_shr:1 row_mask:0xf bank_mask:0xf
	v_mov_b32_dpp v210, v24 row_shr:2 row_mask:0xf bank_mask:0xf
	v_mov_b32_dpp v207, v25 row_shr:1 row_mask:0xf bank_mask:0xf
	v_mov_b32_dpp v211, v25 row_shr:2 row_mask:0xf bank_mask:0xf
	s_waitcnt vmcnt(3)
	v_mov_b32_dpp v223, v170 row_shl:1 row_mask:0xf bank_mask:0xf
	v_mov_b32_dpp v224, v171 row_shl:1 row_mask:0xf bank_mask:0xf
	v_mov_b32_dpp v225, v172 row_shl:1 row_mask:0xf bank_mask:0xf
	v_mov_b32_dpp v226, v173 row_shl:1 row_mask:0xf bank_mask:0xf
	v_cndmask_b32_e64 v208, v208, v170, s[48:49]
	v_cndmask_b32_e64 v209, v209, v171, s[48:49]
	v_cndmask_b32_e64 v210, v210, v172, s[48:49]
	v_cndmask_b32_e64 v211, v211, v173, s[48:49]
	v_cndmask_b32_e64 v204, v204, v223, s[46:47]
	v_cndmask_b32_e64 v205, v205, v224, s[46:47]
	v_cndmask_b32_e64 v206, v206, v225, s[46:47]
	v_cndmask_b32_e64 v207, v207, v226, s[46:47]
	s_mov_b64 exec, s[48:49]
	v_add_u32_e32 v222, 0xf2000, v190
	global_load_dwordx4 v[170:173], v222, s[16:17] offset:16
	s_mov_b64 exec, -1
	v_pk_fma_f32 v[212:213], v[102:103], v[204:205], v[212:213]
	v_pk_fma_f32 v[214:215], v[104:105], v[206:207], v[214:215]
	v_pk_fma_f32 v[212:213], v[98:99], v[208:209], v[212:213]
	v_pk_fma_f32 v[214:215], v[100:101], v[210:211], v[214:215]
	v_pk_fma_f32 v[216:217], v[122:123], v[18:19], v[126:127]
	v_pk_fma_f32 v[218:219], v[124:125], v[20:21], v[128:129]
	s_nop 2
	v_mov_b32_dpp v204, v18 row_shr:1 row_mask:0xf bank_mask:0xf
	v_mov_b32_dpp v208, v18 row_shr:2 row_mask:0xf bank_mask:0xf
	v_mov_b32_dpp v205, v19 row_shr:1 row_mask:0xf bank_mask:0xf
	v_mov_b32_dpp v209, v19 row_shr:2 row_mask:0xf bank_mask:0xf
	v_mov_b32_dpp v206, v20 row_shr:1 row_mask:0xf bank_mask:0xf
	v_mov_b32_dpp v210, v20 row_shr:2 row_mask:0xf bank_mask:0xf
	v_mov_b32_dpp v207, v21 row_shr:1 row_mask:0xf bank_mask:0xf
	v_mov_b32_dpp v211, v21 row_shr:2 row_mask:0xf bank_mask:0xf
	s_waitcnt vmcnt(3)
	v_mov_b32_dpp v223, v174 row_shl:1 row_mask:0xf bank_mask:0xf
	v_mov_b32_dpp v224, v175 row_shl:1 row_mask:0xf bank_mask:0xf
	v_mov_b32_dpp v225, v176 row_shl:1 row_mask:0xf bank_mask:0xf
	v_mov_b32_dpp v226, v177 row_shl:1 row_mask:0xf bank_mask:0xf
	v_cndmask_b32_e64 v208, v208, v174, s[48:49]
	v_cndmask_b32_e64 v209, v209, v175, s[48:49]
	v_cndmask_b32_e64 v210, v210, v176, s[48:49]
	v_cndmask_b32_e64 v211, v211, v177, s[48:49]
	v_cndmask_b32_e64 v204, v204, v223, s[46:47]
	v_cndmask_b32_e64 v205, v205, v224, s[46:47]
	v_cndmask_b32_e64 v206, v206, v225, s[46:47]
	v_cndmask_b32_e64 v207, v207, v226, s[46:47]
	s_mov_b64 exec, s[48:49]
	v_add_u32_e32 v222, 0xf4c00, v190
	global_load_dwordx4 v[174:177], v222, s[16:17] offset:16
	s_mov_b64 exec, -1
	v_pk_fma_f32 v[216:217], v[118:119], v[204:205], v[216:217]
	v_pk_fma_f32 v[218:219], v[120:121], v[206:207], v[218:219]
	v_pk_fma_f32 v[216:217], v[114:115], v[208:209], v[216:217]
	v_pk_fma_f32 v[218:219], v[116:117], v[210:211], v[218:219]
	v_mul_f32_e32 v204, 0xbfb8aa3b, v216
	v_mul_f32_e32 v205, 0xbfb8aa3b, v217
	v_mul_f32_e32 v206, 0xbfb8aa3b, v218
	v_mul_f32_e32 v207, 0xbfb8aa3b, v219
	v_exp_f32_e32 v204, v204
	v_exp_f32_e32 v205, v205
	v_exp_f32_e32 v206, v206
	v_exp_f32_e32 v207, v207
	v_add_f32_e32 v204, 1.0, v204
	v_add_f32_e32 v205, 1.0, v205
	v_add_f32_e32 v206, 1.0, v206
	v_add_f32_e32 v207, 1.0, v207
	v_rcp_f32_e32 v204, v204
	v_rcp_f32_e32 v205, v205
	v_rcp_f32_e32 v206, v206
	v_rcp_f32_e32 v207, v207
	v_mul_f32_e32 v204, v216, v204
	v_mul_f32_e32 v205, v217, v205
	v_mul_f32_e32 v206, v218, v206
	v_mul_f32_e32 v207, v219, v207
	v_mul_f32_e32 v204, v212, v204
	v_mul_f32_e32 v205, v213, v205
	v_mul_f32_e32 v206, v214, v206
	v_mul_f32_e32 v207, v215, v207
	v_cvt_pk_bf16_f32 v22, v204, v205
	v_cvt_pk_bf16_f32 v23, v206, v207
	v_pk_fma_f32 v[212:213], v[106:107], v[14:15], v[110:111]
	v_pk_fma_f32 v[214:215], v[108:109], v[16:17], v[112:113]
	s_nop 2
	v_mov_b32_dpp v204, v14 row_shr:1 row_mask:0xf bank_mask:0xf
	v_mov_b32_dpp v208, v14 row_shr:2 row_mask:0xf bank_mask:0xf
	v_mov_b32_dpp v205, v15 row_shr:1 row_mask:0xf bank_mask:0xf
	v_mov_b32_dpp v209, v15 row_shr:2 row_mask:0xf bank_mask:0xf
	v_mov_b32_dpp v206, v16 row_shr:1 row_mask:0xf bank_mask:0xf
	v_mov_b32_dpp v210, v16 row_shr:2 row_mask:0xf bank_mask:0xf
	v_mov_b32_dpp v207, v17 row_shr:1 row_mask:0xf bank_mask:0xf
	v_mov_b32_dpp v211, v17 row_shr:2 row_mask:0xf bank_mask:0xf
	s_waitcnt vmcnt(3)
	v_mov_b32_dpp v223, v162 row_shl:1 row_mask:0xf bank_mask:0xf
	v_mov_b32_dpp v224, v163 row_shl:1 row_mask:0xf bank_mask:0xf
	v_mov_b32_dpp v225, v164 row_shl:1 row_mask:0xf bank_mask:0xf
	v_mov_b32_dpp v226, v165 row_shl:1 row_mask:0xf bank_mask:0xf
	v_cndmask_b32_e64 v208, v208, v162, s[48:49]
	v_cndmask_b32_e64 v209, v209, v163, s[48:49]
	v_cndmask_b32_e64 v210, v210, v164, s[48:49]
	v_cndmask_b32_e64 v211, v211, v165, s[48:49]
	v_cndmask_b32_e64 v204, v204, v223, s[46:47]
	v_cndmask_b32_e64 v205, v205, v224, s[46:47]
	v_cndmask_b32_e64 v206, v206, v225, s[46:47]
	v_cndmask_b32_e64 v207, v207, v226, s[46:47]
	v_pk_fma_f32 v[212:213], v[102:103], v[204:205], v[212:213]
	v_pk_fma_f32 v[214:215], v[104:105], v[206:207], v[214:215]
	v_pk_fma_f32 v[212:213], v[98:99], v[208:209], v[212:213]
	v_pk_fma_f32 v[214:215], v[100:101], v[210:211], v[214:215]
	v_pk_fma_f32 v[216:217], v[122:123], v[10:11], v[126:127]
	v_pk_fma_f32 v[218:219], v[124:125], v[12:13], v[128:129]
	s_nop 2
	v_mov_b32_dpp v204, v10 row_shr:1 row_mask:0xf bank_mask:0xf
	v_mov_b32_dpp v208, v10 row_shr:2 row_mask:0xf bank_mask:0xf
	v_mov_b32_dpp v205, v11 row_shr:1 row_mask:0xf bank_mask:0xf
	v_mov_b32_dpp v209, v11 row_shr:2 row_mask:0xf bank_mask:0xf
	v_mov_b32_dpp v206, v12 row_shr:1 row_mask:0xf bank_mask:0xf
	v_mov_b32_dpp v210, v12 row_shr:2 row_mask:0xf bank_mask:0xf
	v_mov_b32_dpp v207, v13 row_shr:1 row_mask:0xf bank_mask:0xf
	v_mov_b32_dpp v211, v13 row_shr:2 row_mask:0xf bank_mask:0xf
	s_waitcnt vmcnt(2)
	v_mov_b32_dpp v223, v166 row_shl:1 row_mask:0xf bank_mask:0xf
	v_mov_b32_dpp v224, v167 row_shl:1 row_mask:0xf bank_mask:0xf
	v_mov_b32_dpp v225, v168 row_shl:1 row_mask:0xf bank_mask:0xf
	v_mov_b32_dpp v226, v169 row_shl:1 row_mask:0xf bank_mask:0xf
	v_cndmask_b32_e64 v208, v208, v166, s[48:49]
	v_cndmask_b32_e64 v209, v209, v167, s[48:49]
	v_cndmask_b32_e64 v210, v210, v168, s[48:49]
	v_cndmask_b32_e64 v211, v211, v169, s[48:49]
	v_cndmask_b32_e64 v204, v204, v223, s[46:47]
	v_cndmask_b32_e64 v205, v205, v224, s[46:47]
	v_cndmask_b32_e64 v206, v206, v225, s[46:47]
	v_cndmask_b32_e64 v207, v207, v226, s[46:47]
	v_pk_fma_f32 v[216:217], v[118:119], v[204:205], v[216:217]
	v_pk_fma_f32 v[218:219], v[120:121], v[206:207], v[218:219]
	v_pk_fma_f32 v[216:217], v[114:115], v[208:209], v[216:217]
	v_pk_fma_f32 v[218:219], v[116:117], v[210:211], v[218:219]
	v_mul_f32_e32 v204, 0xbfb8aa3b, v216
	v_mul_f32_e32 v205, 0xbfb8aa3b, v217
	v_mul_f32_e32 v206, 0xbfb8aa3b, v218
	v_mul_f32_e32 v207, 0xbfb8aa3b, v219
	v_exp_f32_e32 v204, v204
	v_exp_f32_e32 v205, v205
	v_exp_f32_e32 v206, v206
	v_exp_f32_e32 v207, v207
	v_add_f32_e32 v204, 1.0, v204
	v_add_f32_e32 v205, 1.0, v205
	v_add_f32_e32 v206, 1.0, v206
	v_add_f32_e32 v207, 1.0, v207
	v_rcp_f32_e32 v204, v204
	v_rcp_f32_e32 v205, v205
	v_rcp_f32_e32 v206, v206
	v_rcp_f32_e32 v207, v207
	v_mul_f32_e32 v204, v216, v204
	v_mul_f32_e32 v205, v217, v205
	v_mul_f32_e32 v206, v218, v206
	v_mul_f32_e32 v207, v219, v207
	v_mul_f32_e32 v204, v212, v204
	v_mul_f32_e32 v205, v213, v205
	v_mul_f32_e32 v206, v214, v206
	v_mul_f32_e32 v207, v215, v207
	v_cvt_pk_bf16_f32 v14, v204, v205
	v_cvt_pk_bf16_f32 v15, v206, v207
	v_pk_fma_f32 v[212:213], v[106:107], v[6:7], v[110:111]
	v_pk_fma_f32 v[214:215], v[108:109], v[8:9], v[112:113]
	s_nop 2
	v_mov_b32_dpp v204, v6 row_shr:1 row_mask:0xf bank_mask:0xf
	v_mov_b32_dpp v208, v6 row_shr:2 row_mask:0xf bank_mask:0xf
	v_mov_b32_dpp v205, v7 row_shr:1 row_mask:0xf bank_mask:0xf
	v_mov_b32_dpp v209, v7 row_shr:2 row_mask:0xf bank_mask:0xf
	v_mov_b32_dpp v206, v8 row_shr:1 row_mask:0xf bank_mask:0xf
	v_mov_b32_dpp v210, v8 row_shr:2 row_mask:0xf bank_mask:0xf
	v_mov_b32_dpp v207, v9 row_shr:1 row_mask:0xf bank_mask:0xf
	v_mov_b32_dpp v211, v9 row_shr:2 row_mask:0xf bank_mask:0xf
	s_waitcnt vmcnt(1)
	v_mov_b32_dpp v223, v170 row_shl:1 row_mask:0xf bank_mask:0xf
	v_mov_b32_dpp v224, v171 row_shl:1 row_mask:0xf bank_mask:0xf
	v_mov_b32_dpp v225, v172 row_shl:1 row_mask:0xf bank_mask:0xf
	v_mov_b32_dpp v226, v173 row_shl:1 row_mask:0xf bank_mask:0xf
	v_cndmask_b32_e64 v208, v208, v170, s[48:49]
	v_cndmask_b32_e64 v209, v209, v171, s[48:49]
	v_cndmask_b32_e64 v210, v210, v172, s[48:49]
	v_cndmask_b32_e64 v211, v211, v173, s[48:49]
	v_cndmask_b32_e64 v204, v204, v223, s[46:47]
	v_cndmask_b32_e64 v205, v205, v224, s[46:47]
	v_cndmask_b32_e64 v206, v206, v225, s[46:47]
	v_cndmask_b32_e64 v207, v207, v226, s[46:47]
	v_pk_fma_f32 v[212:213], v[102:103], v[204:205], v[212:213]
	v_pk_fma_f32 v[214:215], v[104:105], v[206:207], v[214:215]
	v_pk_fma_f32 v[212:213], v[98:99], v[208:209], v[212:213]
	v_pk_fma_f32 v[214:215], v[100:101], v[210:211], v[214:215]
	v_pk_fma_f32 v[216:217], v[122:123], v[2:3], v[126:127]
	v_pk_fma_f32 v[218:219], v[124:125], v[4:5], v[128:129]
	s_nop 2
	v_mov_b32_dpp v204, v2 row_shr:1 row_mask:0xf bank_mask:0xf
	v_mov_b32_dpp v208, v2 row_shr:2 row_mask:0xf bank_mask:0xf
	v_mov_b32_dpp v205, v3 row_shr:1 row_mask:0xf bank_mask:0xf
	v_mov_b32_dpp v209, v3 row_shr:2 row_mask:0xf bank_mask:0xf
	v_mov_b32_dpp v206, v4 row_shr:1 row_mask:0xf bank_mask:0xf
	v_mov_b32_dpp v210, v4 row_shr:2 row_mask:0xf bank_mask:0xf
	v_mov_b32_dpp v207, v5 row_shr:1 row_mask:0xf bank_mask:0xf
	v_mov_b32_dpp v211, v5 row_shr:2 row_mask:0xf bank_mask:0xf
	s_waitcnt vmcnt(0)
	v_mov_b32_dpp v223, v174 row_shl:1 row_mask:0xf bank_mask:0xf
	v_mov_b32_dpp v224, v175 row_shl:1 row_mask:0xf bank_mask:0xf
	v_mov_b32_dpp v225, v176 row_shl:1 row_mask:0xf bank_mask:0xf
	v_mov_b32_dpp v226, v177 row_shl:1 row_mask:0xf bank_mask:0xf
	v_cndmask_b32_e64 v208, v208, v174, s[48:49]
	v_cndmask_b32_e64 v209, v209, v175, s[48:49]
	v_cndmask_b32_e64 v210, v210, v176, s[48:49]
	v_cndmask_b32_e64 v211, v211, v177, s[48:49]
	v_cndmask_b32_e64 v204, v204, v223, s[46:47]
	v_cndmask_b32_e64 v205, v205, v224, s[46:47]
	v_cndmask_b32_e64 v206, v206, v225, s[46:47]
	v_cndmask_b32_e64 v207, v207, v226, s[46:47]
	v_pk_fma_f32 v[216:217], v[118:119], v[204:205], v[216:217]
	v_pk_fma_f32 v[218:219], v[120:121], v[206:207], v[218:219]
	v_pk_fma_f32 v[216:217], v[114:115], v[208:209], v[216:217]
	v_pk_fma_f32 v[218:219], v[116:117], v[210:211], v[218:219]
	v_mul_f32_e32 v204, 0xbfb8aa3b, v216
	v_mul_f32_e32 v205, 0xbfb8aa3b, v217
	v_mul_f32_e32 v206, 0xbfb8aa3b, v218
	v_mul_f32_e32 v207, 0xbfb8aa3b, v219
	v_exp_f32_e32 v204, v204
	v_exp_f32_e32 v205, v205
	v_exp_f32_e32 v206, v206
	v_exp_f32_e32 v207, v207
	v_add_f32_e32 v204, 1.0, v204
	v_add_f32_e32 v205, 1.0, v205
	v_add_f32_e32 v206, 1.0, v206
	v_add_f32_e32 v207, 1.0, v207
	v_rcp_f32_e32 v204, v204
	v_rcp_f32_e32 v205, v205
	v_rcp_f32_e32 v206, v206
	v_rcp_f32_e32 v207, v207
	v_mul_f32_e32 v204, v216, v204
	v_mul_f32_e32 v205, v217, v205
	v_mul_f32_e32 v206, v218, v206
	v_mul_f32_e32 v207, v219, v207
	v_mul_f32_e32 v204, v212, v204
	v_mul_f32_e32 v205, v213, v205
	v_mul_f32_e32 v206, v214, v206
	v_mul_f32_e32 v207, v215, v207
	v_cvt_pk_bf16_f32 v6, v204, v205
	v_cvt_pk_bf16_f32 v7, v206, v207
	v_add_u32_e32 v204, 0xb0000, v231
	s_mov_b32 exec_lo, 0xfffcfffc
	s_mov_b32 exec_hi, 0xfffcfffc
	global_store_dwordx2 v204, v[94:95], s[36:37]
	s_mov_b64 exec, -1
	v_add_u32_e32 v205, 0xc6000, v231
	global_store_dwordx2 v205, v[86:87], s[36:37]
	v_add_u32_e32 v206, 0xdc000, v231
	global_store_dwordx2 v206, v[78:79], s[36:37]
	v_add_u32_e32 v207, 0xf2000, v231
	global_store_dwordx2 v207, v[70:71], s[36:37]
	v_add_u32_e32 v208, 0x8, v231
	s_mov_b32 exec_lo, 0xfffcfffc
	s_mov_b32 exec_hi, 0xfffcfffc
	global_store_dwordx2 v208, v[62:63], s[36:37]
	s_mov_b64 exec, -1
	v_add_u32_e32 v209, 0x16008, v231
	global_store_dwordx2 v209, v[54:55], s[36:37]
	v_add_u32_e32 v210, 0x2c008, v231
	global_store_dwordx2 v210, v[46:47], s[36:37]
	v_add_u32_e32 v211, 0x42008, v231
	global_store_dwordx2 v211, v[38:39], s[36:37]
	v_add_u32_e32 v204, 0xb0008, v231
	s_mov_b32 exec_lo, 0xfffcfffc
	s_mov_b32 exec_hi, 0xfffcfffc
	global_store_dwordx2 v204, v[30:31], s[36:37]
	s_mov_b64 exec, -1
	v_add_u32_e32 v205, 0xc6008, v231
	global_store_dwordx2 v205, v[22:23], s[36:37]
	v_add_u32_e32 v206, 0xdc008, v231
	global_store_dwordx2 v206, v[14:15], s[36:37]
	v_add_u32_e32 v207, 0xf2008, v231
	global_store_dwordx2 v207, v[6:7], s[36:37]
	s_branch .LBB0_2026

.LBB0_4743:
	ds_read_b128 v[130:133], v228
	ds_read_b128 v[134:137], v228 offset:1024
	ds_read_b128 v[138:141], v228 offset:2048
	ds_read_b128 v[142:145], v228 offset:3072
	s_add_u32 s18, s16, 0xfffc0080
	s_addc_u32 s19, s17, -1
	s_cmp_eq_u32 s26, 12
	s_cselect_b32 s21, s13, s19
	s_cselect_b32 s20, s15, s18
	s_cselect_b32 s19, s22, s25
	s_cselect_b32 s18, s23, s24
	v_lshl_add_u64 v[204:205], s[16:17], 0, v[196:197]
	s_add_i32 m0, s62, 0xc000
	ds_read_b128 v[146:149], v229
	ds_read_b128 v[150:153], v229 offset:1024
	ds_read_b128 v[154:157], v229 offset:2048
	ds_read_b128 v[158:161], v229 offset:3072
	ds_read_b128 v[162:165], v229 offset:4096
	ds_read_b128 v[166:169], v229 offset:5120
	ds_read_b128 v[170:173], v229 offset:6144
	ds_read_b128 v[174:177], v229 offset:7168
	global_load_lds_dwordx4 v[204:205], off
	v_lshl_add_u64 v[204:205], s[16:17], 0, v[198:199]
	s_add_i32 m0, s62, 0xe000
	s_nop 0
	global_load_lds_dwordx4 v[204:205], off
	s_waitcnt lgkmcnt(8)
	s_barrier
	s_waitcnt lgkmcnt(0)
	s_setprio 1
	s_waitcnt lgkmcnt(0)
	v_mfma_f32_16x16x32_bf16 v[126:129], v[130:133], v[146:149], v[126:129]
	v_mfma_f32_16x16x32_bf16 v[62:65], v[138:141], v[146:149], v[62:65]
	v_mfma_f32_16x16x32_bf16 v[118:121], v[130:133], v[154:157], v[118:121]
	v_mfma_f32_16x16x32_bf16 v[54:57], v[138:141], v[154:157], v[54:57]
	v_mfma_f32_16x16x32_bf16 v[110:113], v[130:133], v[162:165], v[110:113]
	v_mfma_f32_16x16x32_bf16 v[46:49], v[138:141], v[162:165], v[46:49]
	v_mfma_f32_16x16x32_bf16 v[102:105], v[130:133], v[170:173], v[102:105]
	v_mfma_f32_16x16x32_bf16 v[38:41], v[138:141], v[170:173], v[38:41]
	v_mfma_f32_16x16x32_bf16 v[126:129], v[134:137], v[150:153], v[126:129]
	v_mfma_f32_16x16x32_bf16 v[62:65], v[142:145], v[150:153], v[62:65]
	v_mfma_f32_16x16x32_bf16 v[118:121], v[134:137], v[158:161], v[118:121]
	v_mfma_f32_16x16x32_bf16 v[54:57], v[142:145], v[158:161], v[54:57]
	v_mfma_f32_16x16x32_bf16 v[110:113], v[134:137], v[166:169], v[110:113]
	v_mfma_f32_16x16x32_bf16 v[46:49], v[142:145], v[166:169], v[46:49]
	v_mfma_f32_16x16x32_bf16 v[102:105], v[134:137], v[174:177], v[102:105]
	v_mfma_f32_16x16x32_bf16 v[38:41], v[142:145], v[174:177], v[38:41]
	s_setprio 0
	s_barrier
	s_add_i32 s27, s33, s1
	v_lshl_add_u64 v[220:221], s[18:19], 0, v[184:185]
	s_mov_b32 m0, s27
	ds_read_b128 v[204:207], v230
	ds_read_b128 v[208:211], v230 offset:1024
	ds_read_b128 v[212:215], v230 offset:2048
	ds_read_b128 v[216:219], v230 offset:3072
	global_load_lds_dwordx4 v[220:221], off
	v_lshl_add_u64 v[222:223], s[18:19], 0, v[188:189]
	s_add_i32 m0, s27, 0x2000
	s_nop 0
	global_load_lds_dwordx4 v[222:223], off
	s_barrier
	s_waitcnt lgkmcnt(0)
	s_setprio 1
	s_waitcnt lgkmcnt(0)
	v_mfma_f32_16x16x32_bf16 v[122:125], v[204:207], v[146:149], v[122:125]
	v_mfma_f32_16x16x32_bf16 v[58:61], v[212:215], v[146:149], v[58:61]
	v_mfma_f32_16x16x32_bf16 v[114:117], v[204:207], v[154:157], v[114:117]
	v_mfma_f32_16x16x32_bf16 v[50:53], v[212:215], v[154:157], v[50:53]
	v_mfma_f32_16x16x32_bf16 v[106:109], v[204:207], v[162:165], v[106:109]
	v_mfma_f32_16x16x32_bf16 v[42:45], v[212:215], v[162:165], v[42:45]
	v_mfma_f32_16x16x32_bf16 v[98:101], v[204:207], v[170:173], v[98:101]
	v_mfma_f32_16x16x32_bf16 v[34:37], v[212:215], v[170:173], v[34:37]
	v_mfma_f32_16x16x32_bf16 v[122:125], v[208:211], v[150:153], v[122:125]
	v_mfma_f32_16x16x32_bf16 v[58:61], v[216:219], v[150:153], v[58:61]
	v_mfma_f32_16x16x32_bf16 v[114:117], v[208:211], v[158:161], v[114:117]
	v_mfma_f32_16x16x32_bf16 v[50:53], v[216:219], v[158:161], v[50:53]
	v_mfma_f32_16x16x32_bf16 v[106:109], v[208:211], v[166:169], v[106:109]
	v_mfma_f32_16x16x32_bf16 v[42:45], v[216:219], v[166:169], v[42:45]
	v_mfma_f32_16x16x32_bf16 v[98:101], v[208:211], v[174:177], v[98:101]
	v_mfma_f32_16x16x32_bf16 v[34:37], v[216:219], v[174:177], v[34:37]
	s_setprio 0
	s_mov_b32 m0, s62
	v_lshl_add_u64 v[224:225], s[20:21], 0, v[182:183]
	s_barrier
	ds_read_b128 v[146:149], v229 offset:16384
	ds_read_b128 v[150:153], v229 offset:17408
	ds_read_b128 v[154:157], v229 offset:18432
	ds_read_b128 v[158:161], v229 offset:19456
	ds_read_b128 v[162:165], v229 offset:20480
	ds_read_b128 v[166:169], v229 offset:21504
	ds_read_b128 v[170:173], v229 offset:22528
	ds_read_b128 v[174:177], v229 offset:23552
	global_load_lds_dwordx4 v[224:225], off
	v_lshl_add_u64 v[232:233], s[20:21], 0, v[186:187]
	s_mov_b32 m0, s63
	s_nop 0
	global_load_lds_dwordx4 v[232:233], off
	s_barrier
	s_waitcnt lgkmcnt(0)
	s_setprio 1
	s_waitcnt lgkmcnt(0)
	v_mfma_f32_16x16x32_bf16 v[94:97], v[130:133], v[146:149], v[94:97]
	v_mfma_f32_16x16x32_bf16 v[30:33], v[138:141], v[146:149], v[30:33]
	v_mfma_f32_16x16x32_bf16 v[86:89], v[130:133], v[154:157], v[86:89]
	v_mfma_f32_16x16x32_bf16 v[22:25], v[138:141], v[154:157], v[22:25]
	v_mfma_f32_16x16x32_bf16 v[78:81], v[130:133], v[162:165], v[78:81]
	v_mfma_f32_16x16x32_bf16 v[14:17], v[138:141], v[162:165], v[14:17]
	v_mfma_f32_16x16x32_bf16 v[70:73], v[130:133], v[170:173], v[70:73]
	v_mfma_f32_16x16x32_bf16 v[6:9], v[138:141], v[170:173], v[6:9]
	v_mfma_f32_16x16x32_bf16 v[94:97], v[134:137], v[150:153], v[94:97]
	v_mfma_f32_16x16x32_bf16 v[30:33], v[142:145], v[150:153], v[30:33]
	v_mfma_f32_16x16x32_bf16 v[86:89], v[134:137], v[158:161], v[86:89]
	v_mfma_f32_16x16x32_bf16 v[22:25], v[142:145], v[158:161], v[22:25]
	v_mfma_f32_16x16x32_bf16 v[78:81], v[134:137], v[166:169], v[78:81]
	v_mfma_f32_16x16x32_bf16 v[14:17], v[142:145], v[166:169], v[14:17]
	v_mfma_f32_16x16x32_bf16 v[70:73], v[134:137], v[174:177], v[70:73]
	v_mfma_f32_16x16x32_bf16 v[6:9], v[142:145], v[174:177], v[6:9]
	s_setprio 0
	s_barrier
	s_add_u32 s28, s18, 0x40000
	s_addc_u32 s29, s19, 0
	s_add_i32 s27, s83, s1
	v_lshl_add_u64 v[130:131], s[28:29], 0, v[184:185]
	s_mov_b32 m0, s27
	s_nop 0
	global_load_lds_dwordx4 v[130:131], off
	v_lshl_add_u64 v[130:131], s[28:29], 0, v[188:189]
	s_add_i32 m0, s27, 0x2000
	s_nop 0
	global_load_lds_dwordx4 v[130:131], off
	s_waitcnt vmcnt(6)
	s_barrier
	s_setprio 1
	v_mfma_f32_16x16x32_bf16 v[90:93], v[204:207], v[146:149], v[90:93]
	v_mfma_f32_16x16x32_bf16 v[26:29], v[212:215], v[146:149], v[26:29]
	v_mfma_f32_16x16x32_bf16 v[82:85], v[204:207], v[154:157], v[82:85]
	v_mfma_f32_16x16x32_bf16 v[18:21], v[212:215], v[154:157], v[18:21]
	v_mfma_f32_16x16x32_bf16 v[74:77], v[204:207], v[162:165], v[74:77]
	v_mfma_f32_16x16x32_bf16 v[10:13], v[212:215], v[162:165], v[10:13]
	v_mfma_f32_16x16x32_bf16 v[66:69], v[204:207], v[170:173], v[66:69]
	v_mfma_f32_16x16x32_bf16 v[2:5], v[212:215], v[170:173], v[2:5]
	v_mfma_f32_16x16x32_bf16 v[90:93], v[208:211], v[150:153], v[90:93]
	v_mfma_f32_16x16x32_bf16 v[26:29], v[216:219], v[150:153], v[26:29]
	v_mfma_f32_16x16x32_bf16 v[82:85], v[208:211], v[158:161], v[82:85]
	v_mfma_f32_16x16x32_bf16 v[18:21], v[216:219], v[158:161], v[18:21]
	v_mfma_f32_16x16x32_bf16 v[74:77], v[208:211], v[166:169], v[74:77]
	v_mfma_f32_16x16x32_bf16 v[10:13], v[216:219], v[166:169], v[10:13]
	v_mfma_f32_16x16x32_bf16 v[66:69], v[208:211], v[174:177], v[66:69]
	v_mfma_f32_16x16x32_bf16 v[2:5], v[216:219], v[174:177], v[2:5]
	s_setprio 0
	s_add_i32 s27, 0, 0x18000
	v_add_u32_e32 v142, s27, v1
	s_barrier
	ds_read_b128 v[130:133], v142
	ds_read_b128 v[134:137], v142 offset:1024
	ds_read_b128 v[138:141], v142 offset:2048
	ds_read_b128 v[142:145], v142 offset:3072
	s_add_u32 s20, s20, 0x40000
	s_addc_u32 s21, s21, 0
	s_mov_b32 m0, s6
	v_lshl_add_u64 v[204:205], s[20:21], 0, v[182:183]
	ds_read_b128 v[146:149], v229 offset:32768
	ds_read_b128 v[150:153], v229 offset:33792
	ds_read_b128 v[154:157], v229 offset:34816
	ds_read_b128 v[158:161], v229 offset:35840
	ds_read_b128 v[162:165], v229 offset:36864
	ds_read_b128 v[166:169], v229 offset:37888
	ds_read_b128 v[170:173], v229 offset:38912
	ds_read_b128 v[174:177], v229 offset:39936
	global_load_lds_dwordx4 v[204:205], off
	v_lshl_add_u64 v[204:205], s[20:21], 0, v[186:187]
	s_mov_b32 m0, s7
	s_nop 0
	global_load_lds_dwordx4 v[204:205], off
	s_waitcnt lgkmcnt(8)
	s_barrier
	s_waitcnt lgkmcnt(0)
	s_setprio 1
	s_waitcnt lgkmcnt(0)
	v_mfma_f32_16x16x32_bf16 v[126:129], v[130:133], v[146:149], v[126:129]
	v_mfma_f32_16x16x32_bf16 v[62:65], v[138:141], v[146:149], v[62:65]
	v_mfma_f32_16x16x32_bf16 v[118:121], v[130:133], v[154:157], v[118:121]
	v_mfma_f32_16x16x32_bf16 v[54:57], v[138:141], v[154:157], v[54:57]
	v_mfma_f32_16x16x32_bf16 v[110:113], v[130:133], v[162:165], v[110:113]
	v_mfma_f32_16x16x32_bf16 v[46:49], v[138:141], v[162:165], v[46:49]
	v_mfma_f32_16x16x32_bf16 v[102:105], v[130:133], v[170:173], v[102:105]
	v_mfma_f32_16x16x32_bf16 v[38:41], v[138:141], v[170:173], v[38:41]
	v_mfma_f32_16x16x32_bf16 v[126:129], v[134:137], v[150:153], v[126:129]
	v_mfma_f32_16x16x32_bf16 v[62:65], v[142:145], v[150:153], v[62:65]
	v_mfma_f32_16x16x32_bf16 v[118:121], v[134:137], v[158:161], v[118:121]
	v_mfma_f32_16x16x32_bf16 v[54:57], v[142:145], v[158:161], v[54:57]
	v_mfma_f32_16x16x32_bf16 v[110:113], v[134:137], v[166:169], v[110:113]
	v_mfma_f32_16x16x32_bf16 v[46:49], v[142:145], v[166:169], v[46:49]
	v_mfma_f32_16x16x32_bf16 v[102:105], v[134:137], v[174:177], v[102:105]
	v_mfma_f32_16x16x32_bf16 v[38:41], v[142:145], v[174:177], v[38:41]
	s_setprio 0
	s_barrier
	s_add_i32 s20, 0, 0x1c000
	s_add_i32 s21, s27, s1
	v_add_u32_e32 v190, s20, v1
	v_lshl_add_u64 v[220:221], v[220:221], 0, s[2:3]
	s_mov_b32 m0, s21
	ds_read_b128 v[204:207], v190
	ds_read_b128 v[208:211], v190 offset:1024
	ds_read_b128 v[212:215], v190 offset:2048
	ds_read_b128 v[216:219], v190 offset:3072
	global_load_lds_dwordx4 v[220:221], off
	v_lshl_add_u64 v[220:221], v[222:223], 0, s[2:3]
	s_add_i32 m0, s21, 0x2000
	s_nop 0
	global_load_lds_dwordx4 v[220:221], off
	s_barrier
	s_waitcnt lgkmcnt(0)
	s_setprio 1
	s_waitcnt lgkmcnt(0)
	v_mfma_f32_16x16x32_bf16 v[122:125], v[204:207], v[146:149], v[122:125]
	v_mfma_f32_16x16x32_bf16 v[58:61], v[212:215], v[146:149], v[58:61]
	v_mfma_f32_16x16x32_bf16 v[114:117], v[204:207], v[154:157], v[114:117]
	v_mfma_f32_16x16x32_bf16 v[50:53], v[212:215], v[154:157], v[50:53]
	v_mfma_f32_16x16x32_bf16 v[106:109], v[204:207], v[162:165], v[106:109]
	v_mfma_f32_16x16x32_bf16 v[42:45], v[212:215], v[162:165], v[42:45]
	v_mfma_f32_16x16x32_bf16 v[98:101], v[204:207], v[170:173], v[98:101]
	v_mfma_f32_16x16x32_bf16 v[34:37], v[212:215], v[170:173], v[34:37]
	v_mfma_f32_16x16x32_bf16 v[122:125], v[208:211], v[150:153], v[122:125]
	v_mfma_f32_16x16x32_bf16 v[58:61], v[216:219], v[150:153], v[58:61]
	v_mfma_f32_16x16x32_bf16 v[114:117], v[208:211], v[158:161], v[114:117]
	v_mfma_f32_16x16x32_bf16 v[50:53], v[216:219], v[158:161], v[50:53]
	v_mfma_f32_16x16x32_bf16 v[106:109], v[208:211], v[166:169], v[106:109]
	v_mfma_f32_16x16x32_bf16 v[42:45], v[216:219], v[166:169], v[42:45]
	v_mfma_f32_16x16x32_bf16 v[98:101], v[208:211], v[174:177], v[98:101]
	v_mfma_f32_16x16x32_bf16 v[34:37], v[216:219], v[174:177], v[34:37]
	s_setprio 0
	s_mov_b32 m0, s80
	v_lshl_add_u64 v[220:221], v[224:225], 0, s[2:3]
	s_barrier
	ds_read_b128 v[146:149], v229 offset:49152
	ds_read_b128 v[150:153], v229 offset:50176
	ds_read_b128 v[154:157], v229 offset:51200
	ds_read_b128 v[158:161], v229 offset:52224
	ds_read_b128 v[162:165], v229 offset:53248
	ds_read_b128 v[166:169], v229 offset:54272
	ds_read_b128 v[170:173], v229 offset:55296
	ds_read_b128 v[174:177], v229 offset:56320
	global_load_lds_dwordx4 v[220:221], off
	v_lshl_add_u64 v[220:221], v[232:233], 0, s[2:3]
	s_mov_b32 m0, s81
	s_nop 0
	global_load_lds_dwordx4 v[220:221], off
	s_barrier
	s_waitcnt lgkmcnt(0)
	s_setprio 1
	s_waitcnt lgkmcnt(0)
	v_mfma_f32_16x16x32_bf16 v[94:97], v[130:133], v[146:149], v[94:97]
	v_mfma_f32_16x16x32_bf16 v[30:33], v[138:141], v[146:149], v[30:33]
	v_mfma_f32_16x16x32_bf16 v[86:89], v[130:133], v[154:157], v[86:89]
	v_mfma_f32_16x16x32_bf16 v[22:25], v[138:141], v[154:157], v[22:25]
	v_mfma_f32_16x16x32_bf16 v[78:81], v[130:133], v[162:165], v[78:81]
	v_mfma_f32_16x16x32_bf16 v[14:17], v[138:141], v[162:165], v[14:17]
	v_mfma_f32_16x16x32_bf16 v[70:73], v[130:133], v[170:173], v[70:73]
	v_mfma_f32_16x16x32_bf16 v[6:9], v[138:141], v[170:173], v[6:9]
	v_mfma_f32_16x16x32_bf16 v[94:97], v[134:137], v[150:153], v[94:97]
	v_mfma_f32_16x16x32_bf16 v[30:33], v[142:145], v[150:153], v[30:33]
	v_mfma_f32_16x16x32_bf16 v[86:89], v[134:137], v[158:161], v[86:89]
	v_mfma_f32_16x16x32_bf16 v[22:25], v[142:145], v[158:161], v[22:25]
	v_mfma_f32_16x16x32_bf16 v[78:81], v[134:137], v[166:169], v[78:81]
	v_mfma_f32_16x16x32_bf16 v[14:17], v[142:145], v[166:169], v[14:17]
	v_mfma_f32_16x16x32_bf16 v[70:73], v[134:137], v[174:177], v[70:73]
	v_mfma_f32_16x16x32_bf16 v[6:9], v[142:145], v[174:177], v[6:9]
	s_setprio 0
	s_barrier
	s_add_u32 s18, s18, 0x40080
	s_addc_u32 s19, s19, 0
	s_add_i32 s20, s20, s1
	v_lshl_add_u64 v[130:131], s[18:19], 0, v[184:185]
	s_mov_b32 m0, s20
	s_nop 0
	global_load_lds_dwordx4 v[130:131], off
	v_lshl_add_u64 v[130:131], s[18:19], 0, v[188:189]
	s_add_i32 m0, s20, 0x2000
	s_nop 0
	global_load_lds_dwordx4 v[130:131], off
	s_waitcnt vmcnt(6)
	s_barrier
	s_setprio 1
	v_mfma_f32_16x16x32_bf16 v[90:93], v[204:207], v[146:149], v[90:93]
	v_mfma_f32_16x16x32_bf16 v[26:29], v[212:215], v[146:149], v[26:29]
	v_mfma_f32_16x16x32_bf16 v[82:85], v[204:207], v[154:157], v[82:85]
	v_mfma_f32_16x16x32_bf16 v[18:21], v[212:215], v[154:157], v[18:21]
	v_mfma_f32_16x16x32_bf16 v[74:77], v[204:207], v[162:165], v[74:77]
	v_mfma_f32_16x16x32_bf16 v[10:13], v[212:215], v[162:165], v[10:13]
	v_mfma_f32_16x16x32_bf16 v[66:69], v[204:207], v[170:173], v[66:69]
	v_mfma_f32_16x16x32_bf16 v[2:5], v[212:215], v[170:173], v[2:5]
	v_mfma_f32_16x16x32_bf16 v[90:93], v[208:211], v[150:153], v[90:93]
	v_mfma_f32_16x16x32_bf16 v[26:29], v[216:219], v[150:153], v[26:29]
	v_mfma_f32_16x16x32_bf16 v[82:85], v[208:211], v[158:161], v[82:85]
	v_mfma_f32_16x16x32_bf16 v[18:21], v[216:219], v[158:161], v[18:21]
	v_mfma_f32_16x16x32_bf16 v[74:77], v[208:211], v[166:169], v[74:77]
	v_mfma_f32_16x16x32_bf16 v[10:13], v[216:219], v[166:169], v[10:13]
	v_mfma_f32_16x16x32_bf16 v[66:69], v[208:211], v[174:177], v[66:69]
	v_mfma_f32_16x16x32_bf16 v[2:5], v[216:219], v[174:177], v[2:5]
	s_setprio 0
	s_add_i32 s26, s26, 2
	s_add_u32 s16, s16, 0x100
	s_addc_u32 s17, s17, 0
	s_add_u32 s24, s24, 0x100
	s_addc_u32 s25, s25, 0
	s_cmp_gt_u32 s26, 13
	s_barrier
	s_cbranch_scc0 .LBB0_4743
	s_mov_b64 s[16:17], -1
	s_cmp_lt_i32 s12, 64
	v_lshl_or_b32 v204, s14, 7, v181
	s_cbranch_scc0 .Lmy_ffnB_sample
	s_load_dwordx2 s[36:37], s[78:79], 0x268
	s_load_dwordx2 s[38:39], s[78:79], 0x2a0
	s_load_dwordx4 s[40:43], s[78:79], 0x70
	s_load_dwordx2 s[44:45], s[78:79], 0x120
	v_and_b32_e32 v204, 15, v248
	v_bfe_u32 v205, v248, 8, 1
	v_bfe_u32 v206, v248, 6, 2
	v_bfe_u32 v207, v248, 4, 2
	v_lshlrev_b32_e32 v206, 5, v206
	v_lshl_or_b32 v206, v207, 3, v206
	s_lshl_b32 s13, s14, 7
	v_add_u32_e32 v206, s13, v206
	s_lshl_b32 s13, s12, 8
	v_lshl_add_u32 v207, v205, 6, v204
	v_add_u32_e32 v207, s13, v207
	v_mul_u32_u24_e32 v231, 0x1600, v207
	v_lshl_add_u32 v231, v206, 1, v231
	v_lshlrev_b32_e32 v232, 2, v206
	s_lshl_b32 s13, s12, 4
	v_lshl_add_u32 v233, v205, 2, s13
	v_add_u32_e32 v208, -12, v204
	v_cmp_gt_u32_e32 vcc, 2, v204
	s_nop 1
	v_cndmask_b32_e32 v208, v208, v204, vcc
	v_add_u32_e32 v233, v233, v208
	v_mul_u32_u24_e32 v233, 0x2c00, v233
	v_lshl_add_u32 v233, v206, 1, v233
	s_lshr_b32 s13, s12, 3
	s_lshl_b32 s13, s13, 1
	s_add_i32 s13, s13, 2
	v_add_u32_e32 v234, s13, v204
	v_mul_u32_u24_e32 v234, 0x5800, v234
	v_lshl_add_u32 v234, v206, 2, v234
	v_readfirstlane_b32 s4, v248
	s_lshr_b32 s4, s4, 8
	s_and_b32 s5, s12, 7
	s_cmp_eq_u32 s5, 7
	s_cselect_b32 s5, 1, 0
	s_and_b32 s5, s5, s4
	s_waitcnt lgkmcnt(0)
	s_add_u32 s40, s40, 0x10800
	s_addc_u32 s41, s41, 0
	s_add_u32 s42, s42, 0x5800
	s_addc_u32 s43, s43, 0
	global_load_dwordx4 v[130:133], v232, s[40:41]
	v_add_u32_e32 v213, 0x5800, v232
	global_load_dwordx4 v[134:137], v213, s[40:41]
	v_add_u32_e32 v214, 0xb000, v232
	global_load_dwordx4 v[138:141], v214, s[40:41]
	global_load_dwordx4 v[142:145], v232, s[42:43]
	v_add_u32_e32 v215, 0x2c00, v232
	global_load_dwordx4 v[146:149], v215, s[40:41]
	v_add_u32_e32 v216, 0x8400, v232
	global_load_dwordx4 v[150:153], v216, s[40:41]
	v_add_u32_e32 v217, 0xdc00, v232
	global_load_dwordx4 v[154:157], v217, s[40:41]
	v_add_u32_e32 v218, 0x2c00, v232
	global_load_dwordx4 v[158:161], v218, s[42:43]
	s_mov_b32 exec_lo, 0x30003
	s_mov_b32 exec_hi, 0x30003
	v_cvt_pk_bf16_f32 v162, v126, v127
	v_cvt_pk_bf16_f32 v163, v128, v129
	global_store_dwordx2 v233, v[162:163], s[38:39]
	v_cvt_pk_bf16_f32 v164, v122, v123
	v_cvt_pk_bf16_f32 v165, v124, v125
	v_add_u32_e32 v220, 0x1600, v233
	global_store_dwordx2 v220, v[164:165], s[38:39]
	v_cvt_pk_bf16_f32 v166, v94, v95
	v_cvt_pk_bf16_f32 v167, v96, v97
	v_add_u32_e32 v221, 0x16000, v233
	global_store_dwordx2 v221, v[166:167], s[38:39]
	v_cvt_pk_bf16_f32 v168, v90, v91
	v_cvt_pk_bf16_f32 v169, v92, v93
	v_add_u32_e32 v222, 0x17600, v233
	global_store_dwordx2 v222, v[168:169], s[38:39]
	v_cvt_pk_bf16_f32 v170, v62, v63
	v_cvt_pk_bf16_f32 v171, v64, v65
	v_add_u32_e32 v223, 0x8, v233
	global_store_dwordx2 v223, v[170:171], s[38:39]
	v_cvt_pk_bf16_f32 v172, v58, v59
	v_cvt_pk_bf16_f32 v173, v60, v61
	v_add_u32_e32 v224, 0x1608, v233
	global_store_dwordx2 v224, v[172:173], s[38:39]
	v_cvt_pk_bf16_f32 v174, v30, v31
	v_cvt_pk_bf16_f32 v175, v32, v33
	v_add_u32_e32 v225, 0x16008, v233
	global_store_dwordx2 v225, v[174:175], s[38:39]
	v_cvt_pk_bf16_f32 v176, v26, v27
	v_cvt_pk_bf16_f32 v177, v28, v29
	v_add_u32_e32 v226, 0x17608, v233
	global_store_dwordx2 v226, v[176:177], s[38:39]
	s_mov_b32 exec_lo, 0xc000c000
	s_mov_b32 exec_hi, 0xc000c000
	v_cvt_pk_bf16_f32 v162, v102, v103
	v_cvt_pk_bf16_f32 v163, v104, v105
	global_store_dwordx2 v233, v[162:163], s[38:39]
	v_cvt_pk_bf16_f32 v164, v98, v99
	v_cvt_pk_bf16_f32 v165, v100, v101
	v_add_u32_e32 v220, 0x1600, v233
	global_store_dwordx2 v220, v[164:165], s[38:39]
	v_cvt_pk_bf16_f32 v166, v70, v71
	v_cvt_pk_bf16_f32 v167, v72, v73
	v_add_u32_e32 v221, 0x16000, v233
	global_store_dwordx2 v221, v[166:167], s[38:39]
	v_cvt_pk_bf16_f32 v168, v66, v67
	v_cvt_pk_bf16_f32 v169, v68, v69
	v_add_u32_e32 v222, 0x17600, v233
	global_store_dwordx2 v222, v[168:169], s[38:39]
	v_cvt_pk_bf16_f32 v170, v38, v39
	v_cvt_pk_bf16_f32 v171, v40, v41
	v_add_u32_e32 v223, 0x8, v233
	global_store_dwordx2 v223, v[170:171], s[38:39]
	v_cvt_pk_bf16_f32 v172, v34, v35
	v_cvt_pk_bf16_f32 v173, v36, v37
	v_add_u32_e32 v224, 0x1608, v233
	global_store_dwordx2 v224, v[172:173], s[38:39]
	v_cvt_pk_bf16_f32 v174, v6, v7
	v_cvt_pk_bf16_f32 v175, v8, v9
	v_add_u32_e32 v225, 0x16008, v233
	global_store_dwordx2 v225, v[174:175], s[38:39]
	v_cvt_pk_bf16_f32 v176, v2, v3
	v_cvt_pk_bf16_f32 v177, v4, v5
	v_add_u32_e32 v226, 0x17608, v233
	global_store_dwordx2 v226, v[176:177], s[38:39]
	s_cmp_lg_u32 s5, 0
	s_cbranch_scc0 .Lmy_ffnB_ncp
	global_store_dwordx4 v234, v[70:73], s[44:45]
	v_add_u32_e32 v220, 0x2c00, v234
	global_store_dwordx4 v220, v[66:69], s[44:45]
	v_add_u32_e32 v221, 0x10, v234
	global_store_dwordx4 v221, v[6:9], s[44:45]
	v_add_u32_e32 v222, 0x2c10, v234
	global_store_dwordx4 v222, v[2:5], s[44:45]

.Lmy_ffnB_sample:
	s_load_dwordx2 s[36:37], s[78:79], 0x268
	s_load_dwordx2 s[38:39], s[78:79], 0x2a0
	s_load_dwordx4 s[40:43], s[78:79], 0x70
	s_load_dwordx2 s[44:45], s[78:79], 0x128
	s_load_dwordx2 s[16:17], s[78:79], 0x28
	v_and_b32_e32 v204, 15, v248
	v_bfe_u32 v205, v248, 8, 1
	v_bfe_u32 v206, v248, 6, 2
	v_bfe_u32 v207, v248, 4, 2
	v_lshlrev_b32_e32 v206, 5, v206
	v_lshl_or_b32 v206, v207, 3, v206
	s_lshl_b32 s13, s14, 7
	v_add_u32_e32 v206, s13, v206
	s_lshl_b32 s13, s12, 8
	v_lshl_add_u32 v207, v205, 6, v204
	v_add_u32_e32 v207, s13, v207
	v_mul_u32_u24_e32 v231, 0x1600, v207
	v_lshl_add_u32 v231, v206, 1, v231
	v_lshlrev_b32_e32 v232, 2, v206
	s_lshl_b32 s13, s12, 4
	v_lshl_add_u32 v233, v205, 2, s13
	v_add_u32_e32 v208, -12, v204
	v_cmp_gt_u32_e32 vcc, 2, v204
	s_nop 1
	v_cndmask_b32_e32 v208, v208, v204, vcc
	v_add_u32_e32 v233, v233, v208
	v_mul_u32_u24_e32 v233, 0x2c00, v233
	v_lshl_add_u32 v233, v206, 1, v233
	s_sub_u32 s13, s12, 64
	s_lshl_b32 s13, s13, 5
	s_add_u32 s13, s13, 128
	v_lshrrev_b32_e32 v208, 3, v204
	v_lshl_add_u32 v208, v205, 3, v208
	v_add_u32_e32 v208, s13, v208
	v_mul_u32_u24_e32 v234, 0xb000, v208
	v_add_u32_e32 v234, v234, v232
	v_and_b32_e32 v209, 7, v204
	v_mul_u32_u24_e32 v190, 0x5800, v209
	v_add_u32_e32 v235, 0xfffdf000, v190
	v_add_u32_e32 v235, v235, v234
	v_add_u32_e32 v190, v190, v234
	s_mov_b32 s46, 0x01010101
	s_mov_b32 s47, 0x01010101
	s_mov_b32 s48, 0x03030303
	s_mov_b32 s49, 0x03030303
	s_mov_b32 s50, 0xc0c0c0c0
	s_mov_b32 s51, 0xc0c0c0c0
	s_waitcnt lgkmcnt(0)
	s_add_u32 s40, s40, 0x10800
	s_addc_u32 s41, s41, 0
	s_add_u32 s42, s42, 0x5800
	s_addc_u32 s43, s43, 0
	global_load_dwordx4 v[130:133], v232, s[40:41]
	v_add_u32_e32 v213, 0x5800, v232
	global_load_dwordx4 v[134:137], v213, s[40:41]
	v_add_u32_e32 v214, 0xb000, v232
	global_load_dwordx4 v[138:141], v214, s[40:41]
	global_load_dwordx4 v[142:145], v232, s[42:43]
	v_add_u32_e32 v215, 0x2c00, v232
	global_load_dwordx4 v[146:149], v215, s[40:41]
	v_add_u32_e32 v216, 0x8400, v232
	global_load_dwordx4 v[150:153], v216, s[40:41]
	v_add_u32_e32 v217, 0xdc00, v232
	global_load_dwordx4 v[154:157], v217, s[40:41]
	v_add_u32_e32 v218, 0x2c00, v232
	global_load_dwordx4 v[158:161], v218, s[42:43]
	s_mov_b64 exec, s[48:49]
	global_load_dwordx4 v[162:165], v190, s[16:17]
	s_mov_b64 exec, -1
	s_mov_b64 exec, s[48:49]
	v_add_u32_e32 v222, 0x2c00, v190
	global_load_dwordx4 v[166:169], v222, s[16:17]
	s_mov_b64 exec, -1
	s_mov_b64 exec, s[48:49]
	v_add_u32_e32 v222, 0x16000, v190
	global_load_dwordx4 v[170:173], v222, s[16:17]
	s_mov_b64 exec, -1
	s_mov_b64 exec, s[48:49]
	v_add_u32_e32 v222, 0x18c00, v190
	global_load_dwordx4 v[174:177], v222, s[16:17]
	s_mov_b64 exec, -1
	s_mov_b32 exec_lo, 0x30003
	s_mov_b32 exec_hi, 0x30003
	v_cvt_pk_bf16_f32 v204, v126, v127
	v_cvt_pk_bf16_f32 v205, v128, v129
	global_store_dwordx2 v233, v[204:205], s[38:39]
	v_cvt_pk_bf16_f32 v206, v122, v123
	v_cvt_pk_bf16_f32 v207, v124, v125
	v_add_u32_e32 v220, 0x1600, v233
	global_store_dwordx2 v220, v[206:207], s[38:39]
	v_cvt_pk_bf16_f32 v208, v94, v95
	v_cvt_pk_bf16_f32 v209, v96, v97
	v_add_u32_e32 v221, 0x16000, v233
	global_store_dwordx2 v221, v[208:209], s[38:39]
	v_cvt_pk_bf16_f32 v210, v90, v91
	v_cvt_pk_bf16_f32 v211, v92, v93
	v_add_u32_e32 v222, 0x17600, v233
	global_store_dwordx2 v222, v[210:211], s[38:39]
	v_cvt_pk_bf16_f32 v212, v62, v63
	v_cvt_pk_bf16_f32 v213, v64, v65
	v_add_u32_e32 v223, 0x8, v233
	global_store_dwordx2 v223, v[212:213], s[38:39]
	v_cvt_pk_bf16_f32 v214, v58, v59
	v_cvt_pk_bf16_f32 v215, v60, v61
	v_add_u32_e32 v224, 0x1608, v233
	global_store_dwordx2 v224, v[214:215], s[38:39]
	v_cvt_pk_bf16_f32 v216, v30, v31
	v_cvt_pk_bf16_f32 v217, v32, v33
	v_add_u32_e32 v225, 0x16008, v233
	global_store_dwordx2 v225, v[216:217], s[38:39]
	v_cvt_pk_bf16_f32 v218, v26, v27
	v_cvt_pk_bf16_f32 v219, v28, v29
	v_add_u32_e32 v226, 0x17608, v233
	global_store_dwordx2 v226, v[218:219], s[38:39]
	s_mov_b32 exec_lo, 0xc000c000
	s_mov_b32 exec_hi, 0xc000c000
	v_cvt_pk_bf16_f32 v204, v102, v103
	v_cvt_pk_bf16_f32 v205, v104, v105
	global_store_dwordx2 v233, v[204:205], s[38:39]
	v_cvt_pk_bf16_f32 v206, v98, v99
	v_cvt_pk_bf16_f32 v207, v100, v101
	v_add_u32_e32 v220, 0x1600, v233
	global_store_dwordx2 v220, v[206:207], s[38:39]
	v_cvt_pk_bf16_f32 v208, v70, v71
	v_cvt_pk_bf16_f32 v209, v72, v73
	v_add_u32_e32 v221, 0x16000, v233
	global_store_dwordx2 v221, v[208:209], s[38:39]
	v_cvt_pk_bf16_f32 v210, v66, v67
	v_cvt_pk_bf16_f32 v211, v68, v69
	v_add_u32_e32 v222, 0x17600, v233
	global_store_dwordx2 v222, v[210:211], s[38:39]
	v_cvt_pk_bf16_f32 v212, v38, v39
	v_cvt_pk_bf16_f32 v213, v40, v41
	v_add_u32_e32 v223, 0x8, v233
	global_store_dwordx2 v223, v[212:213], s[38:39]
	v_cvt_pk_bf16_f32 v214, v34, v35
	v_cvt_pk_bf16_f32 v215, v36, v37
	v_add_u32_e32 v224, 0x1608, v233
	global_store_dwordx2 v224, v[214:215], s[38:39]
	v_cvt_pk_bf16_f32 v216, v6, v7
	v_cvt_pk_bf16_f32 v217, v8, v9
	v_add_u32_e32 v225, 0x16008, v233
	global_store_dwordx2 v225, v[216:217], s[38:39]
	v_cvt_pk_bf16_f32 v218, v2, v3
	v_cvt_pk_bf16_f32 v219, v4, v5
	v_add_u32_e32 v226, 0x17608, v233
	global_store_dwordx2 v226, v[218:219], s[38:39]
	s_mov_b64 exec, -1
	s_waitcnt vmcnt(20)
	s_mov_b64 exec, s[50:51]
	global_store_dwordx4 v235, v[126:129], s[44:45]
	v_add_u32_e32 v224, 0x2c00, v235
	global_store_dwordx4 v224, v[122:125], s[44:45]
	v_add_u32_e32 v225, 0x16000, v235
	global_store_dwordx4 v225, v[118:121], s[44:45]
	v_add_u32_e32 v226, 0x18c00, v235
	global_store_dwordx4 v226, v[114:117], s[44:45]
	v_add_u32_e32 v223, 0x2c000, v235
	global_store_dwordx4 v223, v[110:113], s[44:45]
	v_add_u32_e32 v224, 0x2ec00, v235
	global_store_dwordx4 v224, v[106:109], s[44:45]
	v_add_u32_e32 v225, 0x42000, v235
	global_store_dwordx4 v225, v[102:105], s[44:45]
	v_add_u32_e32 v226, 0x44c00, v235
	global_store_dwordx4 v226, v[98:101], s[44:45]
	v_add_u32_e32 v223, 0xb0000, v235
	global_store_dwordx4 v223, v[94:97], s[44:45]
	v_add_u32_e32 v224, 0xb2c00, v235
	global_store_dwordx4 v224, v[90:93], s[44:45]
	v_add_u32_e32 v225, 0xc6000, v235
	global_store_dwordx4 v225, v[86:89], s[44:45]
	v_add_u32_e32 v226, 0xc8c00, v235
	global_store_dwordx4 v226, v[82:85], s[44:45]
	v_add_u32_e32 v223, 0xdc000, v235
	global_store_dwordx4 v223, v[78:81], s[44:45]
	v_add_u32_e32 v224, 0xdec00, v235
	global_store_dwordx4 v224, v[74:77], s[44:45]
	v_add_u32_e32 v225, 0xf2000, v235
	global_store_dwordx4 v225, v[70:73], s[44:45]
	v_add_u32_e32 v226, 0xf4c00, v235
	global_store_dwordx4 v226, v[66:69], s[44:45]
	s_mov_b64 exec, -1
	v_pk_fma_f32 v[212:213], v[138:139], v[126:127], v[142:143]
	v_pk_fma_f32 v[214:215], v[140:141], v[128:129], v[144:145]
	s_nop 2
	v_mov_b32_dpp v204, v126 row_shr:1 row_mask:0xf bank_mask:0xf
	v_mov_b32_dpp v208, v126 row_shr:2 row_mask:0xf bank_mask:0xf
	v_mov_b32_dpp v205, v127 row_shr:1 row_mask:0xf bank_mask:0xf
	v_mov_b32_dpp v209, v127 row_shr:2 row_mask:0xf bank_mask:0xf
	v_mov_b32_dpp v206, v128 row_shr:1 row_mask:0xf bank_mask:0xf
	v_mov_b32_dpp v210, v128 row_shr:2 row_mask:0xf bank_mask:0xf
	v_mov_b32_dpp v207, v129 row_shr:1 row_mask:0xf bank_mask:0xf
	v_mov_b32_dpp v211, v129 row_shr:2 row_mask:0xf bank_mask:0xf
	s_waitcnt vmcnt(35)
	v_mov_b32_dpp v223, v162 row_shl:1 row_mask:0xf bank_mask:0xf
	v_mov_b32_dpp v224, v163 row_shl:1 row_mask:0xf bank_mask:0xf
	v_mov_b32_dpp v225, v164 row_shl:1 row_mask:0xf bank_mask:0xf
	v_mov_b32_dpp v226, v165 row_shl:1 row_mask:0xf bank_mask:0xf
	v_cndmask_b32_e64 v208, v208, v162, s[48:49]
	v_cndmask_b32_e64 v209, v209, v163, s[48:49]
	v_cndmask_b32_e64 v210, v210, v164, s[48:49]
	v_cndmask_b32_e64 v211, v211, v165, s[48:49]
	v_cndmask_b32_e64 v204, v204, v223, s[46:47]
	v_cndmask_b32_e64 v205, v205, v224, s[46:47]
	v_cndmask_b32_e64 v206, v206, v225, s[46:47]
	v_cndmask_b32_e64 v207, v207, v226, s[46:47]
	s_mov_b64 exec, s[48:49]
	v_add_u32_e32 v222, 0x2c000, v190
	global_load_dwordx4 v[162:165], v222, s[16:17]
	s_mov_b64 exec, -1
	v_pk_fma_f32 v[212:213], v[134:135], v[204:205], v[212:213]
	v_pk_fma_f32 v[214:215], v[136:137], v[206:207], v[214:215]
	v_pk_fma_f32 v[212:213], v[130:131], v[208:209], v[212:213]
	v_pk_fma_f32 v[214:215], v[132:133], v[210:211], v[214:215]
	v_pk_fma_f32 v[216:217], v[154:155], v[122:123], v[158:159]
	v_pk_fma_f32 v[218:219], v[156:157], v[124:125], v[160:161]
	s_nop 2
	v_mov_b32_dpp v204, v122 row_shr:1 row_mask:0xf bank_mask:0xf
	v_mov_b32_dpp v208, v122 row_shr:2 row_mask:0xf bank_mask:0xf
	v_mov_b32_dpp v205, v123 row_shr:1 row_mask:0xf bank_mask:0xf
	v_mov_b32_dpp v209, v123 row_shr:2 row_mask:0xf bank_mask:0xf
	v_mov_b32_dpp v206, v124 row_shr:1 row_mask:0xf bank_mask:0xf
	v_mov_b32_dpp v210, v124 row_shr:2 row_mask:0xf bank_mask:0xf
	v_mov_b32_dpp v207, v125 row_shr:1 row_mask:0xf bank_mask:0xf
	v_mov_b32_dpp v211, v125 row_shr:2 row_mask:0xf bank_mask:0xf
	s_waitcnt vmcnt(35)
	v_mov_b32_dpp v223, v166 row_shl:1 row_mask:0xf bank_mask:0xf
	v_mov_b32_dpp v224, v167 row_shl:1 row_mask:0xf bank_mask:0xf
	v_mov_b32_dpp v225, v168 row_shl:1 row_mask:0xf bank_mask:0xf
	v_mov_b32_dpp v226, v169 row_shl:1 row_mask:0xf bank_mask:0xf
	v_cndmask_b32_e64 v208, v208, v166, s[48:49]
	v_cndmask_b32_e64 v209, v209, v167, s[48:49]
	v_cndmask_b32_e64 v210, v210, v168, s[48:49]
	v_cndmask_b32_e64 v211, v211, v169, s[48:49]
	v_cndmask_b32_e64 v204, v204, v223, s[46:47]
	v_cndmask_b32_e64 v205, v205, v224, s[46:47]
	v_cndmask_b32_e64 v206, v206, v225, s[46:47]
	v_cndmask_b32_e64 v207, v207, v226, s[46:47]
	s_mov_b64 exec, s[48:49]
	v_add_u32_e32 v222, 0x2ec00, v190
	global_load_dwordx4 v[166:169], v222, s[16:17]
	s_mov_b64 exec, -1
	v_pk_fma_f32 v[216:217], v[150:151], v[204:205], v[216:217]
	v_pk_fma_f32 v[218:219], v[152:153], v[206:207], v[218:219]
	v_pk_fma_f32 v[216:217], v[146:147], v[208:209], v[216:217]
	v_pk_fma_f32 v[218:219], v[148:149], v[210:211], v[218:219]
	v_mul_f32_e32 v204, 0xbfb8aa3b, v216
	v_mul_f32_e32 v205, 0xbfb8aa3b, v217
	v_mul_f32_e32 v206, 0xbfb8aa3b, v218
	v_mul_f32_e32 v207, 0xbfb8aa3b, v219
	v_exp_f32_e32 v204, v204
	v_exp_f32_e32 v205, v205
	v_exp_f32_e32 v206, v206
	v_exp_f32_e32 v207, v207
	v_add_f32_e32 v204, 1.0, v204
	v_add_f32_e32 v205, 1.0, v205
	v_add_f32_e32 v206, 1.0, v206
	v_add_f32_e32 v207, 1.0, v207
	v_rcp_f32_e32 v204, v204
	v_rcp_f32_e32 v205, v205
	v_rcp_f32_e32 v206, v206
	v_rcp_f32_e32 v207, v207
	v_mul_f32_e32 v204, v216, v204
	v_mul_f32_e32 v205, v217, v205
	v_mul_f32_e32 v206, v218, v206
	v_mul_f32_e32 v207, v219, v207
	v_mul_f32_e32 v204, v212, v204
	v_mul_f32_e32 v205, v213, v205
	v_mul_f32_e32 v206, v214, v206
	v_mul_f32_e32 v207, v215, v207
	v_cvt_pk_bf16_f32 v220, v204, v205
	v_cvt_pk_bf16_f32 v221, v206, v207
	v_mov_b32_e32 v222, v231
	s_mov_b32 exec_lo, 0xfffcfffc
	s_mov_b32 exec_hi, 0xfffcfffc
	global_store_dwordx2 v222, v[220:221], s[36:37]
	s_mov_b64 exec, -1
	v_pk_fma_f32 v[212:213], v[138:139], v[118:119], v[142:143]
	v_pk_fma_f32 v[214:215], v[140:141], v[120:121], v[144:145]
	s_nop 2
	v_mov_b32_dpp v204, v118 row_shr:1 row_mask:0xf bank_mask:0xf
	v_mov_b32_dpp v208, v118 row_shr:2 row_mask:0xf bank_mask:0xf
	v_mov_b32_dpp v205, v119 row_shr:1 row_mask:0xf bank_mask:0xf
	v_mov_b32_dpp v209, v119 row_shr:2 row_mask:0xf bank_mask:0xf
	v_mov_b32_dpp v206, v120 row_shr:1 row_mask:0xf bank_mask:0xf
	v_mov_b32_dpp v210, v120 row_shr:2 row_mask:0xf bank_mask:0xf
	v_mov_b32_dpp v207, v121 row_shr:1 row_mask:0xf bank_mask:0xf
	v_mov_b32_dpp v211, v121 row_shr:2 row_mask:0xf bank_mask:0xf
	s_waitcnt vmcnt(36)
	v_mov_b32_dpp v223, v170 row_shl:1 row_mask:0xf bank_mask:0xf
	v_mov_b32_dpp v224, v171 row_shl:1 row_mask:0xf bank_mask:0xf
	v_mov_b32_dpp v225, v172 row_shl:1 row_mask:0xf bank_mask:0xf
	v_mov_b32_dpp v226, v173 row_shl:1 row_mask:0xf bank_mask:0xf
	v_cndmask_b32_e64 v208, v208, v170, s[48:49]
	v_cndmask_b32_e64 v209, v209, v171, s[48:49]
	v_cndmask_b32_e64 v210, v210, v172, s[48:49]
	v_cndmask_b32_e64 v211, v211, v173, s[48:49]
	v_cndmask_b32_e64 v204, v204, v223, s[46:47]
	v_cndmask_b32_e64 v205, v205, v224, s[46:47]
	v_cndmask_b32_e64 v206, v206, v225, s[46:47]
	v_cndmask_b32_e64 v207, v207, v226, s[46:47]
	s_mov_b64 exec, s[48:49]
	v_add_u32_e32 v222, 0x42000, v190
	global_load_dwordx4 v[170:173], v222, s[16:17]
	s_mov_b64 exec, -1
	v_pk_fma_f32 v[212:213], v[134:135], v[204:205], v[212:213]
	v_pk_fma_f32 v[214:215], v[136:137], v[206:207], v[214:215]
	v_pk_fma_f32 v[212:213], v[130:131], v[208:209], v[212:213]
	v_pk_fma_f32 v[214:215], v[132:133], v[210:211], v[214:215]
	v_pk_fma_f32 v[216:217], v[154:155], v[114:115], v[158:159]
	v_pk_fma_f32 v[218:219], v[156:157], v[116:117], v[160:161]
	s_nop 2
	v_mov_b32_dpp v204, v114 row_shr:1 row_mask:0xf bank_mask:0xf
	v_mov_b32_dpp v208, v114 row_shr:2 row_mask:0xf bank_mask:0xf
	v_mov_b32_dpp v205, v115 row_shr:1 row_mask:0xf bank_mask:0xf
	v_mov_b32_dpp v209, v115 row_shr:2 row_mask:0xf bank_mask:0xf
	v_mov_b32_dpp v206, v116 row_shr:1 row_mask:0xf bank_mask:0xf
	v_mov_b32_dpp v210, v116 row_shr:2 row_mask:0xf bank_mask:0xf
	v_mov_b32_dpp v207, v117 row_shr:1 row_mask:0xf bank_mask:0xf
	v_mov_b32_dpp v211, v117 row_shr:2 row_mask:0xf bank_mask:0xf
	s_waitcnt vmcnt(36)
	v_mov_b32_dpp v223, v174 row_shl:1 row_mask:0xf bank_mask:0xf
	v_mov_b32_dpp v224, v175 row_shl:1 row_mask:0xf bank_mask:0xf
	v_mov_b32_dpp v225, v176 row_shl:1 row_mask:0xf bank_mask:0xf
	v_mov_b32_dpp v226, v177 row_shl:1 row_mask:0xf bank_mask:0xf
	v_cndmask_b32_e64 v208, v208, v174, s[48:49]
	v_cndmask_b32_e64 v209, v209, v175, s[48:49]
	v_cndmask_b32_e64 v210, v210, v176, s[48:49]
	v_cndmask_b32_e64 v211, v211, v177, s[48:49]
	v_cndmask_b32_e64 v204, v204, v223, s[46:47]
	v_cndmask_b32_e64 v205, v205, v224, s[46:47]
	v_cndmask_b32_e64 v206, v206, v225, s[46:47]
	v_cndmask_b32_e64 v207, v207, v226, s[46:47]
	s_mov_b64 exec, s[48:49]
	v_add_u32_e32 v222, 0x44c00, v190
	global_load_dwordx4 v[174:177], v222, s[16:17]
	s_mov_b64 exec, -1
	v_pk_fma_f32 v[216:217], v[150:151], v[204:205], v[216:217]
	v_pk_fma_f32 v[218:219], v[152:153], v[206:207], v[218:219]
	v_pk_fma_f32 v[216:217], v[146:147], v[208:209], v[216:217]
	v_pk_fma_f32 v[218:219], v[148:149], v[210:211], v[218:219]
	v_mul_f32_e32 v204, 0xbfb8aa3b, v216
	v_mul_f32_e32 v205, 0xbfb8aa3b, v217
	v_mul_f32_e32 v206, 0xbfb8aa3b, v218
	v_mul_f32_e32 v207, 0xbfb8aa3b, v219
	v_exp_f32_e32 v204, v204
	v_exp_f32_e32 v205, v205
	v_exp_f32_e32 v206, v206
	v_exp_f32_e32 v207, v207
	v_add_f32_e32 v204, 1.0, v204
	v_add_f32_e32 v205, 1.0, v205
	v_add_f32_e32 v206, 1.0, v206
	v_add_f32_e32 v207, 1.0, v207
	v_rcp_f32_e32 v204, v204
	v_rcp_f32_e32 v205, v205
	v_rcp_f32_e32 v206, v206
	v_rcp_f32_e32 v207, v207
	v_mul_f32_e32 v204, v216, v204
	v_mul_f32_e32 v205, v217, v205
	v_mul_f32_e32 v206, v218, v206
	v_mul_f32_e32 v207, v219, v207
	v_mul_f32_e32 v204, v212, v204
	v_mul_f32_e32 v205, v213, v205
	v_mul_f32_e32 v206, v214, v206
	v_mul_f32_e32 v207, v215, v207
	v_cvt_pk_bf16_f32 v220, v204, v205
	v_cvt_pk_bf16_f32 v221, v206, v207
	v_add_u32_e32 v222, 0x16000, v231
	global_store_dwordx2 v222, v[220:221], s[36:37]
	v_pk_fma_f32 v[212:213], v[138:139], v[110:111], v[142:143]
	v_pk_fma_f32 v[214:215], v[140:141], v[112:113], v[144:145]
	s_nop 2
	v_mov_b32_dpp v204, v110 row_shr:1 row_mask:0xf bank_mask:0xf
	v_mov_b32_dpp v208, v110 row_shr:2 row_mask:0xf bank_mask:0xf
	v_mov_b32_dpp v205, v111 row_shr:1 row_mask:0xf bank_mask:0xf
	v_mov_b32_dpp v209, v111 row_shr:2 row_mask:0xf bank_mask:0xf
	v_mov_b32_dpp v206, v112 row_shr:1 row_mask:0xf bank_mask:0xf
	v_mov_b32_dpp v210, v112 row_shr:2 row_mask:0xf bank_mask:0xf
	v_mov_b32_dpp v207, v113 row_shr:1 row_mask:0xf bank_mask:0xf
	v_mov_b32_dpp v211, v113 row_shr:2 row_mask:0xf bank_mask:0xf
	s_waitcnt vmcnt(5)
	v_mov_b32_dpp v223, v162 row_shl:1 row_mask:0xf bank_mask:0xf
	v_mov_b32_dpp v224, v163 row_shl:1 row_mask:0xf bank_mask:0xf
	v_mov_b32_dpp v225, v164 row_shl:1 row_mask:0xf bank_mask:0xf
	v_mov_b32_dpp v226, v165 row_shl:1 row_mask:0xf bank_mask:0xf
	v_cndmask_b32_e64 v208, v208, v162, s[48:49]
	v_cndmask_b32_e64 v209, v209, v163, s[48:49]
	v_cndmask_b32_e64 v210, v210, v164, s[48:49]
	v_cndmask_b32_e64 v211, v211, v165, s[48:49]
	v_cndmask_b32_e64 v204, v204, v223, s[46:47]
	v_cndmask_b32_e64 v205, v205, v224, s[46:47]
	v_cndmask_b32_e64 v206, v206, v225, s[46:47]
	v_cndmask_b32_e64 v207, v207, v226, s[46:47]
	s_mov_b64 exec, s[48:49]
	v_add_u32_e32 v222, 0xb0000, v190
	global_load_dwordx4 v[162:165], v222, s[16:17]
	s_mov_b64 exec, -1
	v_pk_fma_f32 v[212:213], v[134:135], v[204:205], v[212:213]
	v_pk_fma_f32 v[214:215], v[136:137], v[206:207], v[214:215]
	v_pk_fma_f32 v[212:213], v[130:131], v[208:209], v[212:213]
	v_pk_fma_f32 v[214:215], v[132:133], v[210:211], v[214:215]
	v_pk_fma_f32 v[216:217], v[154:155], v[106:107], v[158:159]
	v_pk_fma_f32 v[218:219], v[156:157], v[108:109], v[160:161]
	s_nop 2
	v_mov_b32_dpp v204, v106 row_shr:1 row_mask:0xf bank_mask:0xf
	v_mov_b32_dpp v208, v106 row_shr:2 row_mask:0xf bank_mask:0xf
	v_mov_b32_dpp v205, v107 row_shr:1 row_mask:0xf bank_mask:0xf
	v_mov_b32_dpp v209, v107 row_shr:2 row_mask:0xf bank_mask:0xf
	v_mov_b32_dpp v206, v108 row_shr:1 row_mask:0xf bank_mask:0xf
	v_mov_b32_dpp v210, v108 row_shr:2 row_mask:0xf bank_mask:0xf
	v_mov_b32_dpp v207, v109 row_shr:1 row_mask:0xf bank_mask:0xf
	v_mov_b32_dpp v211, v109 row_shr:2 row_mask:0xf bank_mask:0xf
	s_waitcnt vmcnt(5)
	v_mov_b32_dpp v223, v166 row_shl:1 row_mask:0xf bank_mask:0xf
	v_mov_b32_dpp v224, v167 row_shl:1 row_mask:0xf bank_mask:0xf
	v_mov_b32_dpp v225, v168 row_shl:1 row_mask:0xf bank_mask:0xf
	v_mov_b32_dpp v226, v169 row_shl:1 row_mask:0xf bank_mask:0xf
	v_cndmask_b32_e64 v208, v208, v166, s[48:49]
	v_cndmask_b32_e64 v209, v209, v167, s[48:49]
	v_cndmask_b32_e64 v210, v210, v168, s[48:49]
	v_cndmask_b32_e64 v211, v211, v169, s[48:49]
	v_cndmask_b32_e64 v204, v204, v223, s[46:47]
	v_cndmask_b32_e64 v205, v205, v224, s[46:47]
	v_cndmask_b32_e64 v206, v206, v225, s[46:47]
	v_cndmask_b32_e64 v207, v207, v226, s[46:47]
	s_mov_b64 exec, s[48:49]
	v_add_u32_e32 v222, 0xb2c00, v190
	global_load_dwordx4 v[166:169], v222, s[16:17]
	s_mov_b64 exec, -1
	v_pk_fma_f32 v[216:217], v[150:151], v[204:205], v[216:217]
	v_pk_fma_f32 v[218:219], v[152:153], v[206:207], v[218:219]
	v_pk_fma_f32 v[216:217], v[146:147], v[208:209], v[216:217]
	v_pk_fma_f32 v[218:219], v[148:149], v[210:211], v[218:219]
	v_mul_f32_e32 v204, 0xbfb8aa3b, v216
	v_mul_f32_e32 v205, 0xbfb8aa3b, v217
	v_mul_f32_e32 v206, 0xbfb8aa3b, v218
	v_mul_f32_e32 v207, 0xbfb8aa3b, v219
	v_exp_f32_e32 v204, v204
	v_exp_f32_e32 v205, v205
	v_exp_f32_e32 v206, v206
	v_exp_f32_e32 v207, v207
	v_add_f32_e32 v204, 1.0, v204
	v_add_f32_e32 v205, 1.0, v205
	v_add_f32_e32 v206, 1.0, v206
	v_add_f32_e32 v207, 1.0, v207
	v_rcp_f32_e32 v204, v204
	v_rcp_f32_e32 v205, v205
	v_rcp_f32_e32 v206, v206
	v_rcp_f32_e32 v207, v207
	v_mul_f32_e32 v204, v216, v204
	v_mul_f32_e32 v205, v217, v205
	v_mul_f32_e32 v206, v218, v206
	v_mul_f32_e32 v207, v219, v207
	v_mul_f32_e32 v204, v212, v204
	v_mul_f32_e32 v205, v213, v205
	v_mul_f32_e32 v206, v214, v206
	v_mul_f32_e32 v207, v215, v207
	v_cvt_pk_bf16_f32 v220, v204, v205
	v_cvt_pk_bf16_f32 v221, v206, v207
	v_add_u32_e32 v222, 0x2c000, v231
	global_store_dwordx2 v222, v[220:221], s[36:37]
	v_pk_fma_f32 v[212:213], v[138:139], v[102:103], v[142:143]
	v_pk_fma_f32 v[214:215], v[140:141], v[104:105], v[144:145]
	s_nop 2
	v_mov_b32_dpp v204, v102 row_shr:1 row_mask:0xf bank_mask:0xf
	v_mov_b32_dpp v208, v102 row_shr:2 row_mask:0xf bank_mask:0xf
	v_mov_b32_dpp v205, v103 row_shr:1 row_mask:0xf bank_mask:0xf
	v_mov_b32_dpp v209, v103 row_shr:2 row_mask:0xf bank_mask:0xf
	v_mov_b32_dpp v206, v104 row_shr:1 row_mask:0xf bank_mask:0xf
	v_mov_b32_dpp v210, v104 row_shr:2 row_mask:0xf bank_mask:0xf
	v_mov_b32_dpp v207, v105 row_shr:1 row_mask:0xf bank_mask:0xf
	v_mov_b32_dpp v211, v105 row_shr:2 row_mask:0xf bank_mask:0xf
	s_waitcnt vmcnt(5)
	v_mov_b32_dpp v223, v170 row_shl:1 row_mask:0xf bank_mask:0xf
	v_mov_b32_dpp v224, v171 row_shl:1 row_mask:0xf bank_mask:0xf
	v_mov_b32_dpp v225, v172 row_shl:1 row_mask:0xf bank_mask:0xf
	v_mov_b32_dpp v226, v173 row_shl:1 row_mask:0xf bank_mask:0xf
	v_cndmask_b32_e64 v208, v208, v170, s[48:49]
	v_cndmask_b32_e64 v209, v209, v171, s[48:49]
	v_cndmask_b32_e64 v210, v210, v172, s[48:49]
	v_cndmask_b32_e64 v211, v211, v173, s[48:49]
	v_cndmask_b32_e64 v204, v204, v223, s[46:47]
	v_cndmask_b32_e64 v205, v205, v224, s[46:47]
	v_cndmask_b32_e64 v206, v206, v225, s[46:47]
	v_cndmask_b32_e64 v207, v207, v226, s[46:47]
	s_mov_b64 exec, s[48:49]
	v_add_u32_e32 v222, 0xc6000, v190
	global_load_dwordx4 v[170:173], v222, s[16:17]
	s_mov_b64 exec, -1
	v_pk_fma_f32 v[212:213], v[134:135], v[204:205], v[212:213]
	v_pk_fma_f32 v[214:215], v[136:137], v[206:207], v[214:215]
	v_pk_fma_f32 v[212:213], v[130:131], v[208:209], v[212:213]
	v_pk_fma_f32 v[214:215], v[132:133], v[210:211], v[214:215]
	v_pk_fma_f32 v[216:217], v[154:155], v[98:99], v[158:159]
	v_pk_fma_f32 v[218:219], v[156:157], v[100:101], v[160:161]
	s_nop 2
	v_mov_b32_dpp v204, v98 row_shr:1 row_mask:0xf bank_mask:0xf
	v_mov_b32_dpp v208, v98 row_shr:2 row_mask:0xf bank_mask:0xf
	v_mov_b32_dpp v205, v99 row_shr:1 row_mask:0xf bank_mask:0xf
	v_mov_b32_dpp v209, v99 row_shr:2 row_mask:0xf bank_mask:0xf
	v_mov_b32_dpp v206, v100 row_shr:1 row_mask:0xf bank_mask:0xf
	v_mov_b32_dpp v210, v100 row_shr:2 row_mask:0xf bank_mask:0xf
	v_mov_b32_dpp v207, v101 row_shr:1 row_mask:0xf bank_mask:0xf
	v_mov_b32_dpp v211, v101 row_shr:2 row_mask:0xf bank_mask:0xf
	s_waitcnt vmcnt(5)
	v_mov_b32_dpp v223, v174 row_shl:1 row_mask:0xf bank_mask:0xf
	v_mov_b32_dpp v224, v175 row_shl:1 row_mask:0xf bank_mask:0xf
	v_mov_b32_dpp v225, v176 row_shl:1 row_mask:0xf bank_mask:0xf
	v_mov_b32_dpp v226, v177 row_shl:1 row_mask:0xf bank_mask:0xf
	v_cndmask_b32_e64 v208, v208, v174, s[48:49]
	v_cndmask_b32_e64 v209, v209, v175, s[48:49]
	v_cndmask_b32_e64 v210, v210, v176, s[48:49]
	v_cndmask_b32_e64 v211, v211, v177, s[48:49]
	v_cndmask_b32_e64 v204, v204, v223, s[46:47]
	v_cndmask_b32_e64 v205, v205, v224, s[46:47]
	v_cndmask_b32_e64 v206, v206, v225, s[46:47]
	v_cndmask_b32_e64 v207, v207, v226, s[46:47]
	s_mov_b64 exec, s[48:49]
	v_add_u32_e32 v222, 0xc8c00, v190
	global_load_dwordx4 v[174:177], v222, s[16:17]
	s_mov_b64 exec, -1
	v_pk_fma_f32 v[216:217], v[150:151], v[204:205], v[216:217]
	v_pk_fma_f32 v[218:219], v[152:153], v[206:207], v[218:219]
	v_pk_fma_f32 v[216:217], v[146:147], v[208:209], v[216:217]
	v_pk_fma_f32 v[218:219], v[148:149], v[210:211], v[218:219]
	v_mul_f32_e32 v204, 0xbfb8aa3b, v216
	v_mul_f32_e32 v205, 0xbfb8aa3b, v217
	v_mul_f32_e32 v206, 0xbfb8aa3b, v218
	v_mul_f32_e32 v207, 0xbfb8aa3b, v219
	v_exp_f32_e32 v204, v204
	v_exp_f32_e32 v205, v205
	v_exp_f32_e32 v206, v206
	v_exp_f32_e32 v207, v207
	v_add_f32_e32 v204, 1.0, v204
	v_add_f32_e32 v205, 1.0, v205
	v_add_f32_e32 v206, 1.0, v206
	v_add_f32_e32 v207, 1.0, v207
	v_rcp_f32_e32 v204, v204
	v_rcp_f32_e32 v205, v205
	v_rcp_f32_e32 v206, v206
	v_rcp_f32_e32 v207, v207
	v_mul_f32_e32 v204, v216, v204
	v_mul_f32_e32 v205, v217, v205
	v_mul_f32_e32 v206, v218, v206
	v_mul_f32_e32 v207, v219, v207
	v_mul_f32_e32 v204, v212, v204
	v_mul_f32_e32 v205, v213, v205
	v_mul_f32_e32 v206, v214, v206
	v_mul_f32_e32 v207, v215, v207
	v_cvt_pk_bf16_f32 v220, v204, v205
	v_cvt_pk_bf16_f32 v221, v206, v207
	v_add_u32_e32 v222, 0x42000, v231
	global_store_dwordx2 v222, v[220:221], s[36:37]
	global_load_dwordx4 v[98:101], v232, s[40:41] offset:16
	v_add_u32_e32 v204, 0x5800, v232
	global_load_dwordx4 v[102:105], v204, s[40:41] offset:16
	v_add_u32_e32 v205, 0xb000, v232
	global_load_dwordx4 v[106:109], v205, s[40:41] offset:16
	global_load_dwordx4 v[110:113], v232, s[42:43] offset:16
	v_add_u32_e32 v206, 0x2c00, v232
	global_load_dwordx4 v[114:117], v206, s[40:41] offset:16
	v_add_u32_e32 v207, 0x8400, v232
	global_load_dwordx4 v[118:121], v207, s[40:41] offset:16
	v_add_u32_e32 v208, 0xdc00, v232
	global_load_dwordx4 v[122:125], v208, s[40:41] offset:16
	v_add_u32_e32 v209, 0x2c00, v232
	global_load_dwordx4 v[126:129], v209, s[42:43] offset:16
	s_mov_b64 exec, s[50:51]
	v_add_u32_e32 v223, 0x10, v235
	global_store_dwordx4 v223, v[62:65], s[44:45]
	v_add_u32_e32 v224, 0x2c10, v235
	global_store_dwordx4 v224, v[58:61], s[44:45]
	v_add_u32_e32 v225, 0x16010, v235
	global_store_dwordx4 v225, v[54:57], s[44:45]
	v_add_u32_e32 v226, 0x18c10, v235
	global_store_dwordx4 v226, v[50:53], s[44:45]
	v_add_u32_e32 v223, 0x2c010, v235
	global_store_dwordx4 v223, v[46:49], s[44:45]
	v_add_u32_e32 v224, 0x2ec10, v235
	global_store_dwordx4 v224, v[42:45], s[44:45]
	v_add_u32_e32 v225, 0x42010, v235
	global_store_dwordx4 v225, v[38:41], s[44:45]
	v_add_u32_e32 v226, 0x44c10, v235
	global_store_dwordx4 v226, v[34:37], s[44:45]
	v_add_u32_e32 v223, 0xb0010, v235
	global_store_dwordx4 v223, v[30:33], s[44:45]
	v_add_u32_e32 v224, 0xb2c10, v235
	global_store_dwordx4 v224, v[26:29], s[44:45]
	v_add_u32_e32 v225, 0xc6010, v235
	global_store_dwordx4 v225, v[22:25], s[44:45]
	v_add_u32_e32 v226, 0xc8c10, v235
	global_store_dwordx4 v226, v[18:21], s[44:45]
	v_add_u32_e32 v223, 0xdc010, v235
	global_store_dwordx4 v223, v[14:17], s[44:45]
	v_add_u32_e32 v224, 0xdec10, v235
	global_store_dwordx4 v224, v[10:13], s[44:45]
	v_add_u32_e32 v225, 0xf2010, v235
	global_store_dwordx4 v225, v[6:9], s[44:45]
	v_add_u32_e32 v226, 0xf4c10, v235
	global_store_dwordx4 v226, v[2:5], s[44:45]
	s_mov_b64 exec, -1
	v_pk_fma_f32 v[212:213], v[138:139], v[94:95], v[142:143]
	v_pk_fma_f32 v[214:215], v[140:141], v[96:97], v[144:145]
	s_nop 2
	v_mov_b32_dpp v204, v94 row_shr:1 row_mask:0xf bank_mask:0xf
	v_mov_b32_dpp v208, v94 row_shr:2 row_mask:0xf bank_mask:0xf
	v_mov_b32_dpp v205, v95 row_shr:1 row_mask:0xf bank_mask:0xf
	v_mov_b32_dpp v209, v95 row_shr:2 row_mask:0xf bank_mask:0xf
	v_mov_b32_dpp v206, v96 row_shr:1 row_mask:0xf bank_mask:0xf
	v_mov_b32_dpp v210, v96 row_shr:2 row_mask:0xf bank_mask:0xf
	v_mov_b32_dpp v207, v97 row_shr:1 row_mask:0xf bank_mask:0xf
	v_mov_b32_dpp v211, v97 row_shr:2 row_mask:0xf bank_mask:0xf
	s_waitcnt vmcnt(29)
	v_mov_b32_dpp v223, v162 row_shl:1 row_mask:0xf bank_mask:0xf
	v_mov_b32_dpp v224, v163 row_shl:1 row_mask:0xf bank_mask:0xf
	v_mov_b32_dpp v225, v164 row_shl:1 row_mask:0xf bank_mask:0xf
	v_mov_b32_dpp v226, v165 row_shl:1 row_mask:0xf bank_mask:0xf
	v_cndmask_b32_e64 v208, v208, v162, s[48:49]
	v_cndmask_b32_e64 v209, v209, v163, s[48:49]
	v_cndmask_b32_e64 v210, v210, v164, s[48:49]
	v_cndmask_b32_e64 v211, v211, v165, s[48:49]
	v_cndmask_b32_e64 v204, v204, v223, s[46:47]
	v_cndmask_b32_e64 v205, v205, v224, s[46:47]
	v_cndmask_b32_e64 v206, v206, v225, s[46:47]
	v_cndmask_b32_e64 v207, v207, v226, s[46:47]
	s_mov_b64 exec, s[48:49]
	v_add_u32_e32 v222, 0xdc000, v190
	global_load_dwordx4 v[162:165], v222, s[16:17]
	s_mov_b64 exec, -1
	v_pk_fma_f32 v[212:213], v[134:135], v[204:205], v[212:213]
	v_pk_fma_f32 v[214:215], v[136:137], v[206:207], v[214:215]
	v_pk_fma_f32 v[212:213], v[130:131], v[208:209], v[212:213]
	v_pk_fma_f32 v[214:215], v[132:133], v[210:211], v[214:215]
	v_pk_fma_f32 v[216:217], v[154:155], v[90:91], v[158:159]
	v_pk_fma_f32 v[218:219], v[156:157], v[92:93], v[160:161]
	s_nop 2
	v_mov_b32_dpp v204, v90 row_shr:1 row_mask:0xf bank_mask:0xf
	v_mov_b32_dpp v208, v90 row_shr:2 row_mask:0xf bank_mask:0xf
	v_mov_b32_dpp v205, v91 row_shr:1 row_mask:0xf bank_mask:0xf
	v_mov_b32_dpp v209, v91 row_shr:2 row_mask:0xf bank_mask:0xf
	v_mov_b32_dpp v206, v92 row_shr:1 row_mask:0xf bank_mask:0xf
	v_mov_b32_dpp v210, v92 row_shr:2 row_mask:0xf bank_mask:0xf
	v_mov_b32_dpp v207, v93 row_shr:1 row_mask:0xf bank_mask:0xf
	v_mov_b32_dpp v211, v93 row_shr:2 row_mask:0xf bank_mask:0xf
	s_waitcnt vmcnt(29)
	v_mov_b32_dpp v223, v166 row_shl:1 row_mask:0xf bank_mask:0xf
	v_mov_b32_dpp v224, v167 row_shl:1 row_mask:0xf bank_mask:0xf
	v_mov_b32_dpp v225, v168 row_shl:1 row_mask:0xf bank_mask:0xf
	v_mov_b32_dpp v226, v169 row_shl:1 row_mask:0xf bank_mask:0xf
	v_cndmask_b32_e64 v208, v208, v166, s[48:49]
	v_cndmask_b32_e64 v209, v209, v167, s[48:49]
	v_cndmask_b32_e64 v210, v210, v168, s[48:49]
	v_cndmask_b32_e64 v211, v211, v169, s[48:49]
	v_cndmask_b32_e64 v204, v204, v223, s[46:47]
	v_cndmask_b32_e64 v205, v205, v224, s[46:47]
	v_cndmask_b32_e64 v206, v206, v225, s[46:47]
	v_cndmask_b32_e64 v207, v207, v226, s[46:47]
	s_mov_b64 exec, s[48:49]
	v_add_u32_e32 v222, 0xdec00, v190
	global_load_dwordx4 v[166:169], v222, s[16:17]
	s_mov_b64 exec, -1
	v_pk_fma_f32 v[216:217], v[150:151], v[204:205], v[216:217]
	v_pk_fma_f32 v[218:219], v[152:153], v[206:207], v[218:219]
	v_pk_fma_f32 v[216:217], v[146:147], v[208:209], v[216:217]
	v_pk_fma_f32 v[218:219], v[148:149], v[210:211], v[218:219]
	v_mul_f32_e32 v204, 0xbfb8aa3b, v216
	v_mul_f32_e32 v205, 0xbfb8aa3b, v217
	v_mul_f32_e32 v206, 0xbfb8aa3b, v218
	v_mul_f32_e32 v207, 0xbfb8aa3b, v219
	v_exp_f32_e32 v204, v204
	v_exp_f32_e32 v205, v205
	v_exp_f32_e32 v206, v206
	v_exp_f32_e32 v207, v207
	v_add_f32_e32 v204, 1.0, v204
	v_add_f32_e32 v205, 1.0, v205
	v_add_f32_e32 v206, 1.0, v206
	v_add_f32_e32 v207, 1.0, v207
	v_rcp_f32_e32 v204, v204
	v_rcp_f32_e32 v205, v205
	v_rcp_f32_e32 v206, v206
	v_rcp_f32_e32 v207, v207
	v_mul_f32_e32 v204, v216, v204
	v_mul_f32_e32 v205, v217, v205
	v_mul_f32_e32 v206, v218, v206
	v_mul_f32_e32 v207, v219, v207
	v_mul_f32_e32 v204, v212, v204
	v_mul_f32_e32 v205, v213, v205
	v_mul_f32_e32 v206, v214, v206
	v_mul_f32_e32 v207, v215, v207
	v_cvt_pk_bf16_f32 v94, v204, v205
	v_cvt_pk_bf16_f32 v95, v206, v207
	v_pk_fma_f32 v[212:213], v[138:139], v[86:87], v[142:143]
	v_pk_fma_f32 v[214:215], v[140:141], v[88:89], v[144:145]
	s_nop 2
	v_mov_b32_dpp v204, v86 row_shr:1 row_mask:0xf bank_mask:0xf
	v_mov_b32_dpp v208, v86 row_shr:2 row_mask:0xf bank_mask:0xf
	v_mov_b32_dpp v205, v87 row_shr:1 row_mask:0xf bank_mask:0xf
	v_mov_b32_dpp v209, v87 row_shr:2 row_mask:0xf bank_mask:0xf
	v_mov_b32_dpp v206, v88 row_shr:1 row_mask:0xf bank_mask:0xf
	v_mov_b32_dpp v210, v88 row_shr:2 row_mask:0xf bank_mask:0xf
	v_mov_b32_dpp v207, v89 row_shr:1 row_mask:0xf bank_mask:0xf
	v_mov_b32_dpp v211, v89 row_shr:2 row_mask:0xf bank_mask:0xf
	s_waitcnt vmcnt(28)
	v_mov_b32_dpp v223, v170 row_shl:1 row_mask:0xf bank_mask:0xf
	v_mov_b32_dpp v224, v171 row_shl:1 row_mask:0xf bank_mask:0xf
	v_mov_b32_dpp v225, v172 row_shl:1 row_mask:0xf bank_mask:0xf
	v_mov_b32_dpp v226, v173 row_shl:1 row_mask:0xf bank_mask:0xf
	v_cndmask_b32_e64 v208, v208, v170, s[48:49]
	v_cndmask_b32_e64 v209, v209, v171, s[48:49]
	v_cndmask_b32_e64 v210, v210, v172, s[48:49]
	v_cndmask_b32_e64 v211, v211, v173, s[48:49]
	v_cndmask_b32_e64 v204, v204, v223, s[46:47]
	v_cndmask_b32_e64 v205, v205, v224, s[46:47]
	v_cndmask_b32_e64 v206, v206, v225, s[46:47]
	v_cndmask_b32_e64 v207, v207, v226, s[46:47]
	s_mov_b64 exec, s[48:49]
	v_add_u32_e32 v222, 0xf2000, v190
	global_load_dwordx4 v[170:173], v222, s[16:17]
	s_mov_b64 exec, -1
	v_pk_fma_f32 v[212:213], v[134:135], v[204:205], v[212:213]
	v_pk_fma_f32 v[214:215], v[136:137], v[206:207], v[214:215]
	v_pk_fma_f32 v[212:213], v[130:131], v[208:209], v[212:213]
	v_pk_fma_f32 v[214:215], v[132:133], v[210:211], v[214:215]
	v_pk_fma_f32 v[216:217], v[154:155], v[82:83], v[158:159]
	v_pk_fma_f32 v[218:219], v[156:157], v[84:85], v[160:161]
	s_nop 2
	v_mov_b32_dpp v204, v82 row_shr:1 row_mask:0xf bank_mask:0xf
	v_mov_b32_dpp v208, v82 row_shr:2 row_mask:0xf bank_mask:0xf
	v_mov_b32_dpp v205, v83 row_shr:1 row_mask:0xf bank_mask:0xf
	v_mov_b32_dpp v209, v83 row_shr:2 row_mask:0xf bank_mask:0xf
	v_mov_b32_dpp v206, v84 row_shr:1 row_mask:0xf bank_mask:0xf
	v_mov_b32_dpp v210, v84 row_shr:2 row_mask:0xf bank_mask:0xf
	v_mov_b32_dpp v207, v85 row_shr:1 row_mask:0xf bank_mask:0xf
	v_mov_b32_dpp v211, v85 row_shr:2 row_mask:0xf bank_mask:0xf
	s_waitcnt vmcnt(28)
	v_mov_b32_dpp v223, v174 row_shl:1 row_mask:0xf bank_mask:0xf
	v_mov_b32_dpp v224, v175 row_shl:1 row_mask:0xf bank_mask:0xf
	v_mov_b32_dpp v225, v176 row_shl:1 row_mask:0xf bank_mask:0xf
	v_mov_b32_dpp v226, v177 row_shl:1 row_mask:0xf bank_mask:0xf
	v_cndmask_b32_e64 v208, v208, v174, s[48:49]
	v_cndmask_b32_e64 v209, v209, v175, s[48:49]
	v_cndmask_b32_e64 v210, v210, v176, s[48:49]
	v_cndmask_b32_e64 v211, v211, v177, s[48:49]
	v_cndmask_b32_e64 v204, v204, v223, s[46:47]
	v_cndmask_b32_e64 v205, v205, v224, s[46:47]
	v_cndmask_b32_e64 v206, v206, v225, s[46:47]
	v_cndmask_b32_e64 v207, v207, v226, s[46:47]
	s_mov_b64 exec, s[48:49]
	v_add_u32_e32 v222, 0xf4c00, v190
	global_load_dwordx4 v[174:177], v222, s[16:17]
	s_mov_b64 exec, -1
	v_pk_fma_f32 v[216:217], v[150:151], v[204:205], v[216:217]
	v_pk_fma_f32 v[218:219], v[152:153], v[206:207], v[218:219]
	v_pk_fma_f32 v[216:217], v[146:147], v[208:209], v[216:217]
	v_pk_fma_f32 v[218:219], v[148:149], v[210:211], v[218:219]
	v_mul_f32_e32 v204, 0xbfb8aa3b, v216
	v_mul_f32_e32 v205, 0xbfb8aa3b, v217
	v_mul_f32_e32 v206, 0xbfb8aa3b, v218
	v_mul_f32_e32 v207, 0xbfb8aa3b, v219
	v_exp_f32_e32 v204, v204
	v_exp_f32_e32 v205, v205
	v_exp_f32_e32 v206, v206
	v_exp_f32_e32 v207, v207
	v_add_f32_e32 v204, 1.0, v204
	v_add_f32_e32 v205, 1.0, v205
	v_add_f32_e32 v206, 1.0, v206
	v_add_f32_e32 v207, 1.0, v207
	v_rcp_f32_e32 v204, v204
	v_rcp_f32_e32 v205, v205
	v_rcp_f32_e32 v206, v206
	v_rcp_f32_e32 v207, v207
	v_mul_f32_e32 v204, v216, v204
	v_mul_f32_e32 v205, v217, v205
	v_mul_f32_e32 v206, v218, v206
	v_mul_f32_e32 v207, v219, v207
	v_mul_f32_e32 v204, v212, v204
	v_mul_f32_e32 v205, v213, v205
	v_mul_f32_e32 v206, v214, v206
	v_mul_f32_e32 v207, v215, v207
	v_cvt_pk_bf16_f32 v86, v204, v205
	v_cvt_pk_bf16_f32 v87, v206, v207
	v_pk_fma_f32 v[212:213], v[138:139], v[78:79], v[142:143]
	v_pk_fma_f32 v[214:215], v[140:141], v[80:81], v[144:145]
	s_nop 2
	v_mov_b32_dpp v204, v78 row_shr:1 row_mask:0xf bank_mask:0xf
	v_mov_b32_dpp v208, v78 row_shr:2 row_mask:0xf bank_mask:0xf
	v_mov_b32_dpp v205, v79 row_shr:1 row_mask:0xf bank_mask:0xf
	v_mov_b32_dpp v209, v79 row_shr:2 row_mask:0xf bank_mask:0xf
	v_mov_b32_dpp v206, v80 row_shr:1 row_mask:0xf bank_mask:0xf
	v_mov_b32_dpp v210, v80 row_shr:2 row_mask:0xf bank_mask:0xf
	v_mov_b32_dpp v207, v81 row_shr:1 row_mask:0xf bank_mask:0xf
	v_mov_b32_dpp v211, v81 row_shr:2 row_mask:0xf bank_mask:0xf
	s_waitcnt vmcnt(3)
	v_mov_b32_dpp v223, v162 row_shl:1 row_mask:0xf bank_mask:0xf
	v_mov_b32_dpp v224, v163 row_shl:1 row_mask:0xf bank_mask:0xf
	v_mov_b32_dpp v225, v164 row_shl:1 row_mask:0xf bank_mask:0xf
	v_mov_b32_dpp v226, v165 row_shl:1 row_mask:0xf bank_mask:0xf
	v_cndmask_b32_e64 v208, v208, v162, s[48:49]
	v_cndmask_b32_e64 v209, v209, v163, s[48:49]
	v_cndmask_b32_e64 v210, v210, v164, s[48:49]
	v_cndmask_b32_e64 v211, v211, v165, s[48:49]
	v_cndmask_b32_e64 v204, v204, v223, s[46:47]
	v_cndmask_b32_e64 v205, v205, v224, s[46:47]
	v_cndmask_b32_e64 v206, v206, v225, s[46:47]
	v_cndmask_b32_e64 v207, v207, v226, s[46:47]
	s_mov_b64 exec, s[48:49]
	global_load_dwordx4 v[162:165], v190, s[16:17] offset:16
	s_mov_b64 exec, -1
	v_pk_fma_f32 v[212:213], v[134:135], v[204:205], v[212:213]
	v_pk_fma_f32 v[214:215], v[136:137], v[206:207], v[214:215]
	v_pk_fma_f32 v[212:213], v[130:131], v[208:209], v[212:213]
	v_pk_fma_f32 v[214:215], v[132:133], v[210:211], v[214:215]
	v_pk_fma_f32 v[216:217], v[154:155], v[74:75], v[158:159]
	v_pk_fma_f32 v[218:219], v[156:157], v[76:77], v[160:161]
	s_nop 2
	v_mov_b32_dpp v204, v74 row_shr:1 row_mask:0xf bank_mask:0xf
	v_mov_b32_dpp v208, v74 row_shr:2 row_mask:0xf bank_mask:0xf
	v_mov_b32_dpp v205, v75 row_shr:1 row_mask:0xf bank_mask:0xf
	v_mov_b32_dpp v209, v75 row_shr:2 row_mask:0xf bank_mask:0xf
	v_mov_b32_dpp v206, v76 row_shr:1 row_mask:0xf bank_mask:0xf
	v_mov_b32_dpp v210, v76 row_shr:2 row_mask:0xf bank_mask:0xf
	v_mov_b32_dpp v207, v77 row_shr:1 row_mask:0xf bank_mask:0xf
	v_mov_b32_dpp v211, v77 row_shr:2 row_mask:0xf bank_mask:0xf
	s_waitcnt vmcnt(3)
	v_mov_b32_dpp v223, v166 row_shl:1 row_mask:0xf bank_mask:0xf
	v_mov_b32_dpp v224, v167 row_shl:1 row_mask:0xf bank_mask:0xf
	v_mov_b32_dpp v225, v168 row_shl:1 row_mask:0xf bank_mask:0xf
	v_mov_b32_dpp v226, v169 row_shl:1 row_mask:0xf bank_mask:0xf
	v_cndmask_b32_e64 v208, v208, v166, s[48:49]
	v_cndmask_b32_e64 v209, v209, v167, s[48:49]
	v_cndmask_b32_e64 v210, v210, v168, s[48:49]
	v_cndmask_b32_e64 v211, v211, v169, s[48:49]
	v_cndmask_b32_e64 v204, v204, v223, s[46:47]
	v_cndmask_b32_e64 v205, v205, v224, s[46:47]
	v_cndmask_b32_e64 v206, v206, v225, s[46:47]
	v_cndmask_b32_e64 v207, v207, v226, s[46:47]
	s_mov_b64 exec, s[48:49]
	v_add_u32_e32 v222, 0x2c00, v190
	global_load_dwordx4 v[166:169], v222, s[16:17] offset:16
	s_mov_b64 exec, -1
	v_pk_fma_f32 v[216:217], v[150:151], v[204:205], v[216:217]
	v_pk_fma_f32 v[218:219], v[152:153], v[206:207], v[218:219]
	v_pk_fma_f32 v[216:217], v[146:147], v[208:209], v[216:217]
	v_pk_fma_f32 v[218:219], v[148:149], v[210:211], v[218:219]
	v_mul_f32_e32 v204, 0xbfb8aa3b, v216
	v_mul_f32_e32 v205, 0xbfb8aa3b, v217
	v_mul_f32_e32 v206, 0xbfb8aa3b, v218
	v_mul_f32_e32 v207, 0xbfb8aa3b, v219
	v_exp_f32_e32 v204, v204
	v_exp_f32_e32 v205, v205
	v_exp_f32_e32 v206, v206
	v_exp_f32_e32 v207, v207
	v_add_f32_e32 v204, 1.0, v204
	v_add_f32_e32 v205, 1.0, v205
	v_add_f32_e32 v206, 1.0, v206
	v_add_f32_e32 v207, 1.0, v207
	v_rcp_f32_e32 v204, v204
	v_rcp_f32_e32 v205, v205
	v_rcp_f32_e32 v206, v206
	v_rcp_f32_e32 v207, v207
	v_mul_f32_e32 v204, v216, v204
	v_mul_f32_e32 v205, v217, v205
	v_mul_f32_e32 v206, v218, v206
	v_mul_f32_e32 v207, v219, v207
	v_mul_f32_e32 v204, v212, v204
	v_mul_f32_e32 v205, v213, v205
	v_mul_f32_e32 v206, v214, v206
	v_mul_f32_e32 v207, v215, v207
	v_cvt_pk_bf16_f32 v78, v204, v205
	v_cvt_pk_bf16_f32 v79, v206, v207
	v_pk_fma_f32 v[212:213], v[138:139], v[70:71], v[142:143]
	v_pk_fma_f32 v[214:215], v[140:141], v[72:73], v[144:145]
	s_nop 2
	v_mov_b32_dpp v204, v70 row_shr:1 row_mask:0xf bank_mask:0xf
	v_mov_b32_dpp v208, v70 row_shr:2 row_mask:0xf bank_mask:0xf
	v_mov_b32_dpp v205, v71 row_shr:1 row_mask:0xf bank_mask:0xf
	v_mov_b32_dpp v209, v71 row_shr:2 row_mask:0xf bank_mask:0xf
	v_mov_b32_dpp v206, v72 row_shr:1 row_mask:0xf bank_mask:0xf
	v_mov_b32_dpp v210, v72 row_shr:2 row_mask:0xf bank_mask:0xf
	v_mov_b32_dpp v207, v73 row_shr:1 row_mask:0xf bank_mask:0xf
	v_mov_b32_dpp v211, v73 row_shr:2 row_mask:0xf bank_mask:0xf
	s_waitcnt vmcnt(3)
	v_mov_b32_dpp v223, v170 row_shl:1 row_mask:0xf bank_mask:0xf
	v_mov_b32_dpp v224, v171 row_shl:1 row_mask:0xf bank_mask:0xf
	v_mov_b32_dpp v225, v172 row_shl:1 row_mask:0xf bank_mask:0xf
	v_mov_b32_dpp v226, v173 row_shl:1 row_mask:0xf bank_mask:0xf
	v_cndmask_b32_e64 v208, v208, v170, s[48:49]
	v_cndmask_b32_e64 v209, v209, v171, s[48:49]
	v_cndmask_b32_e64 v210, v210, v172, s[48:49]
	v_cndmask_b32_e64 v211, v211, v173, s[48:49]
	v_cndmask_b32_e64 v204, v204, v223, s[46:47]
	v_cndmask_b32_e64 v205, v205, v224, s[46:47]
	v_cndmask_b32_e64 v206, v206, v225, s[46:47]
	v_cndmask_b32_e64 v207, v207, v226, s[46:47]
	s_mov_b64 exec, s[48:49]
	v_add_u32_e32 v222, 0x16000, v190
	global_load_dwordx4 v[170:173], v222, s[16:17] offset:16
	s_mov_b64 exec, -1
	v_pk_fma_f32 v[212:213], v[134:135], v[204:205], v[212:213]
	v_pk_fma_f32 v[214:215], v[136:137], v[206:207], v[214:215]
	v_pk_fma_f32 v[212:213], v[130:131], v[208:209], v[212:213]
	v_pk_fma_f32 v[214:215], v[132:133], v[210:211], v[214:215]
	v_pk_fma_f32 v[216:217], v[154:155], v[66:67], v[158:159]
	v_pk_fma_f32 v[218:219], v[156:157], v[68:69], v[160:161]
	s_nop 2
	v_mov_b32_dpp v204, v66 row_shr:1 row_mask:0xf bank_mask:0xf
	v_mov_b32_dpp v208, v66 row_shr:2 row_mask:0xf bank_mask:0xf
	v_mov_b32_dpp v205, v67 row_shr:1 row_mask:0xf bank_mask:0xf
	v_mov_b32_dpp v209, v67 row_shr:2 row_mask:0xf bank_mask:0xf
	v_mov_b32_dpp v206, v68 row_shr:1 row_mask:0xf bank_mask:0xf
	v_mov_b32_dpp v210, v68 row_shr:2 row_mask:0xf bank_mask:0xf
	v_mov_b32_dpp v207, v69 row_shr:1 row_mask:0xf bank_mask:0xf
	v_mov_b32_dpp v211, v69 row_shr:2 row_mask:0xf bank_mask:0xf
	s_waitcnt vmcnt(3)
	v_mov_b32_dpp v223, v174 row_shl:1 row_mask:0xf bank_mask:0xf
	v_mov_b32_dpp v224, v175 row_shl:1 row_mask:0xf bank_mask:0xf
	v_mov_b32_dpp v225, v176 row_shl:1 row_mask:0xf bank_mask:0xf
	v_mov_b32_dpp v226, v177 row_shl:1 row_mask:0xf bank_mask:0xf
	v_cndmask_b32_e64 v208, v208, v174, s[48:49]
	v_cndmask_b32_e64 v209, v209, v175, s[48:49]
	v_cndmask_b32_e64 v210, v210, v176, s[48:49]
	v_cndmask_b32_e64 v211, v211, v177, s[48:49]
	v_cndmask_b32_e64 v204, v204, v223, s[46:47]
	v_cndmask_b32_e64 v205, v205, v224, s[46:47]
	v_cndmask_b32_e64 v206, v206, v225, s[46:47]
	v_cndmask_b32_e64 v207, v207, v226, s[46:47]
	s_mov_b64 exec, s[48:49]
	v_add_u32_e32 v222, 0x18c00, v190
	global_load_dwordx4 v[174:177], v222, s[16:17] offset:16
	s_mov_b64 exec, -1
	v_pk_fma_f32 v[216:217], v[150:151], v[204:205], v[216:217]
	v_pk_fma_f32 v[218:219], v[152:153], v[206:207], v[218:219]
	v_pk_fma_f32 v[216:217], v[146:147], v[208:209], v[216:217]
	v_pk_fma_f32 v[218:219], v[148:149], v[210:211], v[218:219]
	v_mul_f32_e32 v204, 0xbfb8aa3b, v216
	v_mul_f32_e32 v205, 0xbfb8aa3b, v217
	v_mul_f32_e32 v206, 0xbfb8aa3b, v218
	v_mul_f32_e32 v207, 0xbfb8aa3b, v219
	v_exp_f32_e32 v204, v204
	v_exp_f32_e32 v205, v205
	v_exp_f32_e32 v206, v206
	v_exp_f32_e32 v207, v207
	v_add_f32_e32 v204, 1.0, v204
	v_add_f32_e32 v205, 1.0, v205
	v_add_f32_e32 v206, 1.0, v206
	v_add_f32_e32 v207, 1.0, v207
	v_rcp_f32_e32 v204, v204
	v_rcp_f32_e32 v205, v205
	v_rcp_f32_e32 v206, v206
	v_rcp_f32_e32 v207, v207
	v_mul_f32_e32 v204, v216, v204
	v_mul_f32_e32 v205, v217, v205
	v_mul_f32_e32 v206, v218, v206
	v_mul_f32_e32 v207, v219, v207
	v_mul_f32_e32 v204, v212, v204
	v_mul_f32_e32 v205, v213, v205
	v_mul_f32_e32 v206, v214, v206
	v_mul_f32_e32 v207, v215, v207
	v_cvt_pk_bf16_f32 v70, v204, v205
	v_cvt_pk_bf16_f32 v71, v206, v207
	s_waitcnt vmcnt(24)
	v_pk_fma_f32 v[212:213], v[106:107], v[62:63], v[110:111]
	v_pk_fma_f32 v[214:215], v[108:109], v[64:65], v[112:113]
	s_nop 2
	v_mov_b32_dpp v204, v62 row_shr:1 row_mask:0xf bank_mask:0xf
	v_mov_b32_dpp v208, v62 row_shr:2 row_mask:0xf bank_mask:0xf
	v_mov_b32_dpp v205, v63 row_shr:1 row_mask:0xf bank_mask:0xf
	v_mov_b32_dpp v209, v63 row_shr:2 row_mask:0xf bank_mask:0xf
	v_mov_b32_dpp v206, v64 row_shr:1 row_mask:0xf bank_mask:0xf
	v_mov_b32_dpp v210, v64 row_shr:2 row_mask:0xf bank_mask:0xf
	v_mov_b32_dpp v207, v65 row_shr:1 row_mask:0xf bank_mask:0xf
	v_mov_b32_dpp v211, v65 row_shr:2 row_mask:0xf bank_mask:0xf
	s_waitcnt vmcnt(3)
	v_mov_b32_dpp v223, v162 row_shl:1 row_mask:0xf bank_mask:0xf
	v_mov_b32_dpp v224, v163 row_shl:1 row_mask:0xf bank_mask:0xf
	v_mov_b32_dpp v225, v164 row_shl:1 row_mask:0xf bank_mask:0xf
	v_mov_b32_dpp v226, v165 row_shl:1 row_mask:0xf bank_mask:0xf
	v_cndmask_b32_e64 v208, v208, v162, s[48:49]
	v_cndmask_b32_e64 v209, v209, v163, s[48:49]
	v_cndmask_b32_e64 v210, v210, v164, s[48:49]
	v_cndmask_b32_e64 v211, v211, v165, s[48:49]
	v_cndmask_b32_e64 v204, v204, v223, s[46:47]
	v_cndmask_b32_e64 v205, v205, v224, s[46:47]
	v_cndmask_b32_e64 v206, v206, v225, s[46:47]
	v_cndmask_b32_e64 v207, v207, v226, s[46:47]
	s_mov_b64 exec, s[48:49]
	v_add_u32_e32 v222, 0x2c000, v190
	global_load_dwordx4 v[162:165], v222, s[16:17] offset:16
	s_mov_b64 exec, -1
	v_pk_fma_f32 v[212:213], v[102:103], v[204:205], v[212:213]
	v_pk_fma_f32 v[214:215], v[104:105], v[206:207], v[214:215]
	v_pk_fma_f32 v[212:213], v[98:99], v[208:209], v[212:213]
	v_pk_fma_f32 v[214:215], v[100:101], v[210:211], v[214:215]
	v_pk_fma_f32 v[216:217], v[122:123], v[58:59], v[126:127]
	v_pk_fma_f32 v[218:219], v[124:125], v[60:61], v[128:129]
	s_nop 2
	v_mov_b32_dpp v204, v58 row_shr:1 row_mask:0xf bank_mask:0xf
	v_mov_b32_dpp v208, v58 row_shr:2 row_mask:0xf bank_mask:0xf
	v_mov_b32_dpp v205, v59 row_shr:1 row_mask:0xf bank_mask:0xf
	v_mov_b32_dpp v209, v59 row_shr:2 row_mask:0xf bank_mask:0xf
	v_mov_b32_dpp v206, v60 row_shr:1 row_mask:0xf bank_mask:0xf
	v_mov_b32_dpp v210, v60 row_shr:2 row_mask:0xf bank_mask:0xf
	v_mov_b32_dpp v207, v61 row_shr:1 row_mask:0xf bank_mask:0xf
	v_mov_b32_dpp v211, v61 row_shr:2 row_mask:0xf bank_mask:0xf
	s_waitcnt vmcnt(3)
	v_mov_b32_dpp v223, v166 row_shl:1 row_mask:0xf bank_mask:0xf
	v_mov_b32_dpp v224, v167 row_shl:1 row_mask:0xf bank_mask:0xf
	v_mov_b32_dpp v225, v168 row_shl:1 row_mask:0xf bank_mask:0xf
	v_mov_b32_dpp v226, v169 row_shl:1 row_mask:0xf bank_mask:0xf
	v_cndmask_b32_e64 v208, v208, v166, s[48:49]
	v_cndmask_b32_e64 v209, v209, v167, s[48:49]
	v_cndmask_b32_e64 v210, v210, v168, s[48:49]
	v_cndmask_b32_e64 v211, v211, v169, s[48:49]
	v_cndmask_b32_e64 v204, v204, v223, s[46:47]
	v_cndmask_b32_e64 v205, v205, v224, s[46:47]
	v_cndmask_b32_e64 v206, v206, v225, s[46:47]
	v_cndmask_b32_e64 v207, v207, v226, s[46:47]
	s_mov_b64 exec, s[48:49]
	v_add_u32_e32 v222, 0x2ec00, v190
	global_load_dwordx4 v[166:169], v222, s[16:17] offset:16
	s_mov_b64 exec, -1
	v_pk_fma_f32 v[216:217], v[118:119], v[204:205], v[216:217]
	v_pk_fma_f32 v[218:219], v[120:121], v[206:207], v[218:219]
	v_pk_fma_f32 v[216:217], v[114:115], v[208:209], v[216:217]
	v_pk_fma_f32 v[218:219], v[116:117], v[210:211], v[218:219]
	v_mul_f32_e32 v204, 0xbfb8aa3b, v216
	v_mul_f32_e32 v205, 0xbfb8aa3b, v217
	v_mul_f32_e32 v206, 0xbfb8aa3b, v218
	v_mul_f32_e32 v207, 0xbfb8aa3b, v219
	v_exp_f32_e32 v204, v204
	v_exp_f32_e32 v205, v205
	v_exp_f32_e32 v206, v206
	v_exp_f32_e32 v207, v207
	v_add_f32_e32 v204, 1.0, v204
	v_add_f32_e32 v205, 1.0, v205
	v_add_f32_e32 v206, 1.0, v206
	v_add_f32_e32 v207, 1.0, v207
	v_rcp_f32_e32 v204, v204
	v_rcp_f32_e32 v205, v205
	v_rcp_f32_e32 v206, v206
	v_rcp_f32_e32 v207, v207
	v_mul_f32_e32 v204, v216, v204
	v_mul_f32_e32 v205, v217, v205
	v_mul_f32_e32 v206, v218, v206
	v_mul_f32_e32 v207, v219, v207
	v_mul_f32_e32 v204, v212, v204
	v_mul_f32_e32 v205, v213, v205
	v_mul_f32_e32 v206, v214, v206
	v_mul_f32_e32 v207, v215, v207
	v_cvt_pk_bf16_f32 v62, v204, v205
	v_cvt_pk_bf16_f32 v63, v206, v207
	v_pk_fma_f32 v[212:213], v[106:107], v[54:55], v[110:111]
	v_pk_fma_f32 v[214:215], v[108:109], v[56:57], v[112:113]
	s_nop 2
	v_mov_b32_dpp v204, v54 row_shr:1 row_mask:0xf bank_mask:0xf
	v_mov_b32_dpp v208, v54 row_shr:2 row_mask:0xf bank_mask:0xf
	v_mov_b32_dpp v205, v55 row_shr:1 row_mask:0xf bank_mask:0xf
	v_mov_b32_dpp v209, v55 row_shr:2 row_mask:0xf bank_mask:0xf
	v_mov_b32_dpp v206, v56 row_shr:1 row_mask:0xf bank_mask:0xf
	v_mov_b32_dpp v210, v56 row_shr:2 row_mask:0xf bank_mask:0xf
	v_mov_b32_dpp v207, v57 row_shr:1 row_mask:0xf bank_mask:0xf
	v_mov_b32_dpp v211, v57 row_shr:2 row_mask:0xf bank_mask:0xf
	s_waitcnt vmcnt(3)
	v_mov_b32_dpp v223, v170 row_shl:1 row_mask:0xf bank_mask:0xf
	v_mov_b32_dpp v224, v171 row_shl:1 row_mask:0xf bank_mask:0xf
	v_mov_b32_dpp v225, v172 row_shl:1 row_mask:0xf bank_mask:0xf
	v_mov_b32_dpp v226, v173 row_shl:1 row_mask:0xf bank_mask:0xf
	v_cndmask_b32_e64 v208, v208, v170, s[48:49]
	v_cndmask_b32_e64 v209, v209, v171, s[48:49]
	v_cndmask_b32_e64 v210, v210, v172, s[48:49]
	v_cndmask_b32_e64 v211, v211, v173, s[48:49]
	v_cndmask_b32_e64 v204, v204, v223, s[46:47]
	v_cndmask_b32_e64 v205, v205, v224, s[46:47]
	v_cndmask_b32_e64 v206, v206, v225, s[46:47]
	v_cndmask_b32_e64 v207, v207, v226, s[46:47]
	s_mov_b64 exec, s[48:49]
	v_add_u32_e32 v222, 0x42000, v190
	global_load_dwordx4 v[170:173], v222, s[16:17] offset:16
	s_mov_b64 exec, -1
	v_pk_fma_f32 v[212:213], v[102:103], v[204:205], v[212:213]
	v_pk_fma_f32 v[214:215], v[104:105], v[206:207], v[214:215]
	v_pk_fma_f32 v[212:213], v[98:99], v[208:209], v[212:213]
	v_pk_fma_f32 v[214:215], v[100:101], v[210:211], v[214:215]
	v_pk_fma_f32 v[216:217], v[122:123], v[50:51], v[126:127]
	v_pk_fma_f32 v[218:219], v[124:125], v[52:53], v[128:129]
	s_nop 2
	v_mov_b32_dpp v204, v50 row_shr:1 row_mask:0xf bank_mask:0xf
	v_mov_b32_dpp v208, v50 row_shr:2 row_mask:0xf bank_mask:0xf
	v_mov_b32_dpp v205, v51 row_shr:1 row_mask:0xf bank_mask:0xf
	v_mov_b32_dpp v209, v51 row_shr:2 row_mask:0xf bank_mask:0xf
	v_mov_b32_dpp v206, v52 row_shr:1 row_mask:0xf bank_mask:0xf
	v_mov_b32_dpp v210, v52 row_shr:2 row_mask:0xf bank_mask:0xf
	v_mov_b32_dpp v207, v53 row_shr:1 row_mask:0xf bank_mask:0xf
	v_mov_b32_dpp v211, v53 row_shr:2 row_mask:0xf bank_mask:0xf
	s_waitcnt vmcnt(3)
	v_mov_b32_dpp v223, v174 row_shl:1 row_mask:0xf bank_mask:0xf
	v_mov_b32_dpp v224, v175 row_shl:1 row_mask:0xf bank_mask:0xf
	v_mov_b32_dpp v225, v176 row_shl:1 row_mask:0xf bank_mask:0xf
	v_mov_b32_dpp v226, v177 row_shl:1 row_mask:0xf bank_mask:0xf
	v_cndmask_b32_e64 v208, v208, v174, s[48:49]
	v_cndmask_b32_e64 v209, v209, v175, s[48:49]
	v_cndmask_b32_e64 v210, v210, v176, s[48:49]
	v_cndmask_b32_e64 v211, v211, v177, s[48:49]
	v_cndmask_b32_e64 v204, v204, v223, s[46:47]
	v_cndmask_b32_e64 v205, v205, v224, s[46:47]
	v_cndmask_b32_e64 v206, v206, v225, s[46:47]
	v_cndmask_b32_e64 v207, v207, v226, s[46:47]
	s_mov_b64 exec, s[48:49]
	v_add_u32_e32 v222, 0x44c00, v190
	global_load_dwordx4 v[174:177], v222, s[16:17] offset:16
	s_mov_b64 exec, -1
	v_pk_fma_f32 v[216:217], v[118:119], v[204:205], v[216:217]
	v_pk_fma_f32 v[218:219], v[120:121], v[206:207], v[218:219]
	v_pk_fma_f32 v[216:217], v[114:115], v[208:209], v[216:217]
	v_pk_fma_f32 v[218:219], v[116:117], v[210:211], v[218:219]
	v_mul_f32_e32 v204, 0xbfb8aa3b, v216
	v_mul_f32_e32 v205, 0xbfb8aa3b, v217
	v_mul_f32_e32 v206, 0xbfb8aa3b, v218
	v_mul_f32_e32 v207, 0xbfb8aa3b, v219
	v_exp_f32_e32 v204, v204
	v_exp_f32_e32 v205, v205
	v_exp_f32_e32 v206, v206
	v_exp_f32_e32 v207, v207
	v_add_f32_e32 v204, 1.0, v204
	v_add_f32_e32 v205, 1.0, v205
	v_add_f32_e32 v206, 1.0, v206
	v_add_f32_e32 v207, 1.0, v207
	v_rcp_f32_e32 v204, v204
	v_rcp_f32_e32 v205, v205
	v_rcp_f32_e32 v206, v206
	v_rcp_f32_e32 v207, v207
	v_mul_f32_e32 v204, v216, v204
	v_mul_f32_e32 v205, v217, v205
	v_mul_f32_e32 v206, v218, v206
	v_mul_f32_e32 v207, v219, v207
	v_mul_f32_e32 v204, v212, v204
	v_mul_f32_e32 v205, v213, v205
	v_mul_f32_e32 v206, v214, v206
	v_mul_f32_e32 v207, v215, v207
	v_cvt_pk_bf16_f32 v54, v204, v205
	v_cvt_pk_bf16_f32 v55, v206, v207
	v_pk_fma_f32 v[212:213], v[106:107], v[46:47], v[110:111]
	v_pk_fma_f32 v[214:215], v[108:109], v[48:49], v[112:113]
	s_nop 2
	v_mov_b32_dpp v204, v46 row_shr:1 row_mask:0xf bank_mask:0xf
	v_mov_b32_dpp v208, v46 row_shr:2 row_mask:0xf bank_mask:0xf
	v_mov_b32_dpp v205, v47 row_shr:1 row_mask:0xf bank_mask:0xf
	v_mov_b32_dpp v209, v47 row_shr:2 row_mask:0xf bank_mask:0xf
	v_mov_b32_dpp v206, v48 row_shr:1 row_mask:0xf bank_mask:0xf
	v_mov_b32_dpp v210, v48 row_shr:2 row_mask:0xf bank_mask:0xf
	v_mov_b32_dpp v207, v49 row_shr:1 row_mask:0xf bank_mask:0xf
	v_mov_b32_dpp v211, v49 row_shr:2 row_mask:0xf bank_mask:0xf
	s_waitcnt vmcnt(3)
	v_mov_b32_dpp v223, v162 row_shl:1 row_mask:0xf bank_mask:0xf
	v_mov_b32_dpp v224, v163 row_shl:1 row_mask:0xf bank_mask:0xf
	v_mov_b32_dpp v225, v164 row_shl:1 row_mask:0xf bank_mask:0xf
	v_mov_b32_dpp v226, v165 row_shl:1 row_mask:0xf bank_mask:0xf
	v_cndmask_b32_e64 v208, v208, v162, s[48:49]
	v_cndmask_b32_e64 v209, v209, v163, s[48:49]
	v_cndmask_b32_e64 v210, v210, v164, s[48:49]
	v_cndmask_b32_e64 v211, v211, v165, s[48:49]
	v_cndmask_b32_e64 v204, v204, v223, s[46:47]
	v_cndmask_b32_e64 v205, v205, v224, s[46:47]
	v_cndmask_b32_e64 v206, v206, v225, s[46:47]
	v_cndmask_b32_e64 v207, v207, v226, s[46:47]
	s_mov_b64 exec, s[48:49]
	v_add_u32_e32 v222, 0xb0000, v190
	global_load_dwordx4 v[162:165], v222, s[16:17] offset:16
	s_mov_b64 exec, -1
	v_pk_fma_f32 v[212:213], v[102:103], v[204:205], v[212:213]
	v_pk_fma_f32 v[214:215], v[104:105], v[206:207], v[214:215]
	v_pk_fma_f32 v[212:213], v[98:99], v[208:209], v[212:213]
	v_pk_fma_f32 v[214:215], v[100:101], v[210:211], v[214:215]
	v_pk_fma_f32 v[216:217], v[122:123], v[42:43], v[126:127]
	v_pk_fma_f32 v[218:219], v[124:125], v[44:45], v[128:129]
	s_nop 2
	v_mov_b32_dpp v204, v42 row_shr:1 row_mask:0xf bank_mask:0xf
	v_mov_b32_dpp v208, v42 row_shr:2 row_mask:0xf bank_mask:0xf
	v_mov_b32_dpp v205, v43 row_shr:1 row_mask:0xf bank_mask:0xf
	v_mov_b32_dpp v209, v43 row_shr:2 row_mask:0xf bank_mask:0xf
	v_mov_b32_dpp v206, v44 row_shr:1 row_mask:0xf bank_mask:0xf
	v_mov_b32_dpp v210, v44 row_shr:2 row_mask:0xf bank_mask:0xf
	v_mov_b32_dpp v207, v45 row_shr:1 row_mask:0xf bank_mask:0xf
	v_mov_b32_dpp v211, v45 row_shr:2 row_mask:0xf bank_mask:0xf
	s_waitcnt vmcnt(3)
	v_mov_b32_dpp v223, v166 row_shl:1 row_mask:0xf bank_mask:0xf
	v_mov_b32_dpp v224, v167 row_shl:1 row_mask:0xf bank_mask:0xf
	v_mov_b32_dpp v225, v168 row_shl:1 row_mask:0xf bank_mask:0xf
	v_mov_b32_dpp v226, v169 row_shl:1 row_mask:0xf bank_mask:0xf
	v_cndmask_b32_e64 v208, v208, v166, s[48:49]
	v_cndmask_b32_e64 v209, v209, v167, s[48:49]
	v_cndmask_b32_e64 v210, v210, v168, s[48:49]
	v_cndmask_b32_e64 v211, v211, v169, s[48:49]
	v_cndmask_b32_e64 v204, v204, v223, s[46:47]
	v_cndmask_b32_e64 v205, v205, v224, s[46:47]
	v_cndmask_b32_e64 v206, v206, v225, s[46:47]
	v_cndmask_b32_e64 v207, v207, v226, s[46:47]
	s_mov_b64 exec, s[48:49]
	v_add_u32_e32 v222, 0xb2c00, v190
	global_load_dwordx4 v[166:169], v222, s[16:17] offset:16
	s_mov_b64 exec, -1
	v_pk_fma_f32 v[216:217], v[118:119], v[204:205], v[216:217]
	v_pk_fma_f32 v[218:219], v[120:121], v[206:207], v[218:219]
	v_pk_fma_f32 v[216:217], v[114:115], v[208:209], v[216:217]
	v_pk_fma_f32 v[218:219], v[116:117], v[210:211], v[218:219]
	v_mul_f32_e32 v204, 0xbfb8aa3b, v216
	v_mul_f32_e32 v205, 0xbfb8aa3b, v217
	v_mul_f32_e32 v206, 0xbfb8aa3b, v218
	v_mul_f32_e32 v207, 0xbfb8aa3b, v219
	v_exp_f32_e32 v204, v204
	v_exp_f32_e32 v205, v205
	v_exp_f32_e32 v206, v206
	v_exp_f32_e32 v207, v207
	v_add_f32_e32 v204, 1.0, v204
	v_add_f32_e32 v205, 1.0, v205
	v_add_f32_e32 v206, 1.0, v206
	v_add_f32_e32 v207, 1.0, v207
	v_rcp_f32_e32 v204, v204
	v_rcp_f32_e32 v205, v205
	v_rcp_f32_e32 v206, v206
	v_rcp_f32_e32 v207, v207
	v_mul_f32_e32 v204, v216, v204
	v_mul_f32_e32 v205, v217, v205
	v_mul_f32_e32 v206, v218, v206
	v_mul_f32_e32 v207, v219, v207
	v_mul_f32_e32 v204, v212, v204
	v_mul_f32_e32 v205, v213, v205
	v_mul_f32_e32 v206, v214, v206
	v_mul_f32_e32 v207, v215, v207
	v_cvt_pk_bf16_f32 v46, v204, v205
	v_cvt_pk_bf16_f32 v47, v206, v207
	v_pk_fma_f32 v[212:213], v[106:107], v[38:39], v[110:111]
	v_pk_fma_f32 v[214:215], v[108:109], v[40:41], v[112:113]
	s_nop 2
	v_mov_b32_dpp v204, v38 row_shr:1 row_mask:0xf bank_mask:0xf
	v_mov_b32_dpp v208, v38 row_shr:2 row_mask:0xf bank_mask:0xf
	v_mov_b32_dpp v205, v39 row_shr:1 row_mask:0xf bank_mask:0xf
	v_mov_b32_dpp v209, v39 row_shr:2 row_mask:0xf bank_mask:0xf
	v_mov_b32_dpp v206, v40 row_shr:1 row_mask:0xf bank_mask:0xf
	v_mov_b32_dpp v210, v40 row_shr:2 row_mask:0xf bank_mask:0xf
	v_mov_b32_dpp v207, v41 row_shr:1 row_mask:0xf bank_mask:0xf
	v_mov_b32_dpp v211, v41 row_shr:2 row_mask:0xf bank_mask:0xf
	s_waitcnt vmcnt(3)
	v_mov_b32_dpp v223, v170 row_shl:1 row_mask:0xf bank_mask:0xf
	v_mov_b32_dpp v224, v171 row_shl:1 row_mask:0xf bank_mask:0xf
	v_mov_b32_dpp v225, v172 row_shl:1 row_mask:0xf bank_mask:0xf
	v_mov_b32_dpp v226, v173 row_shl:1 row_mask:0xf bank_mask:0xf
	v_cndmask_b32_e64 v208, v208, v170, s[48:49]
	v_cndmask_b32_e64 v209, v209, v171, s[48:49]
	v_cndmask_b32_e64 v210, v210, v172, s[48:49]
	v_cndmask_b32_e64 v211, v211, v173, s[48:49]
	v_cndmask_b32_e64 v204, v204, v223, s[46:47]
	v_cndmask_b32_e64 v205, v205, v224, s[46:47]
	v_cndmask_b32_e64 v206, v206, v225, s[46:47]
	v_cndmask_b32_e64 v207, v207, v226, s[46:47]
	s_mov_b64 exec, s[48:49]
	v_add_u32_e32 v222, 0xc6000, v190
	global_load_dwordx4 v[170:173], v222, s[16:17] offset:16
	s_mov_b64 exec, -1
	v_pk_fma_f32 v[212:213], v[102:103], v[204:205], v[212:213]
	v_pk_fma_f32 v[214:215], v[104:105], v[206:207], v[214:215]
	v_pk_fma_f32 v[212:213], v[98:99], v[208:209], v[212:213]
	v_pk_fma_f32 v[214:215], v[100:101], v[210:211], v[214:215]
	v_pk_fma_f32 v[216:217], v[122:123], v[34:35], v[126:127]
	v_pk_fma_f32 v[218:219], v[124:125], v[36:37], v[128:129]
	s_nop 2
	v_mov_b32_dpp v204, v34 row_shr:1 row_mask:0xf bank_mask:0xf
	v_mov_b32_dpp v208, v34 row_shr:2 row_mask:0xf bank_mask:0xf
	v_mov_b32_dpp v205, v35 row_shr:1 row_mask:0xf bank_mask:0xf
	v_mov_b32_dpp v209, v35 row_shr:2 row_mask:0xf bank_mask:0xf
	v_mov_b32_dpp v206, v36 row_shr:1 row_mask:0xf bank_mask:0xf
	v_mov_b32_dpp v210, v36 row_shr:2 row_mask:0xf bank_mask:0xf
	v_mov_b32_dpp v207, v37 row_shr:1 row_mask:0xf bank_mask:0xf
	v_mov_b32_dpp v211, v37 row_shr:2 row_mask:0xf bank_mask:0xf
	s_waitcnt vmcnt(3)
	v_mov_b32_dpp v223, v174 row_shl:1 row_mask:0xf bank_mask:0xf
	v_mov_b32_dpp v224, v175 row_shl:1 row_mask:0xf bank_mask:0xf
	v_mov_b32_dpp v225, v176 row_shl:1 row_mask:0xf bank_mask:0xf
	v_mov_b32_dpp v226, v177 row_shl:1 row_mask:0xf bank_mask:0xf
	v_cndmask_b32_e64 v208, v208, v174, s[48:49]
	v_cndmask_b32_e64 v209, v209, v175, s[48:49]
	v_cndmask_b32_e64 v210, v210, v176, s[48:49]
	v_cndmask_b32_e64 v211, v211, v177, s[48:49]
	v_cndmask_b32_e64 v204, v204, v223, s[46:47]
	v_cndmask_b32_e64 v205, v205, v224, s[46:47]
	v_cndmask_b32_e64 v206, v206, v225, s[46:47]
	v_cndmask_b32_e64 v207, v207, v226, s[46:47]
	s_mov_b64 exec, s[48:49]
	v_add_u32_e32 v222, 0xc8c00, v190
	global_load_dwordx4 v[174:177], v222, s[16:17] offset:16
	s_mov_b64 exec, -1
	v_pk_fma_f32 v[216:217], v[118:119], v[204:205], v[216:217]
	v_pk_fma_f32 v[218:219], v[120:121], v[206:207], v[218:219]
	v_pk_fma_f32 v[216:217], v[114:115], v[208:209], v[216:217]
	v_pk_fma_f32 v[218:219], v[116:117], v[210:211], v[218:219]
	v_mul_f32_e32 v204, 0xbfb8aa3b, v216
	v_mul_f32_e32 v205, 0xbfb8aa3b, v217
	v_mul_f32_e32 v206, 0xbfb8aa3b, v218
	v_mul_f32_e32 v207, 0xbfb8aa3b, v219
	v_exp_f32_e32 v204, v204
	v_exp_f32_e32 v205, v205
	v_exp_f32_e32 v206, v206
	v_exp_f32_e32 v207, v207
	v_add_f32_e32 v204, 1.0, v204
	v_add_f32_e32 v205, 1.0, v205
	v_add_f32_e32 v206, 1.0, v206
	v_add_f32_e32 v207, 1.0, v207
	v_rcp_f32_e32 v204, v204
	v_rcp_f32_e32 v205, v205
	v_rcp_f32_e32 v206, v206
	v_rcp_f32_e32 v207, v207
	v_mul_f32_e32 v204, v216, v204
	v_mul_f32_e32 v205, v217, v205
	v_mul_f32_e32 v206, v218, v206
	v_mul_f32_e32 v207, v219, v207
	v_mul_f32_e32 v204, v212, v204
	v_mul_f32_e32 v205, v213, v205
	v_mul_f32_e32 v206, v214, v206
	v_mul_f32_e32 v207, v215, v207
	v_cvt_pk_bf16_f32 v38, v204, v205
	v_cvt_pk_bf16_f32 v39, v206, v207
	v_pk_fma_f32 v[212:213], v[106:107], v[30:31], v[110:111]
	v_pk_fma_f32 v[214:215], v[108:109], v[32:33], v[112:113]
	s_nop 2
	v_mov_b32_dpp v204, v30 row_shr:1 row_mask:0xf bank_mask:0xf
	v_mov_b32_dpp v208, v30 row_shr:2 row_mask:0xf bank_mask:0xf
	v_mov_b32_dpp v205, v31 row_shr:1 row_mask:0xf bank_mask:0xf
	v_mov_b32_dpp v209, v31 row_shr:2 row_mask:0xf bank_mask:0xf
	v_mov_b32_dpp v206, v32 row_shr:1 row_mask:0xf bank_mask:0xf
	v_mov_b32_dpp v210, v32 row_shr:2 row_mask:0xf bank_mask:0xf
	v_mov_b32_dpp v207, v33 row_shr:1 row_mask:0xf bank_mask:0xf
	v_mov_b32_dpp v211, v33 row_shr:2 row_mask:0xf bank_mask:0xf
	s_waitcnt vmcnt(3)
	v_mov_b32_dpp v223, v162 row_shl:1 row_mask:0xf bank_mask:0xf
	v_mov_b32_dpp v224, v163 row_shl:1 row_mask:0xf bank_mask:0xf
	v_mov_b32_dpp v225, v164 row_shl:1 row_mask:0xf bank_mask:0xf
	v_mov_b32_dpp v226, v165 row_shl:1 row_mask:0xf bank_mask:0xf
	v_cndmask_b32_e64 v208, v208, v162, s[48:49]
	v_cndmask_b32_e64 v209, v209, v163, s[48:49]
	v_cndmask_b32_e64 v210, v210, v164, s[48:49]
	v_cndmask_b32_e64 v211, v211, v165, s[48:49]
	v_cndmask_b32_e64 v204, v204, v223, s[46:47]
	v_cndmask_b32_e64 v205, v205, v224, s[46:47]
	v_cndmask_b32_e64 v206, v206, v225, s[46:47]
	v_cndmask_b32_e64 v207, v207, v226, s[46:47]
	s_mov_b64 exec, s[48:49]
	v_add_u32_e32 v222, 0xdc000, v190
	global_load_dwordx4 v[162:165], v222, s[16:17] offset:16
	s_mov_b64 exec, -1
	v_pk_fma_f32 v[212:213], v[102:103], v[204:205], v[212:213]
	v_pk_fma_f32 v[214:215], v[104:105], v[206:207], v[214:215]
	v_pk_fma_f32 v[212:213], v[98:99], v[208:209], v[212:213]
	v_pk_fma_f32 v[214:215], v[100:101], v[210:211], v[214:215]
	v_pk_fma_f32 v[216:217], v[122:123], v[26:27], v[126:127]
	v_pk_fma_f32 v[218:219], v[124:125], v[28:29], v[128:129]
	s_nop 2
	v_mov_b32_dpp v204, v26 row_shr:1 row_mask:0xf bank_mask:0xf
	v_mov_b32_dpp v208, v26 row_shr:2 row_mask:0xf bank_mask:0xf
	v_mov_b32_dpp v205, v27 row_shr:1 row_mask:0xf bank_mask:0xf
	v_mov_b32_dpp v209, v27 row_shr:2 row_mask:0xf bank_mask:0xf
	v_mov_b32_dpp v206, v28 row_shr:1 row_mask:0xf bank_mask:0xf
	v_mov_b32_dpp v210, v28 row_shr:2 row_mask:0xf bank_mask:0xf
	v_mov_b32_dpp v207, v29 row_shr:1 row_mask:0xf bank_mask:0xf
	v_mov_b32_dpp v211, v29 row_shr:2 row_mask:0xf bank_mask:0xf
	s_waitcnt vmcnt(3)
	v_mov_b32_dpp v223, v166 row_shl:1 row_mask:0xf bank_mask:0xf
	v_mov_b32_dpp v224, v167 row_shl:1 row_mask:0xf bank_mask:0xf
	v_mov_b32_dpp v225, v168 row_shl:1 row_mask:0xf bank_mask:0xf
	v_mov_b32_dpp v226, v169 row_shl:1 row_mask:0xf bank_mask:0xf
	v_cndmask_b32_e64 v208, v208, v166, s[48:49]
	v_cndmask_b32_e64 v209, v209, v167, s[48:49]
	v_cndmask_b32_e64 v210, v210, v168, s[48:49]
	v_cndmask_b32_e64 v211, v211, v169, s[48:49]
	v_cndmask_b32_e64 v204, v204, v223, s[46:47]
	v_cndmask_b32_e64 v205, v205, v224, s[46:47]
	v_cndmask_b32_e64 v206, v206, v225, s[46:47]
	v_cndmask_b32_e64 v207, v207, v226, s[46:47]
	s_mov_b64 exec, s[48:49]
	v_add_u32_e32 v222, 0xdec00, v190
	global_load_dwordx4 v[166:169], v222, s[16:17] offset:16
	s_mov_b64 exec, -1
	v_pk_fma_f32 v[216:217], v[118:119], v[204:205], v[216:217]
	v_pk_fma_f32 v[218:219], v[120:121], v[206:207], v[218:219]
	v_pk_fma_f32 v[216:217], v[114:115], v[208:209], v[216:217]
	v_pk_fma_f32 v[218:219], v[116:117], v[210:211], v[218:219]
	v_mul_f32_e32 v204, 0xbfb8aa3b, v216
	v_mul_f32_e32 v205, 0xbfb8aa3b, v217
	v_mul_f32_e32 v206, 0xbfb8aa3b, v218
	v_mul_f32_e32 v207, 0xbfb8aa3b, v219
	v_exp_f32_e32 v204, v204
	v_exp_f32_e32 v205, v205
	v_exp_f32_e32 v206, v206
	v_exp_f32_e32 v207, v207
	v_add_f32_e32 v204, 1.0, v204
	v_add_f32_e32 v205, 1.0, v205
	v_add_f32_e32 v206, 1.0, v206
	v_add_f32_e32 v207, 1.0, v207
	v_rcp_f32_e32 v204, v204
	v_rcp_f32_e32 v205, v205
	v_rcp_f32_e32 v206, v206
	v_rcp_f32_e32 v207, v207
	v_mul_f32_e32 v204, v216, v204
	v_mul_f32_e32 v205, v217, v205
	v_mul_f32_e32 v206, v218, v206
	v_mul_f32_e32 v207, v219, v207
	v_mul_f32_e32 v204, v212, v204
	v_mul_f32_e32 v205, v213, v205
	v_mul_f32_e32 v206, v214, v206
	v_mul_f32_e32 v207, v215, v207
	v_cvt_pk_bf16_f32 v30, v204, v205
	v_cvt_pk_bf16_f32 v31, v206, v207
	v_pk_fma_f32 v[212:213], v[106:107], v[22:23], v[110:111]
	v_pk_fma_f32 v[214:215], v[108:109], v[24:25], v[112:113]
	s_nop 2
	v_mov_b32_dpp v204, v22 row_shr:1 row_mask:0xf bank_mask:0xf
	v_mov_b32_dpp v208, v22 row_shr:2 row_mask:0xf bank_mask:0xf
	v_mov_b32_dpp v205, v23 row_shr:1 row_mask:0xf bank_mask:0xf
	v_mov_b32_dpp v209, v23 row_shr:2 row_mask:0xf bank_mask:0xf
	v_mov_b32_dpp v206, v24 row_shr:1 row_mask:0xf bank_mask:0xf
	v_mov_b32_dpp v210, v24 row_shr:2 row_mask:0xf bank_mask:0xf
	v_mov_b32_dpp v207, v25 row_shr:1 row_mask:0xf bank_mask:0xf
	v_mov_b32_dpp v211, v25 row_shr:2 row_mask:0xf bank_mask:0xf
	s_waitcnt vmcnt(3)
	v_mov_b32_dpp v223, v170 row_shl:1 row_mask:0xf bank_mask:0xf
	v_mov_b32_dpp v224, v171 row_shl:1 row_mask:0xf bank_mask:0xf
	v_mov_b32_dpp v225, v172 row_shl:1 row_mask:0xf bank_mask:0xf
	v_mov_b32_dpp v226, v173 row_shl:1 row_mask:0xf bank_mask:0xf
	v_cndmask_b32_e64 v208, v208, v170, s[48:49]
	v_cndmask_b32_e64 v209, v209, v171, s[48:49]
	v_cndmask_b32_e64 v210, v210, v172, s[48:49]
	v_cndmask_b32_e64 v211, v211, v173, s[48:49]
	v_cndmask_b32_e64 v204, v204, v223, s[46:47]
	v_cndmask_b32_e64 v205, v205, v224, s[46:47]
	v_cndmask_b32_e64 v206, v206, v225, s[46:47]
	v_cndmask_b32_e64 v207, v207, v226, s[46:47]
	s_mov_b64 exec, s[48:49]
	v_add_u32_e32 v222, 0xf2000, v190
	global_load_dwordx4 v[170:173], v222, s[16:17] offset:16
	s_mov_b64 exec, -1
	v_pk_fma_f32 v[212:213], v[102:103], v[204:205], v[212:213]
	v_pk_fma_f32 v[214:215], v[104:105], v[206:207], v[214:215]
	v_pk_fma_f32 v[212:213], v[98:99], v[208:209], v[212:213]
	v_pk_fma_f32 v[214:215], v[100:101], v[210:211], v[214:215]
	v_pk_fma_f32 v[216:217], v[122:123], v[18:19], v[126:127]
	v_pk_fma_f32 v[218:219], v[124:125], v[20:21], v[128:129]
	s_nop 2
	v_mov_b32_dpp v204, v18 row_shr:1 row_mask:0xf bank_mask:0xf
	v_mov_b32_dpp v208, v18 row_shr:2 row_mask:0xf bank_mask:0xf
	v_mov_b32_dpp v205, v19 row_shr:1 row_mask:0xf bank_mask:0xf
	v_mov_b32_dpp v209, v19 row_shr:2 row_mask:0xf bank_mask:0xf
	v_mov_b32_dpp v206, v20 row_shr:1 row_mask:0xf bank_mask:0xf
	v_mov_b32_dpp v210, v20 row_shr:2 row_mask:0xf bank_mask:0xf
	v_mov_b32_dpp v207, v21 row_shr:1 row_mask:0xf bank_mask:0xf
	v_mov_b32_dpp v211, v21 row_shr:2 row_mask:0xf bank_mask:0xf
	s_waitcnt vmcnt(3)
	v_mov_b32_dpp v223, v174 row_shl:1 row_mask:0xf bank_mask:0xf
	v_mov_b32_dpp v224, v175 row_shl:1 row_mask:0xf bank_mask:0xf
	v_mov_b32_dpp v225, v176 row_shl:1 row_mask:0xf bank_mask:0xf
	v_mov_b32_dpp v226, v177 row_shl:1 row_mask:0xf bank_mask:0xf
	v_cndmask_b32_e64 v208, v208, v174, s[48:49]
	v_cndmask_b32_e64 v209, v209, v175, s[48:49]
	v_cndmask_b32_e64 v210, v210, v176, s[48:49]
	v_cndmask_b32_e64 v211, v211, v177, s[48:49]
	v_cndmask_b32_e64 v204, v204, v223, s[46:47]
	v_cndmask_b32_e64 v205, v205, v224, s[46:47]
	v_cndmask_b32_e64 v206, v206, v225, s[46:47]
	v_cndmask_b32_e64 v207, v207, v226, s[46:47]
	s_mov_b64 exec, s[48:49]
	v_add_u32_e32 v222, 0xf4c00, v190
	global_load_dwordx4 v[174:177], v222, s[16:17] offset:16
	s_mov_b64 exec, -1
	v_pk_fma_f32 v[216:217], v[118:119], v[204:205], v[216:217]
	v_pk_fma_f32 v[218:219], v[120:121], v[206:207], v[218:219]
	v_pk_fma_f32 v[216:217], v[114:115], v[208:209], v[216:217]
	v_pk_fma_f32 v[218:219], v[116:117], v[210:211], v[218:219]
	v_mul_f32_e32 v204, 0xbfb8aa3b, v216
	v_mul_f32_e32 v205, 0xbfb8aa3b, v217
	v_mul_f32_e32 v206, 0xbfb8aa3b, v218
	v_mul_f32_e32 v207, 0xbfb8aa3b, v219
	v_exp_f32_e32 v204, v204
	v_exp_f32_e32 v205, v205
	v_exp_f32_e32 v206, v206
	v_exp_f32_e32 v207, v207
	v_add_f32_e32 v204, 1.0, v204
	v_add_f32_e32 v205, 1.0, v205
	v_add_f32_e32 v206, 1.0, v206
	v_add_f32_e32 v207, 1.0, v207
	v_rcp_f32_e32 v204, v204
	v_rcp_f32_e32 v205, v205
	v_rcp_f32_e32 v206, v206
	v_rcp_f32_e32 v207, v207
	v_mul_f32_e32 v204, v216, v204
	v_mul_f32_e32 v205, v217, v205
	v_mul_f32_e32 v206, v218, v206
	v_mul_f32_e32 v207, v219, v207
	v_mul_f32_e32 v204, v212, v204
	v_mul_f32_e32 v205, v213, v205
	v_mul_f32_e32 v206, v214, v206
	v_mul_f32_e32 v207, v215, v207
	v_cvt_pk_bf16_f32 v22, v204, v205
	v_cvt_pk_bf16_f32 v23, v206, v207
	v_pk_fma_f32 v[212:213], v[106:107], v[14:15], v[110:111]
	v_pk_fma_f32 v[214:215], v[108:109], v[16:17], v[112:113]
	s_nop 2
	v_mov_b32_dpp v204, v14 row_shr:1 row_mask:0xf bank_mask:0xf
	v_mov_b32_dpp v208, v14 row_shr:2 row_mask:0xf bank_mask:0xf
	v_mov_b32_dpp v205, v15 row_shr:1 row_mask:0xf bank_mask:0xf
	v_mov_b32_dpp v209, v15 row_shr:2 row_mask:0xf bank_mask:0xf
	v_mov_b32_dpp v206, v16 row_shr:1 row_mask:0xf bank_mask:0xf
	v_mov_b32_dpp v210, v16 row_shr:2 row_mask:0xf bank_mask:0xf
	v_mov_b32_dpp v207, v17 row_shr:1 row_mask:0xf bank_mask:0xf
	v_mov_b32_dpp v211, v17 row_shr:2 row_mask:0xf bank_mask:0xf
	s_waitcnt vmcnt(3)
	v_mov_b32_dpp v223, v162 row_shl:1 row_mask:0xf bank_mask:0xf
	v_mov_b32_dpp v224, v163 row_shl:1 row_mask:0xf bank_mask:0xf
	v_mov_b32_dpp v225, v164 row_shl:1 row_mask:0xf bank_mask:0xf
	v_mov_b32_dpp v226, v165 row_shl:1 row_mask:0xf bank_mask:0xf
	v_cndmask_b32_e64 v208, v208, v162, s[48:49]
	v_cndmask_b32_e64 v209, v209, v163, s[48:49]
	v_cndmask_b32_e64 v210, v210, v164, s[48:49]
	v_cndmask_b32_e64 v211, v211, v165, s[48:49]
	v_cndmask_b32_e64 v204, v204, v223, s[46:47]
	v_cndmask_b32_e64 v205, v205, v224, s[46:47]
	v_cndmask_b32_e64 v206, v206, v225, s[46:47]
	v_cndmask_b32_e64 v207, v207, v226, s[46:47]
	v_pk_fma_f32 v[212:213], v[102:103], v[204:205], v[212:213]
	v_pk_fma_f32 v[214:215], v[104:105], v[206:207], v[214:215]
	v_pk_fma_f32 v[212:213], v[98:99], v[208:209], v[212:213]
	v_pk_fma_f32 v[214:215], v[100:101], v[210:211], v[214:215]
	v_pk_fma_f32 v[216:217], v[122:123], v[10:11], v[126:127]
	v_pk_fma_f32 v[218:219], v[124:125], v[12:13], v[128:129]
	s_nop 2
	v_mov_b32_dpp v204, v10 row_shr:1 row_mask:0xf bank_mask:0xf
	v_mov_b32_dpp v208, v10 row_shr:2 row_mask:0xf bank_mask:0xf
	v_mov_b32_dpp v205, v11 row_shr:1 row_mask:0xf bank_mask:0xf
	v_mov_b32_dpp v209, v11 row_shr:2 row_mask:0xf bank_mask:0xf
	v_mov_b32_dpp v206, v12 row_shr:1 row_mask:0xf bank_mask:0xf
	v_mov_b32_dpp v210, v12 row_shr:2 row_mask:0xf bank_mask:0xf
	v_mov_b32_dpp v207, v13 row_shr:1 row_mask:0xf bank_mask:0xf
	v_mov_b32_dpp v211, v13 row_shr:2 row_mask:0xf bank_mask:0xf
	s_waitcnt vmcnt(2)
	v_mov_b32_dpp v223, v166 row_shl:1 row_mask:0xf bank_mask:0xf
	v_mov_b32_dpp v224, v167 row_shl:1 row_mask:0xf bank_mask:0xf
	v_mov_b32_dpp v225, v168 row_shl:1 row_mask:0xf bank_mask:0xf
	v_mov_b32_dpp v226, v169 row_shl:1 row_mask:0xf bank_mask:0xf
	v_cndmask_b32_e64 v208, v208, v166, s[48:49]
	v_cndmask_b32_e64 v209, v209, v167, s[48:49]
	v_cndmask_b32_e64 v210, v210, v168, s[48:49]
	v_cndmask_b32_e64 v211, v211, v169, s[48:49]
	v_cndmask_b32_e64 v204, v204, v223, s[46:47]
	v_cndmask_b32_e64 v205, v205, v224, s[46:47]
	v_cndmask_b32_e64 v206, v206, v225, s[46:47]
	v_cndmask_b32_e64 v207, v207, v226, s[46:47]
	v_pk_fma_f32 v[216:217], v[118:119], v[204:205], v[216:217]
	v_pk_fma_f32 v[218:219], v[120:121], v[206:207], v[218:219]
	v_pk_fma_f32 v[216:217], v[114:115], v[208:209], v[216:217]
	v_pk_fma_f32 v[218:219], v[116:117], v[210:211], v[218:219]
	v_mul_f32_e32 v204, 0xbfb8aa3b, v216
	v_mul_f32_e32 v205, 0xbfb8aa3b, v217
	v_mul_f32_e32 v206, 0xbfb8aa3b, v218
	v_mul_f32_e32 v207, 0xbfb8aa3b, v219
	v_exp_f32_e32 v204, v204
	v_exp_f32_e32 v205, v205
	v_exp_f32_e32 v206, v206
	v_exp_f32_e32 v207, v207
	v_add_f32_e32 v204, 1.0, v204
	v_add_f32_e32 v205, 1.0, v205
	v_add_f32_e32 v206, 1.0, v206
	v_add_f32_e32 v207, 1.0, v207
	v_rcp_f32_e32 v204, v204
	v_rcp_f32_e32 v205, v205
	v_rcp_f32_e32 v206, v206
	v_rcp_f32_e32 v207, v207
	v_mul_f32_e32 v204, v216, v204
	v_mul_f32_e32 v205, v217, v205
	v_mul_f32_e32 v206, v218, v206
	v_mul_f32_e32 v207, v219, v207
	v_mul_f32_e32 v204, v212, v204
	v_mul_f32_e32 v205, v213, v205
	v_mul_f32_e32 v206, v214, v206
	v_mul_f32_e32 v207, v215, v207
	v_cvt_pk_bf16_f32 v14, v204, v205
	v_cvt_pk_bf16_f32 v15, v206, v207
	v_pk_fma_f32 v[212:213], v[106:107], v[6:7], v[110:111]
	v_pk_fma_f32 v[214:215], v[108:109], v[8:9], v[112:113]
	s_nop 2
	v_mov_b32_dpp v204, v6 row_shr:1 row_mask:0xf bank_mask:0xf
	v_mov_b32_dpp v208, v6 row_shr:2 row_mask:0xf bank_mask:0xf
	v_mov_b32_dpp v205, v7 row_shr:1 row_mask:0xf bank_mask:0xf
	v_mov_b32_dpp v209, v7 row_shr:2 row_mask:0xf bank_mask:0xf
	v_mov_b32_dpp v206, v8 row_shr:1 row_mask:0xf bank_mask:0xf
	v_mov_b32_dpp v210, v8 row_shr:2 row_mask:0xf bank_mask:0xf
	v_mov_b32_dpp v207, v9 row_shr:1 row_mask:0xf bank_mask:0xf
	v_mov_b32_dpp v211, v9 row_shr:2 row_mask:0xf bank_mask:0xf
	s_waitcnt vmcnt(1)
	v_mov_b32_dpp v223, v170 row_shl:1 row_mask:0xf bank_mask:0xf
	v_mov_b32_dpp v224, v171 row_shl:1 row_mask:0xf bank_mask:0xf
	v_mov_b32_dpp v225, v172 row_shl:1 row_mask:0xf bank_mask:0xf
	v_mov_b32_dpp v226, v173 row_shl:1 row_mask:0xf bank_mask:0xf
	v_cndmask_b32_e64 v208, v208, v170, s[48:49]
	v_cndmask_b32_e64 v209, v209, v171, s[48:49]
	v_cndmask_b32_e64 v210, v210, v172, s[48:49]
	v_cndmask_b32_e64 v211, v211, v173, s[48:49]
	v_cndmask_b32_e64 v204, v204, v223, s[46:47]
	v_cndmask_b32_e64 v205, v205, v224, s[46:47]
	v_cndmask_b32_e64 v206, v206, v225, s[46:47]
	v_cndmask_b32_e64 v207, v207, v226, s[46:47]
	v_pk_fma_f32 v[212:213], v[102:103], v[204:205], v[212:213]
	v_pk_fma_f32 v[214:215], v[104:105], v[206:207], v[214:215]
	v_pk_fma_f32 v[212:213], v[98:99], v[208:209], v[212:213]
	v_pk_fma_f32 v[214:215], v[100:101], v[210:211], v[214:215]
	v_pk_fma_f32 v[216:217], v[122:123], v[2:3], v[126:127]
	v_pk_fma_f32 v[218:219], v[124:125], v[4:5], v[128:129]
	s_nop 2
	v_mov_b32_dpp v204, v2 row_shr:1 row_mask:0xf bank_mask:0xf
	v_mov_b32_dpp v208, v2 row_shr:2 row_mask:0xf bank_mask:0xf
	v_mov_b32_dpp v205, v3 row_shr:1 row_mask:0xf bank_mask:0xf
	v_mov_b32_dpp v209, v3 row_shr:2 row_mask:0xf bank_mask:0xf
	v_mov_b32_dpp v206, v4 row_shr:1 row_mask:0xf bank_mask:0xf
	v_mov_b32_dpp v210, v4 row_shr:2 row_mask:0xf bank_mask:0xf
	v_mov_b32_dpp v207, v5 row_shr:1 row_mask:0xf bank_mask:0xf
	v_mov_b32_dpp v211, v5 row_shr:2 row_mask:0xf bank_mask:0xf
	s_waitcnt vmcnt(0)
	v_mov_b32_dpp v223, v174 row_shl:1 row_mask:0xf bank_mask:0xf
	v_mov_b32_dpp v224, v175 row_shl:1 row_mask:0xf bank_mask:0xf
	v_mov_b32_dpp v225, v176 row_shl:1 row_mask:0xf bank_mask:0xf
	v_mov_b32_dpp v226, v177 row_shl:1 row_mask:0xf bank_mask:0xf
	v_cndmask_b32_e64 v208, v208, v174, s[48:49]
	v_cndmask_b32_e64 v209, v209, v175, s[48:49]
	v_cndmask_b32_e64 v210, v210, v176, s[48:49]
	v_cndmask_b32_e64 v211, v211, v177, s[48:49]
	v_cndmask_b32_e64 v204, v204, v223, s[46:47]
	v_cndmask_b32_e64 v205, v205, v224, s[46:47]
	v_cndmask_b32_e64 v206, v206, v225, s[46:47]
	v_cndmask_b32_e64 v207, v207, v226, s[46:47]
	v_pk_fma_f32 v[216:217], v[118:119], v[204:205], v[216:217]
	v_pk_fma_f32 v[218:219], v[120:121], v[206:207], v[218:219]
	v_pk_fma_f32 v[216:217], v[114:115], v[208:209], v[216:217]
	v_pk_fma_f32 v[218:219], v[116:117], v[210:211], v[218:219]
	v_mul_f32_e32 v204, 0xbfb8aa3b, v216
	v_mul_f32_e32 v205, 0xbfb8aa3b, v217
	v_mul_f32_e32 v206, 0xbfb8aa3b, v218
	v_mul_f32_e32 v207, 0xbfb8aa3b, v219
	v_exp_f32_e32 v204, v204
	v_exp_f32_e32 v205, v205
	v_exp_f32_e32 v206, v206
	v_exp_f32_e32 v207, v207
	v_add_f32_e32 v204, 1.0, v204
	v_add_f32_e32 v205, 1.0, v205
	v_add_f32_e32 v206, 1.0, v206
	v_add_f32_e32 v207, 1.0, v207
	v_rcp_f32_e32 v204, v204
	v_rcp_f32_e32 v205, v205
	v_rcp_f32_e32 v206, v206
	v_rcp_f32_e32 v207, v207
	v_mul_f32_e32 v204, v216, v204
	v_mul_f32_e32 v205, v217, v205
	v_mul_f32_e32 v206, v218, v206
	v_mul_f32_e32 v207, v219, v207
	v_mul_f32_e32 v204, v212, v204
	v_mul_f32_e32 v205, v213, v205
	v_mul_f32_e32 v206, v214, v206
	v_mul_f32_e32 v207, v215, v207
	v_cvt_pk_bf16_f32 v6, v204, v205
	v_cvt_pk_bf16_f32 v7, v206, v207
	v_add_u32_e32 v204, 0xb0000, v231
	s_mov_b32 exec_lo, 0xfffcfffc
	s_mov_b32 exec_hi, 0xfffcfffc
	global_store_dwordx2 v204, v[94:95], s[36:37]
	s_mov_b64 exec, -1
	v_add_u32_e32 v205, 0xc6000, v231
	global_store_dwordx2 v205, v[86:87], s[36:37]
	v_add_u32_e32 v206, 0xdc000, v231
	global_store_dwordx2 v206, v[78:79], s[36:37]
	v_add_u32_e32 v207, 0xf2000, v231
	global_store_dwordx2 v207, v[70:71], s[36:37]
	v_add_u32_e32 v208, 0x8, v231
	s_mov_b32 exec_lo, 0xfffcfffc
	s_mov_b32 exec_hi, 0xfffcfffc
	global_store_dwordx2 v208, v[62:63], s[36:37]
	s_mov_b64 exec, -1
	v_add_u32_e32 v209, 0x16008, v231
	global_store_dwordx2 v209, v[54:55], s[36:37]
	v_add_u32_e32 v210, 0x2c008, v231
	global_store_dwordx2 v210, v[46:47], s[36:37]
	v_add_u32_e32 v211, 0x42008, v231
	global_store_dwordx2 v211, v[38:39], s[36:37]
	v_add_u32_e32 v204, 0xb0008, v231
	s_mov_b32 exec_lo, 0xfffcfffc
	s_mov_b32 exec_hi, 0xfffcfffc
	global_store_dwordx2 v204, v[30:31], s[36:37]
	s_mov_b64 exec, -1
	v_add_u32_e32 v205, 0xc6008, v231
	global_store_dwordx2 v205, v[22:23], s[36:37]
	v_add_u32_e32 v206, 0xdc008, v231
	global_store_dwordx2 v206, v[14:15], s[36:37]
	v_add_u32_e32 v207, 0xf2008, v231
	global_store_dwordx2 v207, v[6:7], s[36:37]
	s_branch .LBB0_4739
